# second-half residual loads of the DN/pool/GLU epilogues hoisted above the first half (on top of the P13 rewrite)
# speedup vs baseline: 1.0031x; 1.0031x over previous
.LBB0_357:
	ds_read_b128 v[134:137], v190
	ds_read_b128 v[138:141], v190 offset:1024
	ds_read_b128 v[142:145], v190 offset:2048
	ds_read_b128 v[146:149], v190 offset:3072
	s_add_i32 s36, s34, 0xfff50080
	s_cmp_eq_u32 s67, 40
	s_cselect_b32 s69, s27, s29
	s_cselect_b32 s68, s26, s28
	s_cselect_b32 s37, s9, s31
	s_cselect_b32 s70, s8, s30
	s_mov_b32 m0, s54
	v_lshl_add_u64 v[150:151], v[128:129], 0, s[34:35]
	ds_read_b128 v[166:169], v191
	ds_read_b128 v[170:173], v191 offset:1024
	ds_read_b128 v[174:177], v191 offset:2048
	ds_read_b128 v[178:181], v191 offset:3072
	ds_read_b128 v[194:197], v191 offset:4096
	ds_read_b128 v[198:201], v191 offset:5120
	ds_read_b128 v[202:205], v191 offset:6144
	ds_read_b128 v[206:209], v191 offset:7168
	global_load_lds_dwordx4 v[150:151], off
	v_lshl_add_u64 v[150:151], v[130:131], 0, s[34:35]
	s_mov_b32 m0, s55
	s_nop 0
	global_load_lds_dwordx4 v[150:151], off
	s_waitcnt lgkmcnt(8)
	s_barrier
	s_waitcnt lgkmcnt(0)
	s_setprio 1
	s_waitcnt lgkmcnt(0)
	v_mfma_f32_16x16x32_bf16 v[116:119], v[134:137], v[166:169], v[116:119]
	v_mfma_f32_16x16x32_bf16 v[112:115], v[142:145], v[166:169], v[112:115]
	v_mfma_f32_16x16x32_bf16 v[108:111], v[134:137], v[174:177], v[108:111]
	v_mfma_f32_16x16x32_bf16 v[104:107], v[142:145], v[174:177], v[104:107]
	v_mfma_f32_16x16x32_bf16 v[92:95], v[134:137], v[194:197], v[92:95]
	v_mfma_f32_16x16x32_bf16 v[88:91], v[142:145], v[194:197], v[88:91]
	v_mfma_f32_16x16x32_bf16 v[76:79], v[134:137], v[202:205], v[76:79]
	v_mfma_f32_16x16x32_bf16 v[72:75], v[142:145], v[202:205], v[72:75]
	v_mfma_f32_16x16x32_bf16 v[116:119], v[138:141], v[170:173], v[116:119]
	v_mfma_f32_16x16x32_bf16 v[112:115], v[146:149], v[170:173], v[112:115]
	v_mfma_f32_16x16x32_bf16 v[108:111], v[138:141], v[178:181], v[108:111]
	v_mfma_f32_16x16x32_bf16 v[104:107], v[146:149], v[178:181], v[104:107]
	v_mfma_f32_16x16x32_bf16 v[92:95], v[138:141], v[198:201], v[92:95]
	v_mfma_f32_16x16x32_bf16 v[88:91], v[146:149], v[198:201], v[88:91]
	v_mfma_f32_16x16x32_bf16 v[76:79], v[138:141], v[206:209], v[76:79]
	v_mfma_f32_16x16x32_bf16 v[72:75], v[146:149], v[206:209], v[72:75]
	s_setprio 0
	s_barrier
	s_cselect_b32 s71, 0, s36
	s_add_u32 s36, s70, s71
	s_addc_u32 s37, s37, 0
	s_mov_b32 m0, s56
	v_lshl_add_u64 v[150:151], s[36:37], 0, v[156:157]
	ds_read_b128 v[210:213], v192
	ds_read_b128 v[214:217], v192 offset:1024
	ds_read_b128 v[222:225], v192 offset:2048
	ds_read_b128 v[226:229], v192 offset:3072
	global_load_lds_dwordx4 v[150:151], off
	v_lshl_add_u64 v[182:183], s[36:37], 0, v[160:161]
	s_mov_b32 m0, s57
	s_nop 0
	global_load_lds_dwordx4 v[182:183], off
	s_barrier
	s_waitcnt lgkmcnt(0)
	s_setprio 1
	s_waitcnt lgkmcnt(0)
	v_mfma_f32_16x16x32_bf16 v[124:127], v[210:213], v[166:169], v[124:127]
	v_mfma_f32_16x16x32_bf16 v[120:123], v[222:225], v[166:169], v[120:123]
	v_mfma_f32_16x16x32_bf16 v[100:103], v[210:213], v[174:177], v[100:103]
	v_mfma_f32_16x16x32_bf16 v[96:99], v[222:225], v[174:177], v[96:99]
	v_mfma_f32_16x16x32_bf16 v[84:87], v[210:213], v[194:197], v[84:87]
	v_mfma_f32_16x16x32_bf16 v[80:83], v[222:225], v[194:197], v[80:83]
	v_mfma_f32_16x16x32_bf16 v[68:71], v[210:213], v[202:205], v[68:71]
	v_mfma_f32_16x16x32_bf16 v[64:67], v[222:225], v[202:205], v[64:67]
	v_mfma_f32_16x16x32_bf16 v[124:127], v[214:217], v[170:173], v[124:127]
	v_mfma_f32_16x16x32_bf16 v[120:123], v[226:229], v[170:173], v[120:123]
	v_mfma_f32_16x16x32_bf16 v[100:103], v[214:217], v[178:181], v[100:103]
	v_mfma_f32_16x16x32_bf16 v[96:99], v[226:229], v[178:181], v[96:99]
	v_mfma_f32_16x16x32_bf16 v[84:87], v[214:217], v[198:201], v[84:87]
	v_mfma_f32_16x16x32_bf16 v[80:83], v[226:229], v[198:201], v[80:83]
	v_mfma_f32_16x16x32_bf16 v[68:71], v[214:217], v[206:209], v[68:71]
	v_mfma_f32_16x16x32_bf16 v[64:67], v[226:229], v[206:209], v[64:67]
	s_setprio 0
	s_add_u32 s68, s68, s71
	s_addc_u32 s69, s69, 0
	s_mov_b32 m0, s46
	v_lshl_add_u64 v[218:219], s[68:69], 0, v[154:155]
	s_barrier
	ds_read_b128 v[166:169], v191 offset:16384
	ds_read_b128 v[170:173], v191 offset:17408
	ds_read_b128 v[174:177], v191 offset:18432
	ds_read_b128 v[178:181], v191 offset:19456
	ds_read_b128 v[194:197], v191 offset:20480
	ds_read_b128 v[198:201], v191 offset:21504
	ds_read_b128 v[202:205], v191 offset:22528
	ds_read_b128 v[206:209], v191 offset:23552
	global_load_lds_dwordx4 v[218:219], off
	v_lshl_add_u64 v[230:231], s[68:69], 0, v[158:159]
	s_mov_b32 m0, s47
	s_nop 0
	global_load_lds_dwordx4 v[230:231], off
	s_barrier
	s_waitcnt lgkmcnt(0)
	s_setprio 1
	s_waitcnt lgkmcnt(0)
	v_mfma_f32_16x16x32_bf16 v[52:55], v[134:137], v[166:169], v[52:55]
	v_mfma_f32_16x16x32_bf16 v[48:51], v[142:145], v[166:169], v[48:51]
	v_mfma_f32_16x16x32_bf16 v[44:47], v[134:137], v[174:177], v[44:47]
	v_mfma_f32_16x16x32_bf16 v[36:39], v[142:145], v[174:177], v[36:39]
	v_mfma_f32_16x16x32_bf16 v[28:31], v[134:137], v[194:197], v[28:31]
	v_mfma_f32_16x16x32_bf16 v[20:23], v[142:145], v[194:197], v[20:23]
	v_mfma_f32_16x16x32_bf16 v[12:15], v[134:137], v[202:205], v[12:15]
	v_mfma_f32_16x16x32_bf16 v[4:7], v[142:145], v[202:205], v[4:7]
	v_mfma_f32_16x16x32_bf16 v[52:55], v[138:141], v[170:173], v[52:55]
	v_mfma_f32_16x16x32_bf16 v[48:51], v[146:149], v[170:173], v[48:51]
	v_mfma_f32_16x16x32_bf16 v[44:47], v[138:141], v[178:181], v[44:47]
	v_mfma_f32_16x16x32_bf16 v[36:39], v[146:149], v[178:181], v[36:39]
	v_mfma_f32_16x16x32_bf16 v[28:31], v[138:141], v[198:201], v[28:31]
	v_mfma_f32_16x16x32_bf16 v[20:23], v[146:149], v[198:201], v[20:23]
	v_mfma_f32_16x16x32_bf16 v[12:15], v[138:141], v[206:209], v[12:15]
	v_mfma_f32_16x16x32_bf16 v[4:7], v[146:149], v[206:209], v[4:7]
	s_setprio 0
	s_barrier
	s_add_u32 s70, s36, 0xb0000
	s_addc_u32 s71, s37, 0
	s_mov_b32 m0, s0
	v_lshl_add_u64 v[134:135], s[70:71], 0, v[156:157]
	global_load_lds_dwordx4 v[134:135], off
	v_lshl_add_u64 v[134:135], s[70:71], 0, v[160:161]
	s_mov_b32 m0, s62
	s_nop 0
	global_load_lds_dwordx4 v[134:135], off
	s_waitcnt vmcnt(6)
	s_barrier
	s_setprio 1
	v_mfma_f32_16x16x32_bf16 v[60:63], v[210:213], v[166:169], v[60:63]
	v_mfma_f32_16x16x32_bf16 v[56:59], v[222:225], v[166:169], v[56:59]
	v_mfma_f32_16x16x32_bf16 v[40:43], v[210:213], v[174:177], v[40:43]
	v_mfma_f32_16x16x32_bf16 v[32:35], v[222:225], v[174:177], v[32:35]
	v_mfma_f32_16x16x32_bf16 v[24:27], v[210:213], v[194:197], v[24:27]
	v_mfma_f32_16x16x32_bf16 v[16:19], v[222:225], v[194:197], v[16:19]
	v_mfma_f32_16x16x32_bf16 v[8:11], v[210:213], v[202:205], v[8:11]
	v_mfma_f32_16x16x32_bf16 v[0:3], v[222:225], v[202:205], v[0:3]
	v_mfma_f32_16x16x32_bf16 v[60:63], v[214:217], v[170:173], v[60:63]
	v_mfma_f32_16x16x32_bf16 v[56:59], v[226:229], v[170:173], v[56:59]
	v_mfma_f32_16x16x32_bf16 v[40:43], v[214:217], v[178:181], v[40:43]
	v_mfma_f32_16x16x32_bf16 v[32:35], v[226:229], v[178:181], v[32:35]
	v_mfma_f32_16x16x32_bf16 v[24:27], v[214:217], v[198:201], v[24:27]
	v_mfma_f32_16x16x32_bf16 v[16:19], v[226:229], v[198:201], v[16:19]
	v_mfma_f32_16x16x32_bf16 v[8:11], v[214:217], v[206:209], v[8:11]
	v_mfma_f32_16x16x32_bf16 v[0:3], v[226:229], v[206:209], v[0:3]
	s_setprio 0
	s_barrier
	ds_read_b128 v[134:137], v132
	ds_read_b128 v[138:141], v132 offset:1024
	ds_read_b128 v[142:145], v132 offset:2048
	ds_read_b128 v[146:149], v132 offset:3072
	s_add_u32 s68, s68, 0xb0000
	s_addc_u32 s69, s69, 0
	s_mov_b32 m0, s48
	v_lshl_add_u64 v[210:211], s[68:69], 0, v[154:155]
	ds_read_b128 v[166:169], v191 offset:32768
	ds_read_b128 v[170:173], v191 offset:33792
	ds_read_b128 v[174:177], v191 offset:34816
	ds_read_b128 v[178:181], v191 offset:35840
	ds_read_b128 v[194:197], v191 offset:36864
	ds_read_b128 v[198:201], v191 offset:37888
	ds_read_b128 v[202:205], v191 offset:38912
	ds_read_b128 v[206:209], v191 offset:39936
	global_load_lds_dwordx4 v[210:211], off
	v_lshl_add_u64 v[210:211], s[68:69], 0, v[158:159]
	s_mov_b32 m0, s49
	s_nop 0
	global_load_lds_dwordx4 v[210:211], off
	s_waitcnt lgkmcnt(8)
	s_barrier
	s_waitcnt lgkmcnt(0)
	s_setprio 1
	s_waitcnt lgkmcnt(0)
	v_mfma_f32_16x16x32_bf16 v[116:119], v[134:137], v[166:169], v[116:119]
	v_mfma_f32_16x16x32_bf16 v[112:115], v[142:145], v[166:169], v[112:115]
	v_mfma_f32_16x16x32_bf16 v[108:111], v[134:137], v[174:177], v[108:111]
	v_mfma_f32_16x16x32_bf16 v[104:107], v[142:145], v[174:177], v[104:107]
	v_mfma_f32_16x16x32_bf16 v[92:95], v[134:137], v[194:197], v[92:95]
	v_mfma_f32_16x16x32_bf16 v[88:91], v[142:145], v[194:197], v[88:91]
	v_mfma_f32_16x16x32_bf16 v[76:79], v[134:137], v[202:205], v[76:79]
	v_mfma_f32_16x16x32_bf16 v[72:75], v[142:145], v[202:205], v[72:75]
	v_mfma_f32_16x16x32_bf16 v[116:119], v[138:141], v[170:173], v[116:119]
	v_mfma_f32_16x16x32_bf16 v[112:115], v[146:149], v[170:173], v[112:115]
	v_mfma_f32_16x16x32_bf16 v[108:111], v[138:141], v[178:181], v[108:111]
	v_mfma_f32_16x16x32_bf16 v[104:107], v[146:149], v[178:181], v[104:107]
	v_mfma_f32_16x16x32_bf16 v[92:95], v[138:141], v[198:201], v[92:95]
	v_mfma_f32_16x16x32_bf16 v[88:91], v[146:149], v[198:201], v[88:91]
	v_mfma_f32_16x16x32_bf16 v[76:79], v[138:141], v[206:209], v[76:79]
	v_mfma_f32_16x16x32_bf16 v[72:75], v[146:149], v[206:209], v[72:75]
	s_setprio 0
	s_barrier
	s_mov_b32 m0, s63
	v_lshl_add_u64 v[150:151], v[150:151], 0, s[10:11]
	ds_read_b128 v[210:213], v133
	ds_read_b128 v[214:217], v133 offset:1024
	ds_read_b128 v[222:225], v133 offset:2048
	ds_read_b128 v[226:229], v133 offset:3072
	global_load_lds_dwordx4 v[150:151], off
	v_lshl_add_u64 v[150:151], v[182:183], 0, s[10:11]
	s_mov_b32 m0, s64
	s_nop 0
	global_load_lds_dwordx4 v[150:151], off
	s_barrier
	s_waitcnt lgkmcnt(0)
	s_setprio 1
	s_waitcnt lgkmcnt(0)
	v_mfma_f32_16x16x32_bf16 v[124:127], v[210:213], v[166:169], v[124:127]
	v_mfma_f32_16x16x32_bf16 v[120:123], v[222:225], v[166:169], v[120:123]
	v_mfma_f32_16x16x32_bf16 v[100:103], v[210:213], v[174:177], v[100:103]
	v_mfma_f32_16x16x32_bf16 v[96:99], v[222:225], v[174:177], v[96:99]
	v_mfma_f32_16x16x32_bf16 v[84:87], v[210:213], v[194:197], v[84:87]
	v_mfma_f32_16x16x32_bf16 v[80:83], v[222:225], v[194:197], v[80:83]
	v_mfma_f32_16x16x32_bf16 v[68:71], v[210:213], v[202:205], v[68:71]
	v_mfma_f32_16x16x32_bf16 v[64:67], v[222:225], v[202:205], v[64:67]
	v_mfma_f32_16x16x32_bf16 v[124:127], v[214:217], v[170:173], v[124:127]
	v_mfma_f32_16x16x32_bf16 v[120:123], v[226:229], v[170:173], v[120:123]
	v_mfma_f32_16x16x32_bf16 v[100:103], v[214:217], v[178:181], v[100:103]
	v_mfma_f32_16x16x32_bf16 v[96:99], v[226:229], v[178:181], v[96:99]
	v_mfma_f32_16x16x32_bf16 v[84:87], v[214:217], v[198:201], v[84:87]
	v_mfma_f32_16x16x32_bf16 v[80:83], v[226:229], v[198:201], v[80:83]
	v_mfma_f32_16x16x32_bf16 v[68:71], v[214:217], v[206:209], v[68:71]
	v_mfma_f32_16x16x32_bf16 v[64:67], v[226:229], v[206:209], v[64:67]
	s_setprio 0
	s_mov_b32 m0, s51
	v_lshl_add_u64 v[150:151], v[218:219], 0, s[10:11]
	s_barrier
	ds_read_b128 v[166:169], v191 offset:49152
	ds_read_b128 v[170:173], v191 offset:50176
	ds_read_b128 v[174:177], v191 offset:51200
	ds_read_b128 v[178:181], v191 offset:52224
	ds_read_b128 v[194:197], v191 offset:53248
	ds_read_b128 v[198:201], v191 offset:54272
	ds_read_b128 v[202:205], v191 offset:55296
	ds_read_b128 v[206:209], v191 offset:56320
	global_load_lds_dwordx4 v[150:151], off
	v_lshl_add_u64 v[150:151], v[230:231], 0, s[10:11]
	s_mov_b32 m0, s52
	s_nop 0
	global_load_lds_dwordx4 v[150:151], off
	s_barrier
;     ...
;         G_PAIR(0, 1);
; #pragma unroll 1
;         for (int t = 2; t < nt; t += 2) G_PAIR(t, 0);
	s_waitcnt lgkmcnt(0)
	s_setprio 1
	s_waitcnt lgkmcnt(0)
	v_mfma_f32_16x16x32_bf16 v[52:55], v[134:137], v[166:169], v[52:55]
	v_mfma_f32_16x16x32_bf16 v[48:51], v[142:145], v[166:169], v[48:51]
	v_mfma_f32_16x16x32_bf16 v[44:47], v[134:137], v[174:177], v[44:47]
	v_mfma_f32_16x16x32_bf16 v[36:39], v[142:145], v[174:177], v[36:39]
	v_mfma_f32_16x16x32_bf16 v[28:31], v[134:137], v[194:197], v[28:31]
	v_mfma_f32_16x16x32_bf16 v[20:23], v[142:145], v[194:197], v[20:23]
	v_mfma_f32_16x16x32_bf16 v[12:15], v[134:137], v[202:205], v[12:15]
	v_mfma_f32_16x16x32_bf16 v[4:7], v[142:145], v[202:205], v[4:7]
	v_mfma_f32_16x16x32_bf16 v[52:55], v[138:141], v[170:173], v[52:55]
	v_mfma_f32_16x16x32_bf16 v[48:51], v[146:149], v[170:173], v[48:51]
	v_mfma_f32_16x16x32_bf16 v[44:47], v[138:141], v[178:181], v[44:47]
	v_mfma_f32_16x16x32_bf16 v[36:39], v[146:149], v[178:181], v[36:39]
	v_mfma_f32_16x16x32_bf16 v[28:31], v[138:141], v[198:201], v[28:31]
	v_mfma_f32_16x16x32_bf16 v[20:23], v[146:149], v[198:201], v[20:23]
	v_mfma_f32_16x16x32_bf16 v[12:15], v[138:141], v[206:209], v[12:15]
	v_mfma_f32_16x16x32_bf16 v[4:7], v[146:149], v[206:209], v[4:7]
	s_setprio 0
	s_barrier
	s_add_u32 s36, s36, 0xb0080
	s_addc_u32 s37, s37, 0
	s_mov_b32 m0, s65
	v_lshl_add_u64 v[134:135], s[36:37], 0, v[156:157]
	global_load_lds_dwordx4 v[134:135], off
	v_lshl_add_u64 v[134:135], s[36:37], 0, v[160:161]
	s_mov_b32 m0, s66
	s_nop 0
	global_load_lds_dwordx4 v[134:135], off
	s_waitcnt vmcnt(6)
	s_barrier
	s_setprio 1
	v_mfma_f32_16x16x32_bf16 v[60:63], v[210:213], v[166:169], v[60:63]
	v_mfma_f32_16x16x32_bf16 v[56:59], v[222:225], v[166:169], v[56:59]
	v_mfma_f32_16x16x32_bf16 v[40:43], v[210:213], v[174:177], v[40:43]
	v_mfma_f32_16x16x32_bf16 v[32:35], v[222:225], v[174:177], v[32:35]
	v_mfma_f32_16x16x32_bf16 v[24:27], v[210:213], v[194:197], v[24:27]
	v_mfma_f32_16x16x32_bf16 v[16:19], v[222:225], v[194:197], v[16:19]
	v_mfma_f32_16x16x32_bf16 v[8:11], v[210:213], v[202:205], v[8:11]
	v_mfma_f32_16x16x32_bf16 v[0:3], v[222:225], v[202:205], v[0:3]
	v_mfma_f32_16x16x32_bf16 v[60:63], v[214:217], v[170:173], v[60:63]
	v_mfma_f32_16x16x32_bf16 v[56:59], v[226:229], v[170:173], v[56:59]
	v_mfma_f32_16x16x32_bf16 v[40:43], v[214:217], v[178:181], v[40:43]
	v_mfma_f32_16x16x32_bf16 v[32:35], v[226:229], v[178:181], v[32:35]
	v_mfma_f32_16x16x32_bf16 v[24:27], v[214:217], v[198:201], v[24:27]
	v_mfma_f32_16x16x32_bf16 v[16:19], v[226:229], v[198:201], v[16:19]
	v_mfma_f32_16x16x32_bf16 v[8:11], v[214:217], v[206:209], v[8:11]
	v_mfma_f32_16x16x32_bf16 v[0:3], v[226:229], v[206:209], v[0:3]
	s_setprio 0
	s_add_i32 s67, s67, 2
	s_add_u32 s34, s34, 0x100
	s_addc_u32 s35, s35, 0
	s_cmp_gt_u32 s67, 41
	s_barrier
	s_cbranch_scc0 .LBB0_357
; __device__ __forceinline__ unsigned pk2(float lo, float hi) { unsigned r; asm volatile("v_cvt_pk_bf16_f32 %0, %1, %2" : "=v"(r) : "v"(lo), "v"(hi)); return r; }
; __device__ __forceinline__ unsigned pk2(float lo, float hi) { return f2bf(lo) | (f2bf(hi) << 16); }
;     __device__ __forceinline__ void epi(const f32x4 (&acc)[2][2][4][2], const Unit& u, int wr, int wc, int fr, int fq) const {
;     ...
;         const int row0 = u.pm * 256 + wr * 64 + fr, col0 = u.pn * 256 + wc * 32 + 8 * fq;
; #pragma unroll
;         for (int ai = 0; ai < 2; ++ai) {
;             u32x4 xo[4][2];
; #pragma unroll
;             for (int m = 0; m < 4; ++m)
; #pragma unroll
;                 for (int bj = 0; bj < 2; ++bj) xo[m][bj] = *(const u32x4*)(xb + (size_t)(row0 + ai * 128 + m * 16) * D + col0 + bj * 128);
; #pragma unroll
;             for (int m = 0; m < 4; ++m) {
;                 const int row = row0 + ai * 128 + m * 16; const size_t off = (size_t)row * D + col0; float ss = 0.f;
; #pragma unroll
;                 for (int bj = 0; bj < 2; ++bj) {
;                     const u32x4 o = xo[m][bj]; const f32x4 a0v = acc[ai][bj][m][0], a1v = acc[ai][bj][m][1];
;                     const float v0 = bf_lo(o.x) + coef * a0v[0], v1 = bf_hi(o.x) + coef * a0v[1], v2 = bf_lo(o.y) + coef * a0v[2], v3 = bf_hi(o.y) + coef * a0v[3];
;                     const float v4 = bf_lo(o.z) + coef * a1v[0], v5 = bf_hi(o.z) + coef * a1v[1], v6 = bf_lo(o.w) + coef * a1v[2], v7 = bf_hi(o.w) + coef * a1v[3];
;                     u32x4 w; w.x = pk2(v0, v1); w.y = pk2(v2, v3); w.z = pk2(v4, v5); w.w = pk2(v6, v7);
;                     *(u32x4*)(xb + off + bj * 128) = w;
;                     ss += ((v0 * v0 + v1 * v1) + (v2 * v2 + v3 * v3)) + ((v4 * v4 + v5 * v5) + (v6 * v6 + v7 * v7));
;                 }
;                 ss += __shfl_xor(ss, 16); ss += __shfl_xor(ss, 32);
;                 if (fq == 0) rowss[(size_t)row * 32 + u.pn * 4 + wc] = ss;
;             }
	v_lshl_or_b32 v166, s40, 8, v189
	v_lshl_add_u32 v170, s61, 8, v153
	v_ashrrev_i32_e32 v167, 31, v166
	v_lshlrev_b64 v[202:203], 1, v[166:167]
	v_ashrrev_i32_e32 v171, 31, v170
	v_lshl_add_u64 v[168:169], s[20:21], 0, v[202:203]
	v_lshlrev_b64 v[204:205], 11, v[170:171]
	v_lshl_add_u64 v[128:129], v[168:169], 0, v[204:205]
	v_mov_b32_e32 v218, 0x40000
	v_mov_b32_e32 v219, 0
	v_lshl_add_u64 v[216:217], v[128:129], 0, v[218:219]
	v_mov_b32_e32 v218, 0x8000
	global_load_dwordx4 v[194:197], v[128:129], off
	global_load_dwordx4 v[198:201], v[128:129], off offset:256
	v_or_b32_e32 v180, 16, v170
	v_or_b32_e32 v176, 32, v170
	v_or_b32_e32 v172, 48, v170
	v_ashrrev_i32_e32 v181, 31, v180
	v_ashrrev_i32_e32 v177, 31, v176
	v_ashrrev_i32_e32 v173, 31, v172
	v_lshlrev_b64 v[182:183], 11, v[180:181]
	v_lshlrev_b64 v[178:179], 11, v[176:177]
	v_lshlrev_b64 v[174:175], 11, v[172:173]
	v_lshl_add_u64 v[128:129], v[168:169], 0, v[182:183]
	v_lshl_add_u64 v[130:131], v[168:169], 0, v[178:179]
	v_lshl_add_u64 v[206:207], v[168:169], 0, v[174:175]
	global_load_dwordx4 v[148:151], v[128:129], off
	global_load_dwordx4 v[144:147], v[128:129], off offset:256
	global_load_dwordx4 v[140:143], v[130:131], off
	global_load_dwordx4 v[136:139], v[130:131], off offset:256
	global_load_dwordx4 v[132:135], v[206:207], off
	s_nop 0
	global_load_dwordx4 v[128:131], v[206:207], off offset:256
	global_load_dwordx4 v[222:225], v[216:217], off
	global_load_dwordx4 v[226:229], v[216:217], off offset:256
	v_lshl_add_u64 v[216:217], v[216:217], 0, v[218:219]
	global_load_dwordx4 v[230:233], v[216:217], off
	global_load_dwordx4 v[234:237], v[216:217], off offset:256
	v_lshl_add_u64 v[216:217], v[216:217], 0, v[218:219]
	global_load_dwordx4 v[238:241], v[216:217], off
	global_load_dwordx4 v[242:245], v[216:217], off offset:256
	v_lshl_add_u64 v[216:217], v[216:217], 0, v[218:219]
	global_load_dwordx4 v[246:249], v[216:217], off
	global_load_dwordx4 v[250:253], v[216:217], off offset:256
	v_and_b32_e32 v206, 64, v193
	v_xor_b32_e32 v208, 16, v193
	v_add_u32_e32 v206, 64, v206
	v_cmp_lt_i32_e32 vcc, v208, v206
	s_waitcnt vmcnt(8)
	v_lshlrev_b32_e32 v209, 16, v195
	v_cndmask_b32_e32 v207, v193, v208, vcc
	v_lshlrev_b32_e32 v208, 16, v194
	v_and_b32_e32 v194, 0xffff0000, v194
	v_and_b32_e32 v195, 0xffff0000, v195
	v_lshlrev_b32_e32 v210, 16, v196
	v_and_b32_e32 v196, 0xffff0000, v196
	v_lshlrev_b32_e32 v211, 16, v197
	v_and_b32_e32 v197, 0xffff0000, v197
	v_lshlrev_b32_e32 v212, 16, v198
	v_and_b32_e32 v198, 0xffff0000, v198
	v_lshlrev_b32_e32 v213, 16, v199
	v_and_b32_e32 v199, 0xffff0000, v199
	v_lshlrev_b32_e32 v214, 16, v200
	v_and_b32_e32 v200, 0xffff0000, v200
	v_lshlrev_b32_e32 v215, 16, v201
	v_and_b32_e32 v201, 0xffff0000, v201
	v_fmac_f32_e32 v194, 0.5, v117
	v_fmac_f32_e32 v195, 0.5, v119
	v_fmac_f32_e32 v196, 0.5, v113
	v_fmac_f32_e32 v197, 0.5, v115
	v_fmac_f32_e32 v198, 0.5, v125
	v_fmac_f32_e32 v199, 0.5, v127
	v_fmac_f32_e32 v200, 0.5, v121
	v_fmac_f32_e32 v201, 0.5, v123
	v_fmac_f32_e32 v208, 0.5, v116
	v_fmac_f32_e32 v209, 0.5, v118
	v_fmac_f32_e32 v210, 0.5, v112
	v_fmac_f32_e32 v211, 0.5, v114
	v_fmac_f32_e32 v212, 0.5, v124
	v_fmac_f32_e32 v213, 0.5, v126
	v_fmac_f32_e32 v214, 0.5, v120
	v_fmac_f32_e32 v215, 0.5, v122
	v_mul_f32_e32 v112, v194, v194
	v_mul_f32_e32 v113, v195, v195
	v_mul_f32_e32 v118, v196, v196
	v_mul_f32_e32 v119, v197, v197
	v_mul_f32_e32 v120, v198, v198
	v_mul_f32_e32 v121, v199, v199
	v_mul_f32_e32 v122, v200, v200
	v_mul_f32_e32 v123, v201, v201
	v_fmac_f32_e32 v112, v208, v208
	v_fmac_f32_e32 v113, v209, v209
	v_fmac_f32_e32 v118, v210, v210
	v_fmac_f32_e32 v119, v211, v211
	v_fmac_f32_e32 v120, v212, v212
	v_fmac_f32_e32 v121, v213, v213
	v_fmac_f32_e32 v122, v214, v214
	v_fmac_f32_e32 v123, v215, v215
	v_add_f32_e32 v112, v112, v113
	v_add_f32_e32 v113, v118, v119
	v_add_f32_e32 v118, v120, v121
	v_add_f32_e32 v119, v122, v123
	v_add_f32_e32 v112, v112, v113
	v_add_f32_e32 v113, v118, v119
	v_add_f32_e32 v113, v112, v113
	v_lshlrev_b32_e32 v112, 2, v207
	ds_bpermute_b32 v122, v112, v113
	v_lshl_add_u64 v[118:119], s[20:21], 0, v[204:205]
	v_cvt_pk_bf16_f32 v114, v208, v194
	v_lshl_add_u64 v[120:121], v[118:119], 0, v[202:203]
	v_cvt_pk_bf16_f32 v115, v209, v195
	v_cvt_pk_bf16_f32 v116, v210, v196
	v_cvt_pk_bf16_f32 v117, v211, v197
	global_store_dwordx4 v[120:121], v[114:117], off
	s_waitcnt lgkmcnt(0)
	s_nop 0
	v_add_f32_e32 v114, v113, v122
	v_xor_b32_e32 v113, 32, v193
	v_cmp_lt_i32_e32 vcc, v113, v206
	v_cvt_pk_bf16_f32 v116, v212, v198
	v_cvt_pk_bf16_f32 v117, v213, v199
	v_cvt_pk_bf16_f32 v118, v214, v200
	v_cvt_pk_bf16_f32 v119, v215, v201
	global_store_dwordx4 v[120:121], v[116:119], off offset:256
	s_nop 0
	v_cndmask_b32_e32 v113, v193, v113, vcc
	v_lshlrev_b32_e32 v113, 2, v113
	ds_bpermute_b32 v115, v113, v114
	s_and_saveexec_b64 s[28:29], s[6:7]
	s_cbranch_execz .LBB0_360
	s_waitcnt lgkmcnt(0)
	v_add_f32_e32 v116, v114, v115
	s_lshl_b32 s30, s40, 2
	v_lshlrev_b64 v[114:115], 7, v[170:171]
	s_ashr_i32 s31, s30, 31
	v_lshl_add_u64 v[114:115], s[2:3], 0, v[114:115]
	v_lshl_add_u64 v[114:115], s[30:31], 2, v[114:115]
	s_lshl_b32 s0, s50, 2
	v_lshl_add_u64 v[114:115], v[114:115], 0, s[0:1]
	global_store_dword v[114:115], v116, off

; __device__ __forceinline__ unsigned pk2(float lo, float hi) { unsigned r; asm volatile("v_cvt_pk_bf16_f32 %0, %1, %2" : "=v"(r) : "v"(lo), "v"(hi)); return r; }
; __device__ __forceinline__ unsigned pk2(float lo, float hi) { return f2bf(lo) | (f2bf(hi) << 16); }
;     __device__ __forceinline__ void epi(const f32x4 (&acc)[2][2][4][2], const Unit& u, int wr, int wc, int fr, int fq) const {
;     ...
;         for (int ai = 0; ai < 2; ++ai) {
;             u32x4 xo[4][2];
; #pragma unroll
;             for (int m = 0; m < 4; ++m)
; #pragma unroll
;                 for (int bj = 0; bj < 2; ++bj) xo[m][bj] = *(const u32x4*)(xb + (size_t)(row0 + ai * 128 + m * 16) * D + col0 + bj * 128);
; #pragma unroll
;             for (int m = 0; m < 4; ++m) {
;                 const int row = row0 + ai * 128 + m * 16; const size_t off = (size_t)row * D + col0; float ss = 0.f;
; #pragma unroll
;                 for (int bj = 0; bj < 2; ++bj) {
;                     const u32x4 o = xo[m][bj]; const f32x4 a0v = acc[ai][bj][m][0], a1v = acc[ai][bj][m][1];
;                     const float v0 = bf_lo(o.x) + coef * a0v[0], v1 = bf_hi(o.x) + coef * a0v[1], v2 = bf_lo(o.y) + coef * a0v[2], v3 = bf_hi(o.y) + coef * a0v[3];
;                     const float v4 = bf_lo(o.z) + coef * a1v[0], v5 = bf_hi(o.z) + coef * a1v[1], v6 = bf_lo(o.w) + coef * a1v[2], v7 = bf_hi(o.w) + coef * a1v[3];
;                     u32x4 w; w.x = pk2(v0, v1); w.y = pk2(v2, v3); w.z = pk2(v4, v5); w.w = pk2(v6, v7);
;                     *(u32x4*)(xb + off + bj * 128) = w;
;                     ss += ((v0 * v0 + v1 * v1) + (v2 * v2 + v3 * v3)) + ((v4 * v4 + v5 * v5) + (v6 * v6 + v7 * v7));
;                 }
;                 ss += __shfl_xor(ss, 16); ss += __shfl_xor(ss, 32);
;                 if (fq == 0) rowss[(size_t)row * 32 + u.pn * 4 + wc] = ss;
.LBB0_366:
	s_or_b64 exec, exec, s[28:29]
	v_add_u32_e32 v100, 0x80, v170
	v_ashrrev_i32_e32 v101, 31, v100
	v_lshlrev_b64 v[110:111], 11, v[100:101]
	s_waitcnt lgkmcnt(0)
	v_lshl_add_u64 v[64:65], v[168:169], 0, v[110:111]
	s_waitcnt vmcnt(8)
	v_mov_b64_e32 v[102:103], v[222:223]
	v_mov_b64_e32 v[104:105], v[224:225]
	v_mov_b64_e32 v[106:107], v[226:227]
	v_mov_b64_e32 v[108:109], v[228:229]
	v_add_u32_e32 v96, 0x90, v170
	v_add_u32_e32 v92, 0xa0, v170
	v_add_u32_e32 v88, 0xb0, v170
	v_ashrrev_i32_e32 v97, 31, v96
	v_ashrrev_i32_e32 v93, 31, v92
	v_ashrrev_i32_e32 v89, 31, v88
	v_lshlrev_b64 v[98:99], 11, v[96:97]
	v_lshlrev_b64 v[94:95], 11, v[92:93]
	v_lshlrev_b64 v[90:91], 11, v[88:89]
	v_lshl_add_u64 v[64:65], v[168:169], 0, v[98:99]
	v_lshl_add_u64 v[66:67], v[168:169], 0, v[94:95]
	v_lshl_add_u64 v[114:115], v[168:169], 0, v[90:91]
	v_mov_b64_e32 v[84:85], v[230:231]
	v_mov_b64_e32 v[86:87], v[232:233]
	v_mov_b64_e32 v[80:81], v[234:235]
	v_mov_b64_e32 v[82:83], v[236:237]
	v_mov_b64_e32 v[76:77], v[238:239]
	v_mov_b64_e32 v[78:79], v[240:241]
	v_mov_b64_e32 v[72:73], v[242:243]
	v_mov_b64_e32 v[74:75], v[244:245]
	v_mov_b64_e32 v[68:69], v[246:247]
	v_mov_b64_e32 v[70:71], v[248:249]
	s_nop 0
	v_mov_b64_e32 v[64:65], v[250:251]
	v_mov_b64_e32 v[66:67], v[252:253]
	v_lshlrev_b32_e32 v114, 16, v102
	v_and_b32_e32 v102, 0xffff0000, v102
	v_lshlrev_b32_e32 v115, 16, v103
	v_and_b32_e32 v103, 0xffff0000, v103
	v_lshlrev_b32_e32 v116, 16, v104
	v_and_b32_e32 v104, 0xffff0000, v104
	v_lshlrev_b32_e32 v117, 16, v105
	v_and_b32_e32 v105, 0xffff0000, v105
	v_lshlrev_b32_e32 v118, 16, v106
	v_and_b32_e32 v106, 0xffff0000, v106
	v_lshlrev_b32_e32 v119, 16, v107
	v_and_b32_e32 v107, 0xffff0000, v107
	v_lshlrev_b32_e32 v120, 16, v108
	v_and_b32_e32 v108, 0xffff0000, v108
	v_lshlrev_b32_e32 v121, 16, v109
	v_and_b32_e32 v109, 0xffff0000, v109
	v_fmac_f32_e32 v102, 0.5, v53
	v_fmac_f32_e32 v103, 0.5, v55
	v_fmac_f32_e32 v104, 0.5, v49
	v_fmac_f32_e32 v105, 0.5, v51
	v_fmac_f32_e32 v106, 0.5, v61
	v_fmac_f32_e32 v107, 0.5, v63
	v_fmac_f32_e32 v108, 0.5, v57
	v_fmac_f32_e32 v109, 0.5, v59
	v_fmac_f32_e32 v114, 0.5, v52
	v_fmac_f32_e32 v115, 0.5, v54
	v_fmac_f32_e32 v116, 0.5, v48
	v_fmac_f32_e32 v117, 0.5, v50
	v_fmac_f32_e32 v118, 0.5, v60
	v_fmac_f32_e32 v119, 0.5, v62
	v_fmac_f32_e32 v120, 0.5, v56
	v_fmac_f32_e32 v121, 0.5, v58
	v_mul_f32_e32 v52, v102, v102
	v_mul_f32_e32 v53, v103, v103
	v_mul_f32_e32 v54, v104, v104
	v_mul_f32_e32 v55, v105, v105
	v_mul_f32_e32 v56, v106, v106
	v_mul_f32_e32 v57, v107, v107
	v_mul_f32_e32 v58, v108, v108
	v_mul_f32_e32 v59, v109, v109
	v_fmac_f32_e32 v52, v114, v114
	v_fmac_f32_e32 v53, v115, v115
	v_fmac_f32_e32 v54, v116, v116
	v_fmac_f32_e32 v55, v117, v117
	v_fmac_f32_e32 v56, v118, v118
	v_fmac_f32_e32 v57, v119, v119
	v_fmac_f32_e32 v58, v120, v120
	v_fmac_f32_e32 v59, v121, v121
	v_add_f32_e32 v52, v52, v53
	v_add_f32_e32 v53, v54, v55
	v_add_f32_e32 v54, v56, v57
	v_add_f32_e32 v55, v58, v59
	v_add_f32_e32 v52, v52, v53
	v_add_f32_e32 v53, v54, v55
	v_add_f32_e32 v56, v52, v53
	ds_bpermute_b32 v57, v112, v56
	v_lshl_add_u64 v[52:53], s[20:21], 0, v[110:111]
	v_cvt_pk_bf16_f32 v48, v114, v102
	v_lshl_add_u64 v[54:55], v[166:167], 1, v[52:53]
	v_cvt_pk_bf16_f32 v49, v115, v103
	v_cvt_pk_bf16_f32 v50, v116, v104
	v_cvt_pk_bf16_f32 v51, v117, v105
	global_store_dwordx4 v[54:55], v[48:51], off
	s_waitcnt lgkmcnt(0)
	s_nop 0
	v_add_f32_e32 v48, v56, v57
	ds_bpermute_b32 v49, v113, v48
	v_cvt_pk_bf16_f32 v50, v118, v106
	v_cvt_pk_bf16_f32 v51, v119, v107
	v_cvt_pk_bf16_f32 v52, v120, v108
	v_cvt_pk_bf16_f32 v53, v121, v109
	global_store_dwordx4 v[54:55], v[50:53], off offset:256
	s_and_saveexec_b64 s[28:29], s[6:7]
	s_cbranch_execz .LBB0_368
	s_waitcnt lgkmcnt(0)
	v_add_f32_e32 v50, v48, v49
	s_lshl_b32 s30, s40, 2
	v_lshlrev_b64 v[48:49], 7, v[100:101]
	s_ashr_i32 s31, s30, 31
	v_lshl_add_u64 v[48:49], s[2:3], 0, v[48:49]
	v_lshl_add_u64 v[48:49], s[30:31], 2, v[48:49]
	s_lshl_b32 s0, s50, 2
	v_lshl_add_u64 v[48:49], v[48:49], 0, s[0:1]
	global_store_dword v[48:49], v50, off
.LBB0_368:
	s_or_b64 exec, exec, s[28:29]
	v_lshlrev_b32_e32 v48, 16, v84
	v_fmac_f32_e32 v48, 0.5, v44
	v_and_b32_e32 v44, 0xffff0000, v84
	v_fmac_f32_e32 v44, 0.5, v45
	v_lshlrev_b32_e32 v45, 16, v85
	v_fmac_f32_e32 v45, 0.5, v46
	v_and_b32_e32 v46, 0xffff0000, v85
	v_fmac_f32_e32 v46, 0.5, v47
	v_lshlrev_b32_e32 v47, 16, v86
	s_waitcnt lgkmcnt(0)
	v_and_b32_e32 v49, 0xffff0000, v86
	v_fmac_f32_e32 v47, 0.5, v36
	v_fmac_f32_e32 v49, 0.5, v37
	v_and_b32_e32 v51, 0xffff0000, v87
	v_cvt_pk_bf16_f32 v36, v48, v44
	v_cvt_pk_bf16_f32 v37, v45, v46
	v_mul_f32_e32 v44, v44, v44
	v_mul_f32_e32 v46, v46, v46
	v_lshlrev_b32_e32 v50, 16, v87
	v_fmac_f32_e32 v51, 0.5, v39
	v_fmac_f32_e32 v44, v48, v48
	v_fmac_f32_e32 v46, v45, v45
	v_fmac_f32_e32 v50, 0.5, v38
	v_add_f32_e32 v44, v44, v46
	v_mul_f32_e32 v45, v49, v49
	v_mul_f32_e32 v46, v51, v51
	v_cvt_pk_bf16_f32 v38, v47, v49
	v_fmac_f32_e32 v45, v47, v47
	v_fmac_f32_e32 v46, v50, v50
	v_lshlrev_b32_e32 v47, 16, v81
	v_add_f32_e32 v45, v45, v46
	v_and_b32_e32 v46, 0xffff0000, v80
	v_fmac_f32_e32 v47, 0.5, v42
	v_and_b32_e32 v42, 0xffff0000, v81
	v_add_f32_e32 v44, v44, v45
	v_lshlrev_b32_e32 v45, 16, v80
	v_fmac_f32_e32 v46, 0.5, v41
	v_fmac_f32_e32 v42, 0.5, v43
	v_lshlrev_b32_e32 v43, 16, v82
	v_and_b32_e32 v48, 0xffff0000, v82
	v_cvt_pk_bf16_f32 v39, v50, v51
	v_fmac_f32_e32 v45, 0.5, v40
	v_fmac_f32_e32 v43, 0.5, v32
	v_fmac_f32_e32 v48, 0.5, v33
	v_and_b32_e32 v50, 0xffff0000, v83
	v_mul_f32_e32 v32, v46, v46
	v_mul_f32_e32 v33, v42, v42
	v_lshlrev_b32_e32 v49, 16, v83
	v_fmac_f32_e32 v50, 0.5, v35
	v_fmac_f32_e32 v32, v45, v45
	v_fmac_f32_e32 v33, v47, v47
	v_fmac_f32_e32 v49, 0.5, v34
	v_add_f32_e32 v32, v32, v33
	v_mul_f32_e32 v33, v48, v48
	v_mul_f32_e32 v34, v50, v50
	v_fmac_f32_e32 v33, v43, v43
	v_fmac_f32_e32 v34, v49, v49
	v_add_f32_e32 v33, v33, v34
	v_add_f32_e32 v32, v32, v33
	v_add_f32_e32 v35, v44, v32
	ds_bpermute_b32 v44, v112, v35
	v_lshl_add_u64 v[32:33], s[20:21], 0, v[98:99]
	v_lshl_add_u64 v[40:41], v[166:167], 1, v[32:33]
	global_store_dwordx4 v[40:41], v[36:39], off
	v_cvt_pk_bf16_f32 v34, v45, v46
	s_waitcnt lgkmcnt(0)
	v_add_f32_e32 v32, v35, v44
	ds_bpermute_b32 v33, v113, v32
	v_cvt_pk_bf16_f32 v35, v47, v42
	v_cvt_pk_bf16_f32 v36, v43, v48
	v_cvt_pk_bf16_f32 v37, v49, v50
	global_store_dwordx4 v[40:41], v[34:37], off offset:256
	s_and_saveexec_b64 s[28:29], s[6:7]
	s_cbranch_execz .LBB0_370
	s_waitcnt lgkmcnt(0)
	v_add_f32_e32 v34, v32, v33
	s_lshl_b32 s30, s40, 2
	v_lshlrev_b64 v[32:33], 7, v[96:97]
	s_ashr_i32 s31, s30, 31
	v_lshl_add_u64 v[32:33], s[2:3], 0, v[32:33]
	v_lshl_add_u64 v[32:33], s[30:31], 2, v[32:33]
	s_lshl_b32 s0, s50, 2
	v_lshl_add_u64 v[32:33], v[32:33], 0, s[0:1]
	global_store_dword v[32:33], v34, off
; __device__ __forceinline__ unsigned pk2(float lo, float hi) { unsigned r; asm volatile("v_cvt_pk_bf16_f32 %0, %1, %2" : "=v"(r) : "v"(lo), "v"(hi)); return r; }
; __device__ __forceinline__ unsigned pk2(float lo, float hi) { return f2bf(lo) | (f2bf(hi) << 16); }
;     __device__ __forceinline__ void epi(const f32x4 (&acc)[2][2][4][2], const Unit& u, int wr, int wc, int fr, int fq) const {
;     ...
;             for (int m = 0; m < 4; ++m) {
;                 const int row = row0 + ai * 128 + m * 16; const size_t off = (size_t)row * D + col0; float ss = 0.f;
; #pragma unroll
;                 for (int bj = 0; bj < 2; ++bj) {
;                     const u32x4 o = xo[m][bj]; const f32x4 a0v = acc[ai][bj][m][0], a1v = acc[ai][bj][m][1];
;                     const float v0 = bf_lo(o.x) + coef * a0v[0], v1 = bf_hi(o.x) + coef * a0v[1], v2 = bf_lo(o.y) + coef * a0v[2], v3 = bf_hi(o.y) + coef * a0v[3];
;                     const float v4 = bf_lo(o.z) + coef * a1v[0], v5 = bf_hi(o.z) + coef * a1v[1], v6 = bf_lo(o.w) + coef * a1v[2], v7 = bf_hi(o.w) + coef * a1v[3];
;                     u32x4 w; w.x = pk2(v0, v1); w.y = pk2(v2, v3); w.z = pk2(v4, v5); w.w = pk2(v6, v7);
;                     *(u32x4*)(xb + off + bj * 128) = w;
;                     ss += ((v0 * v0 + v1 * v1) + (v2 * v2 + v3 * v3)) + ((v4 * v4 + v5 * v5) + (v6 * v6 + v7 * v7));
;                 }
;                 ss += __shfl_xor(ss, 16); ss += __shfl_xor(ss, 32);
;                 if (fq == 0) rowss[(size_t)row * 32 + u.pn * 4 + wc] = ss;
;             }
.LBB0_370:
	s_or_b64 exec, exec, s[28:29]
	v_lshlrev_b32_e32 v32, 16, v76
	v_fmac_f32_e32 v32, 0.5, v28
	v_and_b32_e32 v28, 0xffff0000, v76
	v_fmac_f32_e32 v28, 0.5, v29
	v_lshlrev_b32_e32 v29, 16, v77
	v_fmac_f32_e32 v29, 0.5, v30
	v_and_b32_e32 v30, 0xffff0000, v77
	v_fmac_f32_e32 v30, 0.5, v31
	v_lshlrev_b32_e32 v31, 16, v78
	s_waitcnt lgkmcnt(0)
	v_and_b32_e32 v33, 0xffff0000, v78
	v_fmac_f32_e32 v31, 0.5, v20
	v_fmac_f32_e32 v33, 0.5, v21
	v_and_b32_e32 v35, 0xffff0000, v79
	v_cvt_pk_bf16_f32 v20, v32, v28
	v_cvt_pk_bf16_f32 v21, v29, v30
	v_mul_f32_e32 v28, v28, v28
	v_mul_f32_e32 v30, v30, v30
	v_lshlrev_b32_e32 v34, 16, v79
	v_fmac_f32_e32 v35, 0.5, v23
	v_fmac_f32_e32 v28, v32, v32
	v_fmac_f32_e32 v30, v29, v29
	v_fmac_f32_e32 v34, 0.5, v22
	v_add_f32_e32 v28, v28, v30
	v_mul_f32_e32 v29, v33, v33
	v_mul_f32_e32 v30, v35, v35
	v_cvt_pk_bf16_f32 v22, v31, v33
	v_fmac_f32_e32 v29, v31, v31
	v_fmac_f32_e32 v30, v34, v34
	v_lshlrev_b32_e32 v31, 16, v73
	v_add_f32_e32 v29, v29, v30
	v_and_b32_e32 v30, 0xffff0000, v72
	v_fmac_f32_e32 v31, 0.5, v26
	v_and_b32_e32 v26, 0xffff0000, v73
	v_add_f32_e32 v28, v28, v29
	v_lshlrev_b32_e32 v29, 16, v72
	v_fmac_f32_e32 v30, 0.5, v25
	v_fmac_f32_e32 v26, 0.5, v27
	v_lshlrev_b32_e32 v27, 16, v74
	v_and_b32_e32 v32, 0xffff0000, v74
	v_cvt_pk_bf16_f32 v23, v34, v35
	v_fmac_f32_e32 v29, 0.5, v24
	v_fmac_f32_e32 v27, 0.5, v16
	v_fmac_f32_e32 v32, 0.5, v17
	v_and_b32_e32 v34, 0xffff0000, v75
	v_mul_f32_e32 v16, v30, v30
	v_mul_f32_e32 v17, v26, v26
	v_lshlrev_b32_e32 v33, 16, v75
	v_fmac_f32_e32 v34, 0.5, v19
	v_fmac_f32_e32 v16, v29, v29
	v_fmac_f32_e32 v17, v31, v31
	v_fmac_f32_e32 v33, 0.5, v18
	v_add_f32_e32 v16, v16, v17
	v_mul_f32_e32 v17, v32, v32
	v_mul_f32_e32 v18, v34, v34
	v_fmac_f32_e32 v17, v27, v27
	v_fmac_f32_e32 v18, v33, v33
	v_add_f32_e32 v17, v17, v18
	v_add_f32_e32 v16, v16, v17
	v_add_f32_e32 v19, v28, v16
	ds_bpermute_b32 v28, v112, v19
	v_lshl_add_u64 v[16:17], s[20:21], 0, v[94:95]
	v_lshl_add_u64 v[24:25], v[166:167], 1, v[16:17]
	global_store_dwordx4 v[24:25], v[20:23], off
	v_cvt_pk_bf16_f32 v18, v29, v30
	s_waitcnt lgkmcnt(0)
	v_add_f32_e32 v16, v19, v28
	ds_bpermute_b32 v17, v113, v16
	v_cvt_pk_bf16_f32 v19, v31, v26
	v_cvt_pk_bf16_f32 v20, v27, v32
	v_cvt_pk_bf16_f32 v21, v33, v34
	global_store_dwordx4 v[24:25], v[18:21], off offset:256
	s_and_saveexec_b64 s[28:29], s[6:7]
	s_cbranch_execz .LBB0_372
	s_waitcnt lgkmcnt(0)
	v_add_f32_e32 v18, v16, v17
	s_lshl_b32 s30, s40, 2
	v_lshlrev_b64 v[16:17], 7, v[92:93]
	s_ashr_i32 s31, s30, 31
	v_lshl_add_u64 v[16:17], s[2:3], 0, v[16:17]
	v_lshl_add_u64 v[16:17], s[30:31], 2, v[16:17]
	s_lshl_b32 s0, s50, 2
	v_lshl_add_u64 v[16:17], v[16:17], 0, s[0:1]
	global_store_dword v[16:17], v18, off
.LBB0_372:
	s_or_b64 exec, exec, s[28:29]
	v_lshlrev_b32_e32 v16, 16, v68
	v_fmac_f32_e32 v16, 0.5, v12
	v_and_b32_e32 v12, 0xffff0000, v68
	v_fmac_f32_e32 v12, 0.5, v13
	v_lshlrev_b32_e32 v13, 16, v69
	v_fmac_f32_e32 v13, 0.5, v14
	v_and_b32_e32 v14, 0xffff0000, v69
	v_fmac_f32_e32 v14, 0.5, v15
	v_lshlrev_b32_e32 v15, 16, v70
	s_waitcnt lgkmcnt(0)
	v_and_b32_e32 v17, 0xffff0000, v70
	v_fmac_f32_e32 v15, 0.5, v4
	v_fmac_f32_e32 v17, 0.5, v5
	v_and_b32_e32 v19, 0xffff0000, v71
	v_cvt_pk_bf16_f32 v4, v16, v12
	v_cvt_pk_bf16_f32 v5, v13, v14
	v_mul_f32_e32 v12, v12, v12
	v_mul_f32_e32 v14, v14, v14
	v_lshlrev_b32_e32 v18, 16, v71
	v_fmac_f32_e32 v19, 0.5, v7
	v_fmac_f32_e32 v12, v16, v16
	v_fmac_f32_e32 v14, v13, v13
	v_fmac_f32_e32 v18, 0.5, v6
	v_add_f32_e32 v12, v12, v14
	v_mul_f32_e32 v13, v17, v17
	v_mul_f32_e32 v14, v19, v19
	v_cvt_pk_bf16_f32 v6, v15, v17
	v_fmac_f32_e32 v13, v15, v15
	v_fmac_f32_e32 v14, v18, v18
	v_lshlrev_b32_e32 v15, 16, v65
	v_add_f32_e32 v13, v13, v14
	v_and_b32_e32 v14, 0xffff0000, v64
	v_fmac_f32_e32 v15, 0.5, v10
	v_and_b32_e32 v10, 0xffff0000, v65
	v_add_f32_e32 v12, v12, v13
	v_lshlrev_b32_e32 v13, 16, v64
	v_fmac_f32_e32 v14, 0.5, v9
	v_fmac_f32_e32 v10, 0.5, v11
	v_lshlrev_b32_e32 v11, 16, v66
	v_and_b32_e32 v16, 0xffff0000, v66
	v_cvt_pk_bf16_f32 v7, v18, v19
	v_fmac_f32_e32 v13, 0.5, v8
	v_fmac_f32_e32 v11, 0.5, v0
	v_fmac_f32_e32 v16, 0.5, v1
	v_and_b32_e32 v18, 0xffff0000, v67
	v_mul_f32_e32 v0, v14, v14
	v_mul_f32_e32 v1, v10, v10
	v_lshlrev_b32_e32 v17, 16, v67
	v_fmac_f32_e32 v18, 0.5, v3
	v_fmac_f32_e32 v0, v13, v13
	v_fmac_f32_e32 v1, v15, v15
	v_fmac_f32_e32 v17, 0.5, v2
	v_add_f32_e32 v0, v0, v1
	v_mul_f32_e32 v1, v16, v16
	v_mul_f32_e32 v2, v18, v18
	v_fmac_f32_e32 v1, v11, v11
	v_fmac_f32_e32 v2, v17, v17
	v_add_f32_e32 v1, v1, v2
	v_add_f32_e32 v0, v0, v1
	v_add_f32_e32 v3, v12, v0
	ds_bpermute_b32 v12, v112, v3
	v_lshl_add_u64 v[0:1], s[20:21], 0, v[90:91]
	v_lshl_add_u64 v[8:9], v[166:167], 1, v[0:1]
	global_store_dwordx4 v[8:9], v[4:7], off
	v_cvt_pk_bf16_f32 v2, v13, v14
	s_waitcnt lgkmcnt(0)
	v_add_f32_e32 v0, v3, v12
	ds_bpermute_b32 v1, v113, v0
	v_cvt_pk_bf16_f32 v3, v15, v10
	v_cvt_pk_bf16_f32 v4, v11, v16
	v_cvt_pk_bf16_f32 v5, v17, v18
	global_store_dwordx4 v[8:9], v[2:5], off offset:256
	s_and_saveexec_b64 s[28:29], s[6:7]
	s_cbranch_execz .LBB0_349
	s_waitcnt lgkmcnt(0)
	v_add_f32_e32 v2, v0, v1
	s_lshl_b32 s30, s40, 2
	v_lshlrev_b64 v[0:1], 7, v[88:89]
	s_ashr_i32 s31, s30, 31
	v_lshl_add_u64 v[0:1], s[2:3], 0, v[0:1]
	v_lshl_add_u64 v[0:1], s[30:31], 2, v[0:1]
	s_lshl_b32 s0, s50, 2
	v_lshl_add_u64 v[0:1], v[0:1], 0, s[0:1]
	global_store_dword v[0:1], v2, off
	s_branch .LBB0_349

.LBB0_920:
	ds_read_b128 v[132:135], v172
	ds_read_b128 v[136:139], v172 offset:1024
	ds_read_b128 v[152:155], v172 offset:2048
	ds_read_b128 v[156:159], v172 offset:3072
	s_add_i32 s19, s30, 0xfffc0080
	s_cmp_eq_u32 s17, 12
	s_cselect_b64 s[34:35], -1, 0
	s_and_b64 s[60:61], s[34:35], exec
	s_cselect_b32 s19, 0, s19
	s_and_b64 s[34:35], s[28:29], s[34:35]
	s_and_b64 s[34:35], s[34:35], exec
	s_cselect_b32 s61, s21, s25
	s_cselect_b32 s60, s20, s24
	s_cselect_b32 s35, s23, s27
	s_cselect_b32 s34, s22, s26
	s_mov_b32 m0, s48
	v_lshl_add_u64 v[168:169], v[120:121], 0, s[30:31]
	ds_read_b128 v[160:163], v173
	ds_read_b128 v[164:167], v173 offset:1024
	ds_read_b128 v[178:181], v173 offset:2048
	ds_read_b128 v[182:185], v173 offset:3072
	ds_read_b128 v[186:189], v173 offset:4096
	ds_read_b128 v[190:193], v173 offset:5120
	ds_read_b128 v[194:197], v173 offset:6144
	ds_read_b128 v[198:201], v173 offset:7168
	global_load_lds_dwordx4 v[168:169], off
	v_lshl_add_u64 v[168:169], v[122:123], 0, s[30:31]
	s_mov_b32 m0, s49
	s_nop 0
	global_load_lds_dwordx4 v[168:169], off
	s_waitcnt lgkmcnt(8)
	s_barrier
	s_waitcnt lgkmcnt(0)
	s_setprio 1
	s_waitcnt lgkmcnt(0)
	v_mfma_f32_16x16x32_bf16 v[116:119], v[132:135], v[160:163], v[116:119]
	v_mfma_f32_16x16x32_bf16 v[112:115], v[152:155], v[160:163], v[112:115]
	v_mfma_f32_16x16x32_bf16 v[100:103], v[132:135], v[178:181], v[100:103]
	v_mfma_f32_16x16x32_bf16 v[96:99], v[152:155], v[178:181], v[96:99]
	v_mfma_f32_16x16x32_bf16 v[84:87], v[132:135], v[186:189], v[84:87]
	v_mfma_f32_16x16x32_bf16 v[80:83], v[152:155], v[186:189], v[80:83]
	v_mfma_f32_16x16x32_bf16 v[68:71], v[132:135], v[194:197], v[68:71]
	v_mfma_f32_16x16x32_bf16 v[64:67], v[152:155], v[194:197], v[64:67]
	v_mfma_f32_16x16x32_bf16 v[116:119], v[136:139], v[164:167], v[116:119]
	v_mfma_f32_16x16x32_bf16 v[112:115], v[156:159], v[164:167], v[112:115]
	v_mfma_f32_16x16x32_bf16 v[100:103], v[136:139], v[182:185], v[100:103]
	v_mfma_f32_16x16x32_bf16 v[96:99], v[156:159], v[182:185], v[96:99]
	v_mfma_f32_16x16x32_bf16 v[84:87], v[136:139], v[190:193], v[84:87]
	v_mfma_f32_16x16x32_bf16 v[80:83], v[156:159], v[190:193], v[80:83]
	v_mfma_f32_16x16x32_bf16 v[68:71], v[136:139], v[198:201], v[68:71]
	v_mfma_f32_16x16x32_bf16 v[64:67], v[156:159], v[198:201], v[64:67]
	s_setprio 0
	s_barrier
	s_add_u32 s34, s34, s19
	s_addc_u32 s35, s35, 0
	s_mov_b32 m0, s50
	v_lshl_add_u64 v[168:169], s[34:35], 0, v[144:145]
	ds_read_b128 v[202:205], v174
	ds_read_b128 v[206:209], v174 offset:1024
	ds_read_b128 v[210:213], v174 offset:2048
	ds_read_b128 v[214:217], v174 offset:3072
	global_load_lds_dwordx4 v[168:169], off
	v_lshl_add_u64 v[218:219], s[34:35], 0, v[140:141]
	s_mov_b32 m0, s51
	s_nop 0
	global_load_lds_dwordx4 v[218:219], off
	s_barrier
	s_waitcnt lgkmcnt(0)
	s_setprio 1
	s_waitcnt lgkmcnt(0)
	v_mfma_f32_16x16x32_bf16 v[128:131], v[202:205], v[160:163], v[128:131]
	v_mfma_f32_16x16x32_bf16 v[124:127], v[210:213], v[160:163], v[124:127]
	v_mfma_f32_16x16x32_bf16 v[108:111], v[202:205], v[178:181], v[108:111]
	v_mfma_f32_16x16x32_bf16 v[104:107], v[210:213], v[178:181], v[104:107]
	v_mfma_f32_16x16x32_bf16 v[92:95], v[202:205], v[186:189], v[92:95]
	v_mfma_f32_16x16x32_bf16 v[88:91], v[210:213], v[186:189], v[88:91]
	v_mfma_f32_16x16x32_bf16 v[76:79], v[202:205], v[194:197], v[76:79]
	v_mfma_f32_16x16x32_bf16 v[72:75], v[210:213], v[194:197], v[72:75]
	v_mfma_f32_16x16x32_bf16 v[128:131], v[206:209], v[164:167], v[128:131]
	v_mfma_f32_16x16x32_bf16 v[124:127], v[214:217], v[164:167], v[124:127]
	v_mfma_f32_16x16x32_bf16 v[108:111], v[206:209], v[182:185], v[108:111]
	v_mfma_f32_16x16x32_bf16 v[104:107], v[214:217], v[182:185], v[104:107]
	v_mfma_f32_16x16x32_bf16 v[92:95], v[206:209], v[190:193], v[92:95]
	v_mfma_f32_16x16x32_bf16 v[88:91], v[214:217], v[190:193], v[88:91]
	v_mfma_f32_16x16x32_bf16 v[76:79], v[206:209], v[198:201], v[76:79]
	v_mfma_f32_16x16x32_bf16 v[72:75], v[214:217], v[198:201], v[72:75]
	s_setprio 0
	s_add_u32 s60, s60, s19
	s_addc_u32 s61, s61, 0
	s_mov_b32 m0, s41
	v_lshl_add_u64 v[222:223], s[60:61], 0, v[146:147]
	s_barrier
	ds_read_b128 v[160:163], v173 offset:16384
	ds_read_b128 v[164:167], v173 offset:17408
	ds_read_b128 v[178:181], v173 offset:18432
	ds_read_b128 v[182:185], v173 offset:19456
	ds_read_b128 v[186:189], v173 offset:20480
	ds_read_b128 v[190:193], v173 offset:21504
	ds_read_b128 v[194:197], v173 offset:22528
	ds_read_b128 v[198:201], v173 offset:23552
	global_load_lds_dwordx4 v[222:223], off
	v_lshl_add_u64 v[224:225], s[60:61], 0, v[142:143]
	s_mov_b32 m0, s42
	s_nop 0
	global_load_lds_dwordx4 v[224:225], off
	s_barrier
	s_waitcnt lgkmcnt(0)
	s_setprio 1
	s_waitcnt lgkmcnt(0)
	v_mfma_f32_16x16x32_bf16 v[52:55], v[132:135], v[160:163], v[52:55]
	v_mfma_f32_16x16x32_bf16 v[48:51], v[152:155], v[160:163], v[48:51]
	v_mfma_f32_16x16x32_bf16 v[36:39], v[132:135], v[178:181], v[36:39]
	v_mfma_f32_16x16x32_bf16 v[32:35], v[152:155], v[178:181], v[32:35]
	v_mfma_f32_16x16x32_bf16 v[20:23], v[132:135], v[186:189], v[20:23]
	v_mfma_f32_16x16x32_bf16 v[16:19], v[152:155], v[186:189], v[16:19]
	v_mfma_f32_16x16x32_bf16 v[4:7], v[132:135], v[194:197], v[4:7]
	v_mfma_f32_16x16x32_bf16 v[0:3], v[152:155], v[194:197], v[0:3]
	v_mfma_f32_16x16x32_bf16 v[52:55], v[136:139], v[164:167], v[52:55]
	v_mfma_f32_16x16x32_bf16 v[48:51], v[156:159], v[164:167], v[48:51]
	v_mfma_f32_16x16x32_bf16 v[36:39], v[136:139], v[182:185], v[36:39]
	v_mfma_f32_16x16x32_bf16 v[32:35], v[156:159], v[182:185], v[32:35]
	v_mfma_f32_16x16x32_bf16 v[20:23], v[136:139], v[190:193], v[20:23]
	v_mfma_f32_16x16x32_bf16 v[16:19], v[156:159], v[190:193], v[16:19]
	v_mfma_f32_16x16x32_bf16 v[4:7], v[136:139], v[198:201], v[4:7]
	v_mfma_f32_16x16x32_bf16 v[0:3], v[156:159], v[198:201], v[0:3]
	s_setprio 0
	s_barrier
	s_add_u32 s62, s34, 0x40000
	s_addc_u32 s63, s35, 0
	s_mov_b32 m0, s52
	v_lshl_add_u64 v[132:133], s[62:63], 0, v[144:145]
	global_load_lds_dwordx4 v[132:133], off
	v_lshl_add_u64 v[132:133], s[62:63], 0, v[140:141]
	s_mov_b32 m0, s53
	s_nop 0
	global_load_lds_dwordx4 v[132:133], off
	s_waitcnt vmcnt(6)
	s_barrier
	s_setprio 1
	v_mfma_f32_16x16x32_bf16 v[60:63], v[202:205], v[160:163], v[60:63]
	v_mfma_f32_16x16x32_bf16 v[56:59], v[210:213], v[160:163], v[56:59]
	v_mfma_f32_16x16x32_bf16 v[44:47], v[202:205], v[178:181], v[44:47]
	v_mfma_f32_16x16x32_bf16 v[40:43], v[210:213], v[178:181], v[40:43]
	v_mfma_f32_16x16x32_bf16 v[28:31], v[202:205], v[186:189], v[28:31]
	v_mfma_f32_16x16x32_bf16 v[24:27], v[210:213], v[186:189], v[24:27]
	v_mfma_f32_16x16x32_bf16 v[12:15], v[202:205], v[194:197], v[12:15]
	v_mfma_f32_16x16x32_bf16 v[8:11], v[210:213], v[194:197], v[8:11]
	v_mfma_f32_16x16x32_bf16 v[60:63], v[206:209], v[164:167], v[60:63]
	v_mfma_f32_16x16x32_bf16 v[56:59], v[214:217], v[164:167], v[56:59]
	v_mfma_f32_16x16x32_bf16 v[44:47], v[206:209], v[182:185], v[44:47]
	v_mfma_f32_16x16x32_bf16 v[40:43], v[214:217], v[182:185], v[40:43]
	v_mfma_f32_16x16x32_bf16 v[28:31], v[206:209], v[190:193], v[28:31]
	v_mfma_f32_16x16x32_bf16 v[24:27], v[214:217], v[190:193], v[24:27]
	v_mfma_f32_16x16x32_bf16 v[12:15], v[206:209], v[198:201], v[12:15]
	v_mfma_f32_16x16x32_bf16 v[8:11], v[214:217], v[198:201], v[8:11]
	s_setprio 0
	s_barrier
	ds_read_b128 v[132:135], v176
	ds_read_b128 v[136:139], v176 offset:1024
	ds_read_b128 v[152:155], v176 offset:2048
	ds_read_b128 v[156:159], v176 offset:3072
	s_add_u32 s60, s60, 0x40000
	s_addc_u32 s61, s61, 0
	s_mov_b32 m0, s43
	v_lshl_add_u64 v[202:203], s[60:61], 0, v[146:147]
	ds_read_b128 v[160:163], v173 offset:32768
	ds_read_b128 v[164:167], v173 offset:33792
	ds_read_b128 v[178:181], v173 offset:34816
	ds_read_b128 v[182:185], v173 offset:35840
	ds_read_b128 v[186:189], v173 offset:36864
	ds_read_b128 v[190:193], v173 offset:37888
	ds_read_b128 v[194:197], v173 offset:38912
	ds_read_b128 v[198:201], v173 offset:39936
	global_load_lds_dwordx4 v[202:203], off
	v_lshl_add_u64 v[202:203], s[60:61], 0, v[142:143]
	s_mov_b32 m0, s44
	s_nop 0
	global_load_lds_dwordx4 v[202:203], off
	s_waitcnt lgkmcnt(8)
	s_barrier
	s_waitcnt lgkmcnt(0)
	s_setprio 1
	s_waitcnt lgkmcnt(0)
	v_mfma_f32_16x16x32_bf16 v[116:119], v[132:135], v[160:163], v[116:119]
	v_mfma_f32_16x16x32_bf16 v[112:115], v[152:155], v[160:163], v[112:115]
	v_mfma_f32_16x16x32_bf16 v[100:103], v[132:135], v[178:181], v[100:103]
	v_mfma_f32_16x16x32_bf16 v[96:99], v[152:155], v[178:181], v[96:99]
	v_mfma_f32_16x16x32_bf16 v[84:87], v[132:135], v[186:189], v[84:87]
	v_mfma_f32_16x16x32_bf16 v[80:83], v[152:155], v[186:189], v[80:83]
	v_mfma_f32_16x16x32_bf16 v[68:71], v[132:135], v[194:197], v[68:71]
	v_mfma_f32_16x16x32_bf16 v[64:67], v[152:155], v[194:197], v[64:67]
	v_mfma_f32_16x16x32_bf16 v[116:119], v[136:139], v[164:167], v[116:119]
	v_mfma_f32_16x16x32_bf16 v[112:115], v[156:159], v[164:167], v[112:115]
	v_mfma_f32_16x16x32_bf16 v[100:103], v[136:139], v[182:185], v[100:103]
	v_mfma_f32_16x16x32_bf16 v[96:99], v[156:159], v[182:185], v[96:99]
	v_mfma_f32_16x16x32_bf16 v[84:87], v[136:139], v[190:193], v[84:87]
	v_mfma_f32_16x16x32_bf16 v[80:83], v[156:159], v[190:193], v[80:83]
	v_mfma_f32_16x16x32_bf16 v[68:71], v[136:139], v[198:201], v[68:71]
	v_mfma_f32_16x16x32_bf16 v[64:67], v[156:159], v[198:201], v[64:67]
	s_setprio 0
	s_barrier
	s_mov_b32 m0, s54
	v_lshl_add_u64 v[168:169], v[168:169], 0, s[6:7]
	ds_read_b128 v[202:205], v177
	ds_read_b128 v[206:209], v177 offset:1024
	ds_read_b128 v[210:213], v177 offset:2048
	ds_read_b128 v[214:217], v177 offset:3072
	global_load_lds_dwordx4 v[168:169], off
	v_lshl_add_u64 v[168:169], v[218:219], 0, s[6:7]
	s_mov_b32 m0, s55
	s_nop 0
	global_load_lds_dwordx4 v[168:169], off
	s_barrier
	s_waitcnt lgkmcnt(0)
	s_setprio 1
	s_waitcnt lgkmcnt(0)
	v_mfma_f32_16x16x32_bf16 v[128:131], v[202:205], v[160:163], v[128:131]
	v_mfma_f32_16x16x32_bf16 v[124:127], v[210:213], v[160:163], v[124:127]
	v_mfma_f32_16x16x32_bf16 v[108:111], v[202:205], v[178:181], v[108:111]
	v_mfma_f32_16x16x32_bf16 v[104:107], v[210:213], v[178:181], v[104:107]
	v_mfma_f32_16x16x32_bf16 v[92:95], v[202:205], v[186:189], v[92:95]
	v_mfma_f32_16x16x32_bf16 v[88:91], v[210:213], v[186:189], v[88:91]
	v_mfma_f32_16x16x32_bf16 v[76:79], v[202:205], v[194:197], v[76:79]
	v_mfma_f32_16x16x32_bf16 v[72:75], v[210:213], v[194:197], v[72:75]
	v_mfma_f32_16x16x32_bf16 v[128:131], v[206:209], v[164:167], v[128:131]
	v_mfma_f32_16x16x32_bf16 v[124:127], v[214:217], v[164:167], v[124:127]
	v_mfma_f32_16x16x32_bf16 v[108:111], v[206:209], v[182:185], v[108:111]
	v_mfma_f32_16x16x32_bf16 v[104:107], v[214:217], v[182:185], v[104:107]
	v_mfma_f32_16x16x32_bf16 v[92:95], v[206:209], v[190:193], v[92:95]
	v_mfma_f32_16x16x32_bf16 v[88:91], v[214:217], v[190:193], v[88:91]
	v_mfma_f32_16x16x32_bf16 v[76:79], v[206:209], v[198:201], v[76:79]
	v_mfma_f32_16x16x32_bf16 v[72:75], v[214:217], v[198:201], v[72:75]
	s_setprio 0
	s_mov_b32 m0, s46
	v_lshl_add_u64 v[168:169], v[222:223], 0, s[6:7]
	s_barrier
	ds_read_b128 v[160:163], v173 offset:49152
	ds_read_b128 v[164:167], v173 offset:50176
	ds_read_b128 v[178:181], v173 offset:51200
	ds_read_b128 v[182:185], v173 offset:52224
	ds_read_b128 v[186:189], v173 offset:53248
	ds_read_b128 v[190:193], v173 offset:54272
	ds_read_b128 v[194:197], v173 offset:55296
	ds_read_b128 v[198:201], v173 offset:56320
	global_load_lds_dwordx4 v[168:169], off
	v_lshl_add_u64 v[168:169], v[224:225], 0, s[6:7]
	s_mov_b32 m0, s47
	s_nop 0
	global_load_lds_dwordx4 v[168:169], off
	s_barrier
;     ...
;         G_PAIR(0, 1);
; #pragma unroll 1
;         for (int t = 2; t < nt; t += 2) G_PAIR(t, 0);
	s_waitcnt lgkmcnt(0)
	s_setprio 1
	s_waitcnt lgkmcnt(0)
	v_mfma_f32_16x16x32_bf16 v[52:55], v[132:135], v[160:163], v[52:55]
	v_mfma_f32_16x16x32_bf16 v[48:51], v[152:155], v[160:163], v[48:51]
	v_mfma_f32_16x16x32_bf16 v[36:39], v[132:135], v[178:181], v[36:39]
	v_mfma_f32_16x16x32_bf16 v[32:35], v[152:155], v[178:181], v[32:35]
	v_mfma_f32_16x16x32_bf16 v[20:23], v[132:135], v[186:189], v[20:23]
	v_mfma_f32_16x16x32_bf16 v[16:19], v[152:155], v[186:189], v[16:19]
	v_mfma_f32_16x16x32_bf16 v[4:7], v[132:135], v[194:197], v[4:7]
	v_mfma_f32_16x16x32_bf16 v[0:3], v[152:155], v[194:197], v[0:3]
	v_mfma_f32_16x16x32_bf16 v[52:55], v[136:139], v[164:167], v[52:55]
	v_mfma_f32_16x16x32_bf16 v[48:51], v[156:159], v[164:167], v[48:51]
	v_mfma_f32_16x16x32_bf16 v[36:39], v[136:139], v[182:185], v[36:39]
	v_mfma_f32_16x16x32_bf16 v[32:35], v[156:159], v[182:185], v[32:35]
	v_mfma_f32_16x16x32_bf16 v[20:23], v[136:139], v[190:193], v[20:23]
	v_mfma_f32_16x16x32_bf16 v[16:19], v[156:159], v[190:193], v[16:19]
	v_mfma_f32_16x16x32_bf16 v[4:7], v[136:139], v[198:201], v[4:7]
	v_mfma_f32_16x16x32_bf16 v[0:3], v[156:159], v[198:201], v[0:3]
	s_setprio 0
	s_barrier
	s_add_u32 s34, s34, 0x40080
	s_addc_u32 s35, s35, 0
	s_mov_b32 m0, s56
	v_lshl_add_u64 v[132:133], s[34:35], 0, v[144:145]
	global_load_lds_dwordx4 v[132:133], off
	v_lshl_add_u64 v[132:133], s[34:35], 0, v[140:141]
	s_mov_b32 m0, s57
	s_nop 0
	global_load_lds_dwordx4 v[132:133], off
	s_waitcnt vmcnt(6)
	s_barrier
	s_setprio 1
	v_mfma_f32_16x16x32_bf16 v[60:63], v[202:205], v[160:163], v[60:63]
	v_mfma_f32_16x16x32_bf16 v[56:59], v[210:213], v[160:163], v[56:59]
	v_mfma_f32_16x16x32_bf16 v[44:47], v[202:205], v[178:181], v[44:47]
	v_mfma_f32_16x16x32_bf16 v[40:43], v[210:213], v[178:181], v[40:43]
	v_mfma_f32_16x16x32_bf16 v[28:31], v[202:205], v[186:189], v[28:31]
	v_mfma_f32_16x16x32_bf16 v[24:27], v[210:213], v[186:189], v[24:27]
	v_mfma_f32_16x16x32_bf16 v[12:15], v[202:205], v[194:197], v[12:15]
	v_mfma_f32_16x16x32_bf16 v[8:11], v[210:213], v[194:197], v[8:11]
	v_mfma_f32_16x16x32_bf16 v[60:63], v[206:209], v[164:167], v[60:63]
	v_mfma_f32_16x16x32_bf16 v[56:59], v[214:217], v[164:167], v[56:59]
	v_mfma_f32_16x16x32_bf16 v[44:47], v[206:209], v[182:185], v[44:47]
	v_mfma_f32_16x16x32_bf16 v[40:43], v[214:217], v[182:185], v[40:43]
	v_mfma_f32_16x16x32_bf16 v[28:31], v[206:209], v[190:193], v[28:31]
	v_mfma_f32_16x16x32_bf16 v[24:27], v[214:217], v[190:193], v[24:27]
	v_mfma_f32_16x16x32_bf16 v[12:15], v[206:209], v[198:201], v[12:15]
	v_mfma_f32_16x16x32_bf16 v[8:11], v[214:217], v[198:201], v[8:11]
	s_setprio 0
	s_add_i32 s17, s17, 2
	s_add_u32 s30, s30, 0x100
	s_addc_u32 s31, s31, 0
	s_cmp_gt_u32 s17, 13
	s_barrier
	s_cbranch_scc0 .LBB0_920
; __device__ __forceinline__ unsigned pk2(float lo, float hi) { unsigned r; asm volatile("v_cvt_pk_bf16_f32 %0, %1, %2" : "=v"(r) : "v"(lo), "v"(hi)); return r; }
; __device__ __forceinline__ unsigned pk2(float lo, float hi) { return f2bf(lo) | (f2bf(hi) << 16); }
; __device__ __forceinline__ float fast_sigmoid(float z) { return __builtin_amdgcn_rcpf(1.0f + __expf(-z)); }
;     __device__ __forceinline__ void epi(const f32x4 (&acc)[2][2][4][2], const Unit& u, int wr, int wc, int fr, int fq) const {
;         const int row0 = u.pm * 256 + wr * 64 + fr, col0 = u.pn * 128 + wc * 32 + 8 * fq;
; #pragma unroll
;         for (int ai = 0; ai < 2; ++ai) {
;             u32x4 xo[4];
; #pragma unroll
;             for (int m = 0; m < 4; ++m) xo[m] = *(const u32x4*)(xb + (size_t)(row0 + ai * 128 + m * 16) * D + col0);
; #pragma unroll
;             for (int m = 0; m < 4; ++m) {
;                 const int row = row0 + ai * 128 + m * 16; const size_t off = (size_t)row * D + col0;
;                 const u32x4 o = xo[m]; const f32x4 a0v = acc[ai][0][m][0], a1v = acc[ai][0][m][1], b0v = acc[ai][1][m][0], b1v = acc[ai][1][m][1];
;                 const float v0 = bf_lo(o.x) + coef * a0v[0] * fast_sigmoid(b0v[0]), v1 = bf_hi(o.x) + coef * a0v[1] * fast_sigmoid(b0v[1]);
;                 const float v2 = bf_lo(o.y) + coef * a0v[2] * fast_sigmoid(b0v[2]), v3 = bf_hi(o.y) + coef * a0v[3] * fast_sigmoid(b0v[3]);
;                 const float v4 = bf_lo(o.z) + coef * a1v[0] * fast_sigmoid(b1v[0]), v5 = bf_hi(o.z) + coef * a1v[1] * fast_sigmoid(b1v[1]);
;                 const float v6 = bf_lo(o.w) + coef * a1v[2] * fast_sigmoid(b1v[2]), v7 = bf_hi(o.w) + coef * a1v[3] * fast_sigmoid(b1v[3]);
;                 u32x4 w; w.x = pk2(v0, v1); w.y = pk2(v2, v3); w.z = pk2(v4, v5); w.w = pk2(v6, v7);
;                 *(u32x4*)(xb + off) = w;
;                 float ss = ((v0 * v0 + v1 * v1) + (v2 * v2 + v3 * v3)) + ((v4 * v4 + v5 * v5) + (v6 * v6 + v7 * v7));
;                 ss += __shfl_xor(ss, 16); ss += __shfl_xor(ss, 32);
;                 if (fq == 0) rowss[(size_t)row * 32 + u.pn * 4 + wc] = ss;
	v_lshl_or_b32 v152, s59, 7, v171
	v_lshl_add_u32 v156, s8, 8, v170
	v_ashrrev_i32_e32 v153, 31, v152
	v_lshlrev_b64 v[182:183], 1, v[152:153]
	v_ashrrev_i32_e32 v157, 31, v156
	v_lshl_add_u64 v[154:155], s[0:1], 0, v[182:183]
	v_lshlrev_b64 v[184:185], 11, v[156:157]
	v_lshl_add_u64 v[120:121], v[154:155], 0, v[184:185]
	v_mov_b32_e32 v236, 0x40000
	v_mov_b32_e32 v237, 0
	v_lshl_add_u64 v[234:235], v[120:121], 0, v[236:237]
	v_mov_b32_e32 v236, 0x8000
	global_load_dwordx4 v[178:181], v[120:121], off
	v_or_b32_e32 v166, 16, v156
	v_or_b32_e32 v162, 32, v156
	v_or_b32_e32 v158, 48, v156
	v_ashrrev_i32_e32 v167, 31, v166
	v_ashrrev_i32_e32 v163, 31, v162
	v_ashrrev_i32_e32 v159, 31, v158
	v_lshlrev_b64 v[168:169], 11, v[166:167]
	v_lshlrev_b64 v[164:165], 11, v[162:163]
	v_lshlrev_b64 v[160:161], 11, v[158:159]
	v_lshl_add_u64 v[120:121], v[154:155], 0, v[168:169]
	v_lshl_add_u64 v[122:123], v[154:155], 0, v[164:165]
	v_lshl_add_u64 v[186:187], v[154:155], 0, v[160:161]
	global_load_dwordx4 v[136:139], v[120:121], off
	global_load_dwordx4 v[132:135], v[122:123], off
	s_nop 0
	global_load_dwordx4 v[120:123], v[186:187], off
	global_load_dwordx4 v[238:241], v[234:235], off
	v_lshl_add_u64 v[234:235], v[234:235], 0, v[236:237]
	global_load_dwordx4 v[242:245], v[234:235], off
	v_lshl_add_u64 v[234:235], v[234:235], 0, v[236:237]
	global_load_dwordx4 v[246:249], v[234:235], off
	v_lshl_add_u64 v[234:235], v[234:235], 0, v[236:237]
	global_load_dwordx4 v[250:253], v[234:235], off
	v_mul_f32_e32 v129, 0xbfb8aa3b, v129
	v_mul_f32_e32 v131, 0xbfb8aa3b, v131
	v_mul_f32_e32 v125, 0xbfb8aa3b, v125
	v_mul_f32_e32 v127, 0xbfb8aa3b, v127
	v_mul_f32_e32 v128, 0xbfb8aa3b, v128
	v_mul_f32_e32 v130, 0xbfb8aa3b, v130
	v_mul_f32_e32 v124, 0xbfb8aa3b, v124
	v_mul_f32_e32 v126, 0xbfb8aa3b, v126
	v_exp_f32_e32 v129, v129
	v_exp_f32_e32 v131, v131
	v_exp_f32_e32 v125, v125
	v_exp_f32_e32 v127, v127
	v_exp_f32_e32 v128, v128
	v_exp_f32_e32 v130, v130
	v_exp_f32_e32 v189, v124
	v_exp_f32_e32 v126, v126
	v_and_b32_e32 v187, 64, v175
	v_xor_b32_e32 v186, 16, v175
	v_add_u32_e32 v187, 64, v187
	v_cmp_lt_i32_e32 vcc, v186, v187
	v_add_f32_e32 v129, 1.0, v129
	v_add_f32_e32 v131, 1.0, v131
	v_add_f32_e32 v125, 1.0, v125
	v_add_f32_e32 v127, 1.0, v127
	v_cndmask_b32_e32 v124, v175, v186, vcc
	v_add_f32_e32 v128, 1.0, v128
	v_add_f32_e32 v130, 1.0, v130
	v_add_f32_e32 v186, 1.0, v189
	v_add_f32_e32 v126, 1.0, v126
	v_rcp_f32_e32 v129, v129
	v_rcp_f32_e32 v131, v131
	v_rcp_f32_e32 v125, v125
	v_rcp_f32_e32 v127, v127
	v_rcp_f32_e32 v128, v128
	v_rcp_f32_e32 v130, v130
	v_rcp_f32_e32 v186, v186
	v_rcp_f32_e32 v126, v126
	v_lshlrev_b32_e32 v124, 2, v124
	v_xor_b32_e32 v188, 32, v175
	v_cmp_lt_i32_e32 vcc, v188, v187
	s_lshl_b32 s24, s59, 2
	s_ashr_i32 s25, s24, 31
	s_waitcnt vmcnt(4)
	v_lshlrev_b32_e32 v189, 16, v178
	v_and_b32_e32 v178, 0xffff0000, v178
	v_lshlrev_b32_e32 v190, 16, v179
	v_and_b32_e32 v179, 0xffff0000, v179
	v_lshlrev_b32_e32 v191, 16, v180
	v_and_b32_e32 v180, 0xffff0000, v180
	v_lshlrev_b32_e32 v192, 16, v181
	v_and_b32_e32 v181, 0xffff0000, v181
	v_fmac_f32_e32 v178, v117, v129
	v_fmac_f32_e32 v179, v119, v131
	v_fmac_f32_e32 v180, v113, v125
	v_fmac_f32_e32 v181, v115, v127
	v_fmac_f32_e32 v189, v116, v128
	v_fmac_f32_e32 v190, v118, v130
	v_fmac_f32_e32 v191, v112, v186
	v_fmac_f32_e32 v192, v114, v126
	v_mul_f32_e32 v112, v178, v178
	v_mul_f32_e32 v113, v179, v179
	v_mul_f32_e32 v114, v180, v180
	v_mul_f32_e32 v115, v181, v181
	v_fmac_f32_e32 v112, v189, v189
	v_fmac_f32_e32 v113, v190, v190
	v_fmac_f32_e32 v114, v191, v191
	v_fmac_f32_e32 v115, v192, v192
	v_add_f32_e32 v112, v112, v113
	v_add_f32_e32 v113, v114, v115
	v_add_f32_e32 v112, v112, v113
	ds_bpermute_b32 v113, v124, v112
	v_lshl_add_u64 v[126:127], s[0:1], 0, v[184:185]
	v_lshl_add_u64 v[126:127], v[126:127], 0, v[182:183]
	v_cvt_pk_bf16_f32 v116, v189, v178
	v_cvt_pk_bf16_f32 v117, v190, v179
	s_waitcnt lgkmcnt(0)
	v_add_f32_e32 v113, v112, v113
	v_cndmask_b32_e32 v112, v175, v188, vcc
	v_lshlrev_b32_e32 v112, 2, v112
	ds_bpermute_b32 v114, v112, v113
	v_cvt_pk_bf16_f32 v118, v191, v180
	v_cvt_pk_bf16_f32 v119, v192, v181
	global_store_dwordx4 v[126:127], v[116:119], off
	s_and_saveexec_b64 s[26:27], s[4:5]
	s_cbranch_execz .LBB0_923
	v_lshlrev_b64 v[116:117], 7, v[156:157]
	v_lshl_add_u64 v[116:117], s[2:3], 0, v[116:117]
	v_lshl_add_u64 v[116:117], s[24:25], 2, v[116:117]
	s_lshl_b32 s8, s45, 2
	v_lshl_add_u64 v[116:117], v[116:117], 0, s[8:9]
	s_waitcnt lgkmcnt(0)
	v_add_f32_e32 v113, v113, v114
	global_store_dword v[116:117], v113, off

; __device__ __forceinline__ unsigned pk2(float lo, float hi) { unsigned r; asm volatile("v_cvt_pk_bf16_f32 %0, %1, %2" : "=v"(r) : "v"(lo), "v"(hi)); return r; }
; __device__ __forceinline__ unsigned pk2(float lo, float hi) { return f2bf(lo) | (f2bf(hi) << 16); }
; __device__ __forceinline__ float fast_sigmoid(float z) { return __builtin_amdgcn_rcpf(1.0f + __expf(-z)); }
;     __device__ __forceinline__ void epi(const f32x4 (&acc)[2][2][4][2], const Unit& u, int wr, int wc, int fr, int fq) const {
;     ...
;         for (int ai = 0; ai < 2; ++ai) {
;             u32x4 xo[4];
; #pragma unroll
;             for (int m = 0; m < 4; ++m) xo[m] = *(const u32x4*)(xb + (size_t)(row0 + ai * 128 + m * 16) * D + col0);
; #pragma unroll
;             for (int m = 0; m < 4; ++m) {
;                 const int row = row0 + ai * 128 + m * 16; const size_t off = (size_t)row * D + col0;
;                 const u32x4 o = xo[m]; const f32x4 a0v = acc[ai][0][m][0], a1v = acc[ai][0][m][1], b0v = acc[ai][1][m][0], b1v = acc[ai][1][m][1];
;                 const float v0 = bf_lo(o.x) + coef * a0v[0] * fast_sigmoid(b0v[0]), v1 = bf_hi(o.x) + coef * a0v[1] * fast_sigmoid(b0v[1]);
;                 const float v2 = bf_lo(o.y) + coef * a0v[2] * fast_sigmoid(b0v[2]), v3 = bf_hi(o.y) + coef * a0v[3] * fast_sigmoid(b0v[3]);
;                 const float v4 = bf_lo(o.z) + coef * a1v[0] * fast_sigmoid(b1v[0]), v5 = bf_hi(o.z) + coef * a1v[1] * fast_sigmoid(b1v[1]);
;                 const float v6 = bf_lo(o.w) + coef * a1v[2] * fast_sigmoid(b1v[2]), v7 = bf_hi(o.w) + coef * a1v[3] * fast_sigmoid(b1v[3]);
;                 u32x4 w; w.x = pk2(v0, v1); w.y = pk2(v2, v3); w.z = pk2(v4, v5); w.w = pk2(v6, v7);
;                 *(u32x4*)(xb + off) = w;
;                 float ss = ((v0 * v0 + v1 * v1) + (v2 * v2 + v3 * v3)) + ((v4 * v4 + v5 * v5) + (v6 * v6 + v7 * v7));
;                 ss += __shfl_xor(ss, 16); ss += __shfl_xor(ss, 32);
;                 if (fq == 0) rowss[(size_t)row * 32 + u.pn * 4 + wc] = ss;
.LBB0_929:
	s_or_b64 exec, exec, s[26:27]
	v_add_u32_e32 v88, 0x80, v156
	v_ashrrev_i32_e32 v89, 31, v88
	v_lshlrev_b64 v[94:95], 11, v[88:89]
	s_waitcnt lgkmcnt(0)
	v_lshl_add_u64 v[64:65], v[154:155], 0, v[94:95]
	s_waitcnt vmcnt(4)
	v_mov_b64_e32 v[90:91], v[238:239]
	v_mov_b64_e32 v[92:93], v[240:241]
	v_add_u32_e32 v84, 0x90, v156
	v_add_u32_e32 v80, 0xa0, v156
	v_add_u32_e32 v76, 0xb0, v156
	v_ashrrev_i32_e32 v85, 31, v84
	v_ashrrev_i32_e32 v81, 31, v80
	v_ashrrev_i32_e32 v77, 31, v76
	v_lshlrev_b64 v[86:87], 11, v[84:85]
	v_lshlrev_b64 v[82:83], 11, v[80:81]
	v_lshlrev_b64 v[78:79], 11, v[76:77]
	v_lshl_add_u64 v[64:65], v[154:155], 0, v[86:87]
	v_lshl_add_u64 v[66:67], v[154:155], 0, v[82:83]
	v_lshl_add_u64 v[96:97], v[154:155], 0, v[78:79]
	v_mov_b64_e32 v[72:73], v[242:243]
	v_mov_b64_e32 v[74:75], v[244:245]
	v_mov_b64_e32 v[68:69], v[246:247]
	v_mov_b64_e32 v[70:71], v[248:249]
	s_nop 0
	v_mov_b64_e32 v[64:65], v[250:251]
	v_mov_b64_e32 v[66:67], v[252:253]
	v_mul_f32_e32 v61, 0xbfb8aa3b, v61
	v_mul_f32_e32 v63, 0xbfb8aa3b, v63
	v_mul_f32_e32 v57, 0xbfb8aa3b, v57
	v_mul_f32_e32 v59, 0xbfb8aa3b, v59
	v_mul_f32_e32 v60, 0xbfb8aa3b, v60
	v_mul_f32_e32 v62, 0xbfb8aa3b, v62
	v_mul_f32_e32 v56, 0xbfb8aa3b, v56
	v_mul_f32_e32 v58, 0xbfb8aa3b, v58
	v_exp_f32_e32 v61, v61
	v_exp_f32_e32 v63, v63
	v_exp_f32_e32 v57, v57
	v_exp_f32_e32 v59, v59
	v_exp_f32_e32 v60, v60
	v_exp_f32_e32 v62, v62
	v_exp_f32_e32 v56, v56
	v_exp_f32_e32 v58, v58
	v_add_f32_e32 v61, 1.0, v61
	v_add_f32_e32 v63, 1.0, v63
	v_add_f32_e32 v57, 1.0, v57
	v_add_f32_e32 v59, 1.0, v59
	v_add_f32_e32 v60, 1.0, v60
	v_add_f32_e32 v62, 1.0, v62
	v_add_f32_e32 v56, 1.0, v56
	v_add_f32_e32 v58, 1.0, v58
	v_rcp_f32_e32 v61, v61
	v_rcp_f32_e32 v63, v63
	v_rcp_f32_e32 v57, v57
	v_rcp_f32_e32 v59, v59
	v_rcp_f32_e32 v60, v60
	v_rcp_f32_e32 v62, v62
	v_rcp_f32_e32 v56, v56
	v_rcp_f32_e32 v58, v58
	v_lshlrev_b32_e32 v96, 16, v90
	v_and_b32_e32 v90, 0xffff0000, v90
	v_lshlrev_b32_e32 v97, 16, v91
	v_and_b32_e32 v91, 0xffff0000, v91
	v_lshlrev_b32_e32 v98, 16, v92
	v_and_b32_e32 v92, 0xffff0000, v92
	v_lshlrev_b32_e32 v99, 16, v93
	v_and_b32_e32 v93, 0xffff0000, v93
	v_fmac_f32_e32 v90, v53, v61
	v_fmac_f32_e32 v91, v55, v63
	v_fmac_f32_e32 v92, v49, v57
	v_fmac_f32_e32 v93, v51, v59
	v_fmac_f32_e32 v96, v52, v60
	v_fmac_f32_e32 v97, v54, v62
	v_fmac_f32_e32 v98, v48, v56
	v_fmac_f32_e32 v99, v50, v58
	v_mul_f32_e32 v48, v90, v90
	v_mul_f32_e32 v49, v91, v91
	v_mul_f32_e32 v50, v92, v92
	v_mul_f32_e32 v51, v93, v93
	v_fmac_f32_e32 v48, v96, v96
	v_fmac_f32_e32 v49, v97, v97
	v_fmac_f32_e32 v50, v98, v98
	v_fmac_f32_e32 v51, v99, v99
	v_add_f32_e32 v48, v48, v49
	v_add_f32_e32 v49, v50, v51
	v_add_f32_e32 v48, v48, v49
	ds_bpermute_b32 v49, v124, v48
	v_lshl_add_u64 v[54:55], s[0:1], 0, v[94:95]
	v_lshl_add_u64 v[54:55], v[152:153], 1, v[54:55]
	v_cvt_pk_bf16_f32 v50, v96, v90
	v_cvt_pk_bf16_f32 v51, v97, v91
	s_waitcnt lgkmcnt(0)
	v_add_f32_e32 v48, v48, v49
	ds_bpermute_b32 v49, v112, v48
	v_cvt_pk_bf16_f32 v52, v98, v92
	v_cvt_pk_bf16_f32 v53, v99, v93
	global_store_dwordx4 v[54:55], v[50:53], off
	s_and_saveexec_b64 s[26:27], s[4:5]
	s_cbranch_execz .LBB0_931
	v_lshlrev_b64 v[50:51], 7, v[88:89]
	v_lshl_add_u64 v[50:51], s[2:3], 0, v[50:51]
	v_lshl_add_u64 v[50:51], s[24:25], 2, v[50:51]
	s_lshl_b32 s8, s45, 2
	v_lshl_add_u64 v[50:51], v[50:51], 0, s[8:9]
	s_waitcnt lgkmcnt(0)
	v_add_f32_e32 v48, v48, v49
	global_store_dword v[50:51], v48, off
.LBB0_931:
	s_or_b64 exec, exec, s[26:27]
	v_mul_f32_e32 v44, 0xbfb8aa3b, v44
	v_exp_f32_e32 v44, v44
	v_mul_f32_e32 v45, 0xbfb8aa3b, v45
	v_exp_f32_e32 v45, v45
	v_lshlrev_b32_e32 v48, 16, v72
	v_add_f32_e32 v44, 1.0, v44
	v_rcp_f32_e32 v44, v44
	v_add_f32_e32 v45, 1.0, v45
	v_rcp_f32_e32 v45, v45
	s_waitcnt lgkmcnt(0)
	v_and_b32_e32 v49, 0xffff0000, v72
	v_fmac_f32_e32 v48, v36, v44
	v_mul_f32_e32 v36, 0xbfb8aa3b, v46
	v_fmac_f32_e32 v49, v37, v45
	v_exp_f32_e32 v36, v36
	v_mul_f32_e32 v37, 0xbfb8aa3b, v47
	v_exp_f32_e32 v37, v37
	v_mul_f32_e32 v40, 0xbfb8aa3b, v40
	v_add_f32_e32 v36, 1.0, v36
	v_rcp_f32_e32 v36, v36
	v_add_f32_e32 v37, 1.0, v37
	v_rcp_f32_e32 v37, v37
	v_exp_f32_e32 v40, v40
	v_lshlrev_b32_e32 v44, 16, v73
	v_fmac_f32_e32 v44, v38, v36
	v_and_b32_e32 v36, 0xffff0000, v73
	v_fmac_f32_e32 v36, v39, v37
	v_add_f32_e32 v37, 1.0, v40
	v_mul_f32_e32 v38, 0xbfb8aa3b, v41
	v_rcp_f32_e32 v37, v37
	v_exp_f32_e32 v38, v38
	v_lshlrev_b32_e32 v39, 16, v74
	v_mul_f32_e32 v40, 0xbfb8aa3b, v43
	v_fmac_f32_e32 v39, v32, v37
	v_add_f32_e32 v37, 1.0, v38
	v_mul_f32_e32 v38, 0xbfb8aa3b, v42
	v_rcp_f32_e32 v37, v37
	v_exp_f32_e32 v38, v38
	v_exp_f32_e32 v40, v40
	v_and_b32_e32 v32, 0xffff0000, v74
	v_fmac_f32_e32 v32, v33, v37
	v_add_f32_e32 v33, 1.0, v38
	v_rcp_f32_e32 v33, v33
	v_add_f32_e32 v37, 1.0, v40
	v_rcp_f32_e32 v37, v37
	v_lshlrev_b32_e32 v38, 16, v75
	v_fmac_f32_e32 v38, v34, v33
	v_and_b32_e32 v40, 0xffff0000, v75
	v_mul_f32_e32 v33, v49, v49
	v_mul_f32_e32 v34, v36, v36
	v_fmac_f32_e32 v40, v35, v37
	v_fmac_f32_e32 v33, v48, v48
	v_fmac_f32_e32 v34, v44, v44
	v_add_f32_e32 v33, v33, v34
	v_mul_f32_e32 v34, v32, v32
	v_mul_f32_e32 v35, v40, v40
	v_fmac_f32_e32 v34, v39, v39
	v_fmac_f32_e32 v35, v38, v38
	v_add_f32_e32 v34, v34, v35
	v_add_f32_e32 v33, v33, v34
	ds_bpermute_b32 v37, v124, v33
	v_cvt_pk_bf16_f32 v34, v48, v49
	v_cvt_pk_bf16_f32 v35, v44, v36
	v_cvt_pk_bf16_f32 v36, v39, v32
	s_waitcnt lgkmcnt(0)
	v_add_f32_e32 v32, v33, v37
	ds_bpermute_b32 v33, v112, v32
	v_cvt_pk_bf16_f32 v37, v38, v40
	v_lshl_add_u64 v[38:39], s[0:1], 0, v[86:87]
	v_lshl_add_u64 v[38:39], v[152:153], 1, v[38:39]
	global_store_dwordx4 v[38:39], v[34:37], off
	s_and_saveexec_b64 s[26:27], s[4:5]
	s_cbranch_execz .LBB0_933
	v_lshlrev_b64 v[34:35], 7, v[84:85]
	v_lshl_add_u64 v[34:35], s[2:3], 0, v[34:35]
	v_lshl_add_u64 v[34:35], s[24:25], 2, v[34:35]
	s_lshl_b32 s8, s45, 2
	v_lshl_add_u64 v[34:35], v[34:35], 0, s[8:9]
	s_waitcnt lgkmcnt(0)
	v_add_f32_e32 v32, v32, v33
	global_store_dword v[34:35], v32, off
; __device__ __forceinline__ unsigned pk2(float lo, float hi) { unsigned r; asm volatile("v_cvt_pk_bf16_f32 %0, %1, %2" : "=v"(r) : "v"(lo), "v"(hi)); return r; }
; __device__ __forceinline__ unsigned pk2(float lo, float hi) { return f2bf(lo) | (f2bf(hi) << 16); }
; __device__ __forceinline__ float fast_sigmoid(float z) { return __builtin_amdgcn_rcpf(1.0f + __expf(-z)); }
;     __device__ __forceinline__ void epi(const f32x4 (&acc)[2][2][4][2], const Unit& u, int wr, int wc, int fr, int fq) const {
;     ...
;             for (int m = 0; m < 4; ++m) {
;                 const int row = row0 + ai * 128 + m * 16; const size_t off = (size_t)row * D + col0;
;                 const u32x4 o = xo[m]; const f32x4 a0v = acc[ai][0][m][0], a1v = acc[ai][0][m][1], b0v = acc[ai][1][m][0], b1v = acc[ai][1][m][1];
;                 const float v0 = bf_lo(o.x) + coef * a0v[0] * fast_sigmoid(b0v[0]), v1 = bf_hi(o.x) + coef * a0v[1] * fast_sigmoid(b0v[1]);
;                 const float v2 = bf_lo(o.y) + coef * a0v[2] * fast_sigmoid(b0v[2]), v3 = bf_hi(o.y) + coef * a0v[3] * fast_sigmoid(b0v[3]);
;                 const float v4 = bf_lo(o.z) + coef * a1v[0] * fast_sigmoid(b1v[0]), v5 = bf_hi(o.z) + coef * a1v[1] * fast_sigmoid(b1v[1]);
;                 const float v6 = bf_lo(o.w) + coef * a1v[2] * fast_sigmoid(b1v[2]), v7 = bf_hi(o.w) + coef * a1v[3] * fast_sigmoid(b1v[3]);
;                 u32x4 w; w.x = pk2(v0, v1); w.y = pk2(v2, v3); w.z = pk2(v4, v5); w.w = pk2(v6, v7);
;                 *(u32x4*)(xb + off) = w;
;                 float ss = ((v0 * v0 + v1 * v1) + (v2 * v2 + v3 * v3)) + ((v4 * v4 + v5 * v5) + (v6 * v6 + v7 * v7));
;                 ss += __shfl_xor(ss, 16); ss += __shfl_xor(ss, 32);
;                 if (fq == 0) rowss[(size_t)row * 32 + u.pn * 4 + wc] = ss;
.LBB0_933:
	s_or_b64 exec, exec, s[26:27]
	v_mul_f32_e32 v28, 0xbfb8aa3b, v28
	v_exp_f32_e32 v28, v28
	v_mul_f32_e32 v29, 0xbfb8aa3b, v29
	v_exp_f32_e32 v29, v29
	v_lshlrev_b32_e32 v32, 16, v68
	v_add_f32_e32 v28, 1.0, v28
	v_rcp_f32_e32 v28, v28
	v_add_f32_e32 v29, 1.0, v29
	v_rcp_f32_e32 v29, v29
	s_waitcnt lgkmcnt(0)
	v_and_b32_e32 v33, 0xffff0000, v68
	v_fmac_f32_e32 v32, v20, v28
	v_mul_f32_e32 v20, 0xbfb8aa3b, v30
	v_fmac_f32_e32 v33, v21, v29
	v_exp_f32_e32 v20, v20
	v_mul_f32_e32 v21, 0xbfb8aa3b, v31
	v_exp_f32_e32 v21, v21
	v_mul_f32_e32 v24, 0xbfb8aa3b, v24
	v_add_f32_e32 v20, 1.0, v20
	v_rcp_f32_e32 v20, v20
	v_add_f32_e32 v21, 1.0, v21
	v_rcp_f32_e32 v21, v21
	v_exp_f32_e32 v24, v24
	v_lshlrev_b32_e32 v28, 16, v69
	v_fmac_f32_e32 v28, v22, v20
	v_and_b32_e32 v20, 0xffff0000, v69
	v_fmac_f32_e32 v20, v23, v21
	v_add_f32_e32 v21, 1.0, v24
	v_mul_f32_e32 v22, 0xbfb8aa3b, v25
	v_rcp_f32_e32 v21, v21
	v_exp_f32_e32 v22, v22
	v_lshlrev_b32_e32 v23, 16, v70
	v_mul_f32_e32 v24, 0xbfb8aa3b, v27
	v_fmac_f32_e32 v23, v16, v21
	v_add_f32_e32 v21, 1.0, v22
	v_mul_f32_e32 v22, 0xbfb8aa3b, v26
	v_rcp_f32_e32 v21, v21
	v_exp_f32_e32 v22, v22
	v_exp_f32_e32 v24, v24
	v_and_b32_e32 v16, 0xffff0000, v70
	v_fmac_f32_e32 v16, v17, v21
	v_add_f32_e32 v17, 1.0, v22
	v_rcp_f32_e32 v17, v17
	v_add_f32_e32 v21, 1.0, v24
	v_rcp_f32_e32 v21, v21
	v_lshlrev_b32_e32 v22, 16, v71
	v_fmac_f32_e32 v22, v18, v17
	v_and_b32_e32 v24, 0xffff0000, v71
	v_mul_f32_e32 v17, v33, v33
	v_mul_f32_e32 v18, v20, v20
	v_fmac_f32_e32 v24, v19, v21
	v_fmac_f32_e32 v17, v32, v32
	v_fmac_f32_e32 v18, v28, v28
	v_add_f32_e32 v17, v17, v18
	v_mul_f32_e32 v18, v16, v16
	v_mul_f32_e32 v19, v24, v24
	v_fmac_f32_e32 v18, v23, v23
	v_fmac_f32_e32 v19, v22, v22
	v_add_f32_e32 v18, v18, v19
	v_add_f32_e32 v17, v17, v18
	ds_bpermute_b32 v21, v124, v17
	v_cvt_pk_bf16_f32 v18, v32, v33
	v_cvt_pk_bf16_f32 v19, v28, v20
	v_cvt_pk_bf16_f32 v20, v23, v16
	s_waitcnt lgkmcnt(0)
	v_add_f32_e32 v16, v17, v21
	ds_bpermute_b32 v17, v112, v16
	v_cvt_pk_bf16_f32 v21, v22, v24
	v_lshl_add_u64 v[22:23], s[0:1], 0, v[82:83]
	v_lshl_add_u64 v[22:23], v[152:153], 1, v[22:23]
	global_store_dwordx4 v[22:23], v[18:21], off
	s_and_saveexec_b64 s[26:27], s[4:5]
	s_cbranch_execz .LBB0_935
	v_lshlrev_b64 v[18:19], 7, v[80:81]
	v_lshl_add_u64 v[18:19], s[2:3], 0, v[18:19]
	v_lshl_add_u64 v[18:19], s[24:25], 2, v[18:19]
	s_lshl_b32 s8, s45, 2
	v_lshl_add_u64 v[18:19], v[18:19], 0, s[8:9]
	s_waitcnt lgkmcnt(0)
	v_add_f32_e32 v16, v16, v17
	global_store_dword v[18:19], v16, off
.LBB0_935:
	s_or_b64 exec, exec, s[26:27]
	v_mul_f32_e32 v12, 0xbfb8aa3b, v12
	v_exp_f32_e32 v12, v12
	v_mul_f32_e32 v13, 0xbfb8aa3b, v13
	v_exp_f32_e32 v13, v13
	v_lshlrev_b32_e32 v16, 16, v64
	v_add_f32_e32 v12, 1.0, v12
	v_rcp_f32_e32 v12, v12
	v_add_f32_e32 v13, 1.0, v13
	v_rcp_f32_e32 v13, v13
	s_waitcnt lgkmcnt(0)
	v_and_b32_e32 v17, 0xffff0000, v64
	v_fmac_f32_e32 v16, v4, v12
	v_mul_f32_e32 v4, 0xbfb8aa3b, v14
	v_fmac_f32_e32 v17, v5, v13
	v_exp_f32_e32 v4, v4
	v_mul_f32_e32 v5, 0xbfb8aa3b, v15
	v_exp_f32_e32 v5, v5
	v_mul_f32_e32 v8, 0xbfb8aa3b, v8
	v_add_f32_e32 v4, 1.0, v4
	v_rcp_f32_e32 v4, v4
	v_add_f32_e32 v5, 1.0, v5
	v_rcp_f32_e32 v5, v5
	v_exp_f32_e32 v8, v8
	v_lshlrev_b32_e32 v12, 16, v65
	v_fmac_f32_e32 v12, v6, v4
	v_and_b32_e32 v4, 0xffff0000, v65
	v_fmac_f32_e32 v4, v7, v5
	v_add_f32_e32 v5, 1.0, v8
	v_mul_f32_e32 v6, 0xbfb8aa3b, v9
	v_rcp_f32_e32 v5, v5
	v_exp_f32_e32 v6, v6
	v_lshlrev_b32_e32 v7, 16, v66
	v_mul_f32_e32 v8, 0xbfb8aa3b, v11
	v_fmac_f32_e32 v7, v0, v5
	v_add_f32_e32 v5, 1.0, v6
	v_mul_f32_e32 v6, 0xbfb8aa3b, v10
	v_rcp_f32_e32 v5, v5
	v_exp_f32_e32 v6, v6
	v_exp_f32_e32 v8, v8
	v_and_b32_e32 v0, 0xffff0000, v66
	v_fmac_f32_e32 v0, v1, v5
	v_add_f32_e32 v1, 1.0, v6
	v_rcp_f32_e32 v1, v1
	v_add_f32_e32 v5, 1.0, v8
	v_rcp_f32_e32 v5, v5
	v_lshlrev_b32_e32 v6, 16, v67
	v_fmac_f32_e32 v6, v2, v1
	v_and_b32_e32 v8, 0xffff0000, v67
	v_mul_f32_e32 v1, v17, v17
	v_mul_f32_e32 v2, v4, v4
	v_fmac_f32_e32 v8, v3, v5
	v_fmac_f32_e32 v1, v16, v16
	v_fmac_f32_e32 v2, v12, v12
	v_add_f32_e32 v1, v1, v2
	v_mul_f32_e32 v2, v0, v0
	v_mul_f32_e32 v3, v8, v8
	v_fmac_f32_e32 v2, v7, v7
	v_fmac_f32_e32 v3, v6, v6
	v_add_f32_e32 v2, v2, v3
	v_add_f32_e32 v1, v1, v2
	ds_bpermute_b32 v5, v124, v1
	v_cvt_pk_bf16_f32 v2, v16, v17
	v_cvt_pk_bf16_f32 v3, v12, v4
	v_cvt_pk_bf16_f32 v4, v7, v0
	s_waitcnt lgkmcnt(0)
	v_add_f32_e32 v0, v1, v5
	ds_bpermute_b32 v1, v112, v0
	v_cvt_pk_bf16_f32 v5, v6, v8
	v_lshl_add_u64 v[6:7], s[0:1], 0, v[78:79]
	v_lshl_add_u64 v[6:7], v[152:153], 1, v[6:7]
	global_store_dwordx4 v[6:7], v[2:5], off
	s_and_saveexec_b64 s[26:27], s[4:5]
	s_cbranch_execz .LBB0_916
	v_lshlrev_b64 v[2:3], 7, v[76:77]
	v_lshl_add_u64 v[2:3], s[2:3], 0, v[2:3]
	v_lshl_add_u64 v[2:3], s[24:25], 2, v[2:3]
	s_lshl_b32 s8, s45, 2
	v_lshl_add_u64 v[2:3], v[2:3], 0, s[8:9]
	s_waitcnt lgkmcnt(0)
	v_add_f32_e32 v0, v0, v1
	global_store_dword v[2:3], v0, off
	s_branch .LBB0_916

; #define G_STAGE_A(buf, h, b0, b1, tt) do { const bool _s2 = P::SEG && (tt) >= P::TS; \
;         const char* _g = _s2 ? (b1) + (ptrdiff_t)((tt) - P::TS) * kA2 + (ptrdiff_t)(h) * hA2 : (b0) + (ptrdiff_t)(tt) * kA + (ptrdiff_t)(h) * hA; \
;         stage2(lds + G_SA(buf, h) + ldsw, _g, _s2 ? voA20 : voA0, _s2 ? voA21 : voA1); } while (0)
; #define G_STAGE_B(buf, h, b0, b1, tt) do { const bool _s2 = P::SEG && (tt) >= P::TS; \
;         const char* _g = _s2 ? (b1) + (ptrdiff_t)((tt) - P::TS) * kB2 + (ptrdiff_t)(h) * hB2 : (b0) + (ptrdiff_t)(tt) * kB + (ptrdiff_t)(h) * hB; \
;         stage2(lds + G_SB(buf, h) + ldsw, _g, _s2 ? voB20 : voB0, _s2 ? voB21 : voB1); } while (0)
; #define G_WAIT_V(n) asm volatile("s_waitcnt vmcnt(" #n ")" ::: "memory")
; #define G_BAR __builtin_amdgcn_s_barrier()
;     __device__ __forceinline__ bool unit(int L, Unit& u) const { u.g = L; return order_mn(L, T / 256, NGU / 256, u.pm, u.pn); }
;     __device__ __forceinline__ bool unit(int L, Unit& u) const { u.g = L; return order_mn(L, T / 256, D / 256, u.pm, u.pn); }
;     __device__ __forceinline__ bool unit(int L, Unit& u) const { u.g = 0; return order_mn(L, T / 256, 8, u.pm, u.pn); }
;     __device__ __forceinline__ bool unit(int L, Unit& u) const { if (L >= NG * 4) return false; u.g = L >> 2; u.pm = (L >> 1) & 1; u.pn = L & 1; return true; }
;     __device__ __forceinline__ bool unit(int L, Unit& u) const { if (L >= NG * 8) return false; u.g = L >> 3; u.pm = (L >> 2) & 1; u.pn = L & 3; return true; }
;     ...
;     const char* cA = p.a0(cur); const char* cB = p.b0(cur);
;     const char* cA2 = P::SEG ? p.a1(cur) : cA; const char* cB2 = P::SEG ? p.b1(cur) : cB;
;     G_STAGE_B(0, 0, cB, cB2, 0); G_STAGE_A(0, 0, cA, cA2, 0); G_STAGE_B(0, 1, cB, cB2, 0); G_STAGE_A(0, 1, cA, cA2, 0);
;     if (wr == 1) G_BAR;
;     G_WAIT_V(4); G_BAR;
;     G_STAGE_B(1, 0, cB, cB2, 1); G_STAGE_A(1, 0, cA, cA2, 1); G_STAGE_B(1, 1, cB, cB2, 1);
;     G_WAIT_V(6); G_BAR;
;     for (;;) {
;         const bool has_next = p.unit((ui + 1) * G + c, nxt);
;         const char* nA = has_next ? p.a0(nxt) : cA; const char* nB = has_next ? p.b0(nxt) : cB;
;         const char* nA2 = P::SEG ? (has_next ? p.a1(nxt) : cA2) : nA; const char* nB2 = P::SEG ? (has_next ? p.b1(nxt) : cB2) : nB;
;     ...
;         G_PAIR(0, 1);
.LBB0_1670:
	s_waitcnt lgkmcnt(0)
	ds_read_b128 v[0:3], v173
	ds_read_b128 v[4:7], v173 offset:1024
	ds_read_b128 v[8:11], v173 offset:2048
	ds_read_b128 v[12:15], v173 offset:3072
	s_lshl_b64 s[22:23], s[16:17], 17
	s_add_u32 s22, s35, s22
	s_addc_u32 s23, s36, s23
	s_add_u32 s52, s24, 0x40080
	s_addc_u32 s53, s25, 0
	s_mov_b32 m0, s47
	v_lshl_add_u64 v[48:49], s[52:53], 0, v[150:151]
	ds_read_b128 v[16:19], v174
	ds_read_b128 v[20:23], v174 offset:1024
	ds_read_b128 v[24:27], v174 offset:2048
	ds_read_b128 v[28:31], v174 offset:3072
	ds_read_b128 v[32:35], v174 offset:4096
	ds_read_b128 v[36:39], v174 offset:5120
	ds_read_b128 v[40:43], v174 offset:6144
	ds_read_b128 v[44:47], v174 offset:7168
	global_load_lds_dwordx4 v[48:49], off
	v_lshl_add_u64 v[48:49], s[52:53], 0, v[146:147]
	s_mov_b32 m0, s48
	s_nop 0
	global_load_lds_dwordx4 v[48:49], off
	s_waitcnt lgkmcnt(8)
	s_barrier
	s_waitcnt lgkmcnt(0)
	s_setprio 1
	s_waitcnt lgkmcnt(0)
	v_mfma_f32_16x16x32_bf16 v[48:51], v[0:3], v[16:19], 0
	v_mfma_f32_16x16x32_bf16 v[52:55], v[8:11], v[16:19], 0
	v_mfma_f32_16x16x32_bf16 v[56:59], v[0:3], v[24:27], 0
	v_mfma_f32_16x16x32_bf16 v[60:63], v[8:11], v[24:27], 0
	v_mfma_f32_16x16x32_bf16 v[64:67], v[0:3], v[32:35], 0
	v_mfma_f32_16x16x32_bf16 v[68:71], v[8:11], v[32:35], 0
	v_mfma_f32_16x16x32_bf16 v[72:75], v[0:3], v[40:43], 0
	v_mfma_f32_16x16x32_bf16 v[76:79], v[8:11], v[40:43], 0
	v_mfma_f32_16x16x32_bf16 v[48:51], v[4:7], v[20:23], v[48:51]
	v_mfma_f32_16x16x32_bf16 v[52:55], v[12:15], v[20:23], v[52:55]
	v_mfma_f32_16x16x32_bf16 v[56:59], v[4:7], v[28:31], v[56:59]
	v_mfma_f32_16x16x32_bf16 v[60:63], v[12:15], v[28:31], v[60:63]
	v_mfma_f32_16x16x32_bf16 v[64:67], v[4:7], v[36:39], v[64:67]
	v_mfma_f32_16x16x32_bf16 v[68:71], v[12:15], v[36:39], v[68:71]
	v_mfma_f32_16x16x32_bf16 v[72:75], v[4:7], v[44:47], v[72:75]
	v_mfma_f32_16x16x32_bf16 v[76:79], v[12:15], v[44:47], v[76:79]
	s_setprio 0
	s_barrier
	v_lshl_add_u64 v[168:169], s[26:27], 0, v[148:149]
	s_mov_b32 m0, s49
	v_lshl_add_u64 v[96:97], v[168:169], 0, s[10:11]
	v_lshl_add_u64 v[212:213], s[26:27], 0, v[144:145]
	ds_read_b128 v[80:83], v175
	ds_read_b128 v[84:87], v175 offset:1024
	ds_read_b128 v[88:91], v175 offset:2048
	ds_read_b128 v[92:95], v175 offset:3072
	global_load_lds_dwordx4 v[96:97], off
	v_lshl_add_u64 v[96:97], v[212:213], 0, s[10:11]
	s_mov_b32 m0, s50
	s_nop 0
	global_load_lds_dwordx4 v[96:97], off
	s_barrier
	s_waitcnt lgkmcnt(0)
	s_setprio 1
	s_waitcnt lgkmcnt(0)
	v_mfma_f32_16x16x32_bf16 v[96:99], v[80:83], v[16:19], 0
	v_mfma_f32_16x16x32_bf16 v[16:19], v[88:91], v[16:19], 0
	v_mfma_f32_16x16x32_bf16 v[100:103], v[80:83], v[24:27], 0
	v_mfma_f32_16x16x32_bf16 v[24:27], v[88:91], v[24:27], 0
	v_mfma_f32_16x16x32_bf16 v[104:107], v[80:83], v[32:35], 0
	v_mfma_f32_16x16x32_bf16 v[32:35], v[88:91], v[32:35], 0
	v_mfma_f32_16x16x32_bf16 v[108:111], v[80:83], v[40:43], 0
	v_mfma_f32_16x16x32_bf16 v[40:43], v[88:91], v[40:43], 0
	v_mfma_f32_16x16x32_bf16 v[96:99], v[84:87], v[20:23], v[96:99]
	v_mfma_f32_16x16x32_bf16 v[16:19], v[92:95], v[20:23], v[16:19]
	v_mfma_f32_16x16x32_bf16 v[20:23], v[84:87], v[28:31], v[100:103]
	v_mfma_f32_16x16x32_bf16 v[24:27], v[92:95], v[28:31], v[24:27]
	v_mfma_f32_16x16x32_bf16 v[28:31], v[84:87], v[36:39], v[104:107]
	v_mfma_f32_16x16x32_bf16 v[32:35], v[92:95], v[36:39], v[32:35]
	v_mfma_f32_16x16x32_bf16 v[36:39], v[84:87], v[44:47], v[108:111]
	v_mfma_f32_16x16x32_bf16 v[40:43], v[92:95], v[44:47], v[40:43]
	s_setprio 0
	v_lshl_add_u64 v[214:215], s[24:25], 0, v[150:151]
	s_mov_b32 m0, s38
	v_lshl_add_u64 v[128:129], v[214:215], 0, s[10:11]
	v_lshl_add_u64 v[216:217], s[24:25], 0, v[146:147]
	s_barrier
	ds_read_b128 v[44:47], v174 offset:16384
	ds_read_b128 v[100:103], v174 offset:17408
	ds_read_b128 v[104:107], v174 offset:18432
	ds_read_b128 v[108:111], v174 offset:19456
	ds_read_b128 v[112:115], v174 offset:20480
	ds_read_b128 v[116:119], v174 offset:21504
	ds_read_b128 v[120:123], v174 offset:22528
	ds_read_b128 v[124:127], v174 offset:23552
	global_load_lds_dwordx4 v[128:129], off
	v_lshl_add_u64 v[128:129], v[216:217], 0, s[10:11]
	s_mov_b32 m0, s39
	s_nop 0
	global_load_lds_dwordx4 v[128:129], off
	s_barrier
	s_waitcnt lgkmcnt(0)
	s_setprio 1
	s_waitcnt lgkmcnt(0)
	v_mfma_f32_16x16x32_bf16 v[128:131], v[0:3], v[44:47], 0
	v_mfma_f32_16x16x32_bf16 v[132:135], v[8:11], v[44:47], 0
	v_mfma_f32_16x16x32_bf16 v[136:139], v[0:3], v[104:107], 0
	v_mfma_f32_16x16x32_bf16 v[140:143], v[8:11], v[104:107], 0
	v_mfma_f32_16x16x32_bf16 v[152:155], v[0:3], v[112:115], 0
	v_mfma_f32_16x16x32_bf16 v[156:159], v[8:11], v[112:115], 0
	v_mfma_f32_16x16x32_bf16 v[0:3], v[0:3], v[120:123], 0
	v_mfma_f32_16x16x32_bf16 v[8:11], v[8:11], v[120:123], 0
	v_mfma_f32_16x16x32_bf16 v[128:131], v[4:7], v[100:103], v[128:131]
	v_mfma_f32_16x16x32_bf16 v[136:139], v[4:7], v[108:111], v[136:139]
	v_mfma_f32_16x16x32_bf16 v[140:143], v[12:15], v[108:111], v[140:143]
	v_mfma_f32_16x16x32_bf16 v[152:155], v[4:7], v[116:119], v[152:155]
	v_mfma_f32_16x16x32_bf16 v[156:159], v[12:15], v[116:119], v[156:159]
	v_mfma_f32_16x16x32_bf16 v[0:3], v[4:7], v[124:127], v[0:3]
	v_mfma_f32_16x16x32_bf16 v[4:7], v[12:15], v[124:127], v[8:11]
	v_mfma_f32_16x16x32_bf16 v[132:135], v[12:15], v[100:103], v[132:135]
	s_setprio 0
	s_barrier
	s_add_u32 s52, s26, 0x10100
	s_addc_u32 s53, s27, 0
	s_add_i32 s19, s46, s37
	v_lshl_add_u64 v[8:9], s[52:53], 0, v[148:149]
	s_mov_b32 m0, s19
	s_add_i32 s17, s19, 0x2000
	global_load_lds_dwordx4 v[8:9], off
	v_lshl_add_u64 v[8:9], s[52:53], 0, v[144:145]
	s_mov_b32 m0, s17
	s_nop 0
	global_load_lds_dwordx4 v[8:9], off
	s_waitcnt vmcnt(6)
	s_barrier
	s_setprio 1
	v_mfma_f32_16x16x32_bf16 v[8:11], v[80:83], v[44:47], 0
	v_mfma_f32_16x16x32_bf16 v[12:15], v[88:91], v[44:47], 0
	v_mfma_f32_16x16x32_bf16 v[44:47], v[80:83], v[104:107], 0
	v_mfma_f32_16x16x32_bf16 v[104:107], v[88:91], v[104:107], 0
	v_mfma_f32_16x16x32_bf16 v[160:163], v[80:83], v[112:115], 0
	v_mfma_f32_16x16x32_bf16 v[112:115], v[88:91], v[112:115], 0
	v_mfma_f32_16x16x32_bf16 v[80:83], v[80:83], v[120:123], 0
	v_mfma_f32_16x16x32_bf16 v[88:91], v[88:91], v[120:123], 0
	v_mfma_f32_16x16x32_bf16 v[8:11], v[84:87], v[100:103], v[8:11]
	v_mfma_f32_16x16x32_bf16 v[12:15], v[92:95], v[100:103], v[12:15]
	v_mfma_f32_16x16x32_bf16 v[44:47], v[84:87], v[108:111], v[44:47]
	v_mfma_f32_16x16x32_bf16 v[100:103], v[92:95], v[108:111], v[104:107]
	v_mfma_f32_16x16x32_bf16 v[104:107], v[84:87], v[116:119], v[160:163]
	v_mfma_f32_16x16x32_bf16 v[108:111], v[92:95], v[116:119], v[112:115]
	v_mfma_f32_16x16x32_bf16 v[80:83], v[84:87], v[124:127], v[80:83]
	v_mfma_f32_16x16x32_bf16 v[84:87], v[92:95], v[124:127], v[88:91]
	s_setprio 0
	s_add_i32 s51, 0, 0x18000
	v_add_u32_e32 v221, s51, v171
	s_barrier
	ds_read_b128 v[88:91], v221
	ds_read_b128 v[92:95], v221 offset:1024
	ds_read_b128 v[112:115], v221 offset:2048
	ds_read_b128 v[116:119], v221 offset:3072
	s_add_u32 s52, s24, 0x40100
	s_addc_u32 s53, s25, 0
	s_mov_b32 m0, s40
	v_lshl_add_u64 v[196:197], s[52:53], 0, v[150:151]
	ds_read_b128 v[120:123], v174 offset:32768
	ds_read_b128 v[124:127], v174 offset:33792
	ds_read_b128 v[160:163], v174 offset:34816
	ds_read_b128 v[164:167], v174 offset:35840
	ds_read_b128 v[180:183], v174 offset:36864
	ds_read_b128 v[184:187], v174 offset:37888
	ds_read_b128 v[188:191], v174 offset:38912
	ds_read_b128 v[192:195], v174 offset:39936
	global_load_lds_dwordx4 v[196:197], off
	v_lshl_add_u64 v[196:197], s[52:53], 0, v[146:147]
	s_mov_b32 m0, s41
	s_nop 0
	global_load_lds_dwordx4 v[196:197], off
	s_waitcnt lgkmcnt(8)
	s_barrier
	s_waitcnt lgkmcnt(0)
	s_setprio 1
	s_waitcnt lgkmcnt(0)
	v_mfma_f32_16x16x32_bf16 v[48:51], v[88:91], v[120:123], v[48:51]
	v_mfma_f32_16x16x32_bf16 v[52:55], v[112:115], v[120:123], v[52:55]
	v_mfma_f32_16x16x32_bf16 v[56:59], v[88:91], v[160:163], v[56:59]
	v_mfma_f32_16x16x32_bf16 v[60:63], v[112:115], v[160:163], v[60:63]
	v_mfma_f32_16x16x32_bf16 v[64:67], v[88:91], v[180:183], v[64:67]
	v_mfma_f32_16x16x32_bf16 v[68:71], v[112:115], v[180:183], v[68:71]
	v_mfma_f32_16x16x32_bf16 v[72:75], v[88:91], v[188:191], v[72:75]
	v_mfma_f32_16x16x32_bf16 v[76:79], v[112:115], v[188:191], v[76:79]
	v_mfma_f32_16x16x32_bf16 v[48:51], v[92:95], v[124:127], v[48:51]
	v_mfma_f32_16x16x32_bf16 v[52:55], v[116:119], v[124:127], v[52:55]
	v_mfma_f32_16x16x32_bf16 v[56:59], v[92:95], v[164:167], v[56:59]
	v_mfma_f32_16x16x32_bf16 v[60:63], v[116:119], v[164:167], v[60:63]
	v_mfma_f32_16x16x32_bf16 v[64:67], v[92:95], v[184:187], v[64:67]
	v_mfma_f32_16x16x32_bf16 v[68:71], v[116:119], v[184:187], v[68:71]
	v_mfma_f32_16x16x32_bf16 v[72:75], v[92:95], v[192:195], v[72:75]
	v_mfma_f32_16x16x32_bf16 v[76:79], v[116:119], v[192:195], v[76:79]
	s_setprio 0
	s_barrier
	s_add_i32 s54, 0, 0x1c000
	s_add_i32 s53, s51, s37
	v_add_u32_e32 v226, s54, v171
	v_lshl_add_u64 v[168:169], v[168:169], 0, s[12:13]
	s_mov_b32 m0, s53
	s_add_i32 s51, s53, 0x2000
	ds_read_b128 v[196:199], v226
	ds_read_b128 v[200:203], v226 offset:1024
	ds_read_b128 v[204:207], v226 offset:2048
	ds_read_b128 v[208:211], v226 offset:3072
	global_load_lds_dwordx4 v[168:169], off
	v_lshl_add_u64 v[168:169], v[212:213], 0, s[12:13]
	s_mov_b32 m0, s51
	s_nop 0
	global_load_lds_dwordx4 v[168:169], off
	s_barrier
	s_waitcnt lgkmcnt(0)
	s_setprio 1
	s_waitcnt lgkmcnt(0)
	v_mfma_f32_16x16x32_bf16 v[96:99], v[196:199], v[120:123], v[96:99]
	v_mfma_f32_16x16x32_bf16 v[16:19], v[204:207], v[120:123], v[16:19]
	v_mfma_f32_16x16x32_bf16 v[20:23], v[196:199], v[160:163], v[20:23]
	v_mfma_f32_16x16x32_bf16 v[24:27], v[204:207], v[160:163], v[24:27]
	v_mfma_f32_16x16x32_bf16 v[28:31], v[196:199], v[180:183], v[28:31]
	v_mfma_f32_16x16x32_bf16 v[32:35], v[204:207], v[180:183], v[32:35]
	v_mfma_f32_16x16x32_bf16 v[36:39], v[196:199], v[188:191], v[36:39]
	v_mfma_f32_16x16x32_bf16 v[40:43], v[204:207], v[188:191], v[40:43]
	v_mfma_f32_16x16x32_bf16 v[96:99], v[200:203], v[124:127], v[96:99]
	v_mfma_f32_16x16x32_bf16 v[16:19], v[208:211], v[124:127], v[16:19]
	v_mfma_f32_16x16x32_bf16 v[20:23], v[200:203], v[164:167], v[20:23]
	v_mfma_f32_16x16x32_bf16 v[24:27], v[208:211], v[164:167], v[24:27]
	v_mfma_f32_16x16x32_bf16 v[28:31], v[200:203], v[184:187], v[28:31]
	v_mfma_f32_16x16x32_bf16 v[32:35], v[208:211], v[184:187], v[32:35]
	v_mfma_f32_16x16x32_bf16 v[36:39], v[200:203], v[192:195], v[36:39]
	v_mfma_f32_16x16x32_bf16 v[40:43], v[208:211], v[192:195], v[40:43]
	s_setprio 0
	s_mov_b32 m0, s43
	v_lshl_add_u64 v[168:169], v[214:215], 0, s[12:13]
	s_barrier
	ds_read_b128 v[120:123], v174 offset:49152
	ds_read_b128 v[124:127], v174 offset:50176
	ds_read_b128 v[160:163], v174 offset:51200
	ds_read_b128 v[164:167], v174 offset:52224
	ds_read_b128 v[180:183], v174 offset:53248
	ds_read_b128 v[184:187], v174 offset:54272
	ds_read_b128 v[188:191], v174 offset:55296
	ds_read_b128 v[192:195], v174 offset:56320
	global_load_lds_dwordx4 v[168:169], off
	v_lshl_add_u64 v[168:169], v[216:217], 0, s[12:13]
	s_mov_b32 m0, s44
	s_nop 0
	global_load_lds_dwordx4 v[168:169], off
	s_barrier
	s_waitcnt lgkmcnt(0)
	s_setprio 1
	s_waitcnt lgkmcnt(0)
	v_mfma_f32_16x16x32_bf16 v[128:131], v[88:91], v[120:123], v[128:131]
	v_mfma_f32_16x16x32_bf16 v[132:135], v[112:115], v[120:123], v[132:135]
	v_mfma_f32_16x16x32_bf16 v[136:139], v[88:91], v[160:163], v[136:139]
	v_mfma_f32_16x16x32_bf16 v[140:143], v[112:115], v[160:163], v[140:143]
	v_mfma_f32_16x16x32_bf16 v[152:155], v[88:91], v[180:183], v[152:155]
	v_mfma_f32_16x16x32_bf16 v[156:159], v[112:115], v[180:183], v[156:159]
	v_mfma_f32_16x16x32_bf16 v[0:3], v[88:91], v[188:191], v[0:3]
	v_mfma_f32_16x16x32_bf16 v[4:7], v[112:115], v[188:191], v[4:7]
	v_mfma_f32_16x16x32_bf16 v[88:91], v[92:95], v[124:127], v[128:131]
	v_mfma_f32_16x16x32_bf16 v[112:115], v[116:119], v[124:127], v[132:135]
	v_mfma_f32_16x16x32_bf16 v[128:131], v[92:95], v[164:167], v[136:139]
	v_mfma_f32_16x16x32_bf16 v[132:135], v[116:119], v[164:167], v[140:143]
	v_mfma_f32_16x16x32_bf16 v[136:139], v[92:95], v[184:187], v[152:155]
	v_mfma_f32_16x16x32_bf16 v[140:143], v[116:119], v[184:187], v[156:159]
	v_mfma_f32_16x16x32_bf16 v[0:3], v[92:95], v[192:195], v[0:3]
	v_mfma_f32_16x16x32_bf16 v[4:7], v[116:119], v[192:195], v[4:7]
	s_setprio 0
	s_barrier
	s_add_u32 s56, s26, 0x10180
	s_addc_u32 s57, s27, 0
	s_add_i32 s54, s54, s37
	v_lshl_add_u64 v[92:93], s[56:57], 0, v[148:149]
	s_mov_b32 m0, s54
	s_add_i32 s52, s54, 0x2000
	global_load_lds_dwordx4 v[92:93], off
	v_lshl_add_u64 v[92:93], s[56:57], 0, v[144:145]
	s_mov_b32 m0, s52
	s_nop 0
	global_load_lds_dwordx4 v[92:93], off
	s_waitcnt vmcnt(6)
	s_barrier
	s_setprio 1
	v_mfma_f32_16x16x32_bf16 v[8:11], v[196:199], v[120:123], v[8:11]
	s_and_b64 s[28:29], s[28:29], exec
	s_cselect_b32 s27, s23, s27
	s_cselect_b32 s26, s22, s26
	v_mfma_f32_16x16x32_bf16 v[12:15], v[204:207], v[120:123], v[12:15]
	v_mfma_f32_16x16x32_bf16 v[44:47], v[196:199], v[160:163], v[44:47]
	v_mfma_f32_16x16x32_bf16 v[92:95], v[204:207], v[160:163], v[100:103]
	v_mfma_f32_16x16x32_bf16 v[100:103], v[196:199], v[180:183], v[104:107]
	v_mfma_f32_16x16x32_bf16 v[104:107], v[204:207], v[180:183], v[108:111]
	v_mfma_f32_16x16x32_bf16 v[80:83], v[196:199], v[188:191], v[80:83]
	v_mfma_f32_16x16x32_bf16 v[84:87], v[204:207], v[188:191], v[84:87]
	v_mfma_f32_16x16x32_bf16 v[8:11], v[200:203], v[124:127], v[8:11]
	v_mfma_f32_16x16x32_bf16 v[12:15], v[208:211], v[124:127], v[12:15]
	v_mfma_f32_16x16x32_bf16 v[44:47], v[200:203], v[164:167], v[44:47]
	v_mfma_f32_16x16x32_bf16 v[92:95], v[208:211], v[164:167], v[92:95]
	v_mfma_f32_16x16x32_bf16 v[100:103], v[200:203], v[184:187], v[100:103]
	v_mfma_f32_16x16x32_bf16 v[104:107], v[208:211], v[184:187], v[104:107]
	v_mfma_f32_16x16x32_bf16 v[80:83], v[200:203], v[192:195], v[80:83]
	v_mfma_f32_16x16x32_bf16 v[84:87], v[208:211], v[192:195], v[84:87]
	s_setprio 0
	s_barrier
	ds_read_b128 v[108:111], v173
	ds_read_b128 v[116:119], v173 offset:1024
	ds_read_b128 v[120:123], v173 offset:2048
	ds_read_b128 v[124:127], v173 offset:3072
	s_add_u32 s24, s24, 0x40180
	s_addc_u32 s25, s25, 0
	s_mov_b32 m0, s47
	v_lshl_add_u64 v[168:169], s[24:25], 0, v[150:151]
	ds_read_b128 v[152:155], v174
	ds_read_b128 v[156:159], v174 offset:1024
	ds_read_b128 v[160:163], v174 offset:2048
	ds_read_b128 v[164:167], v174 offset:3072
	ds_read_b128 v[180:183], v174 offset:4096
	ds_read_b128 v[184:187], v174 offset:5120
	ds_read_b128 v[188:191], v174 offset:6144
	ds_read_b128 v[192:195], v174 offset:7168
	global_load_lds_dwordx4 v[168:169], off
	v_lshl_add_u64 v[168:169], s[24:25], 0, v[146:147]
	s_mov_b32 m0, s48
	s_nop 0
	global_load_lds_dwordx4 v[168:169], off
	s_waitcnt lgkmcnt(8)
	s_barrier
	s_waitcnt lgkmcnt(0)
	s_setprio 1
	s_waitcnt lgkmcnt(0)
	v_mfma_f32_16x16x32_bf16 v[48:51], v[108:111], v[152:155], v[48:51]
	v_mfma_f32_16x16x32_bf16 v[52:55], v[120:123], v[152:155], v[52:55]
	v_mfma_f32_16x16x32_bf16 v[56:59], v[108:111], v[160:163], v[56:59]
	v_mfma_f32_16x16x32_bf16 v[60:63], v[120:123], v[160:163], v[60:63]
	v_mfma_f32_16x16x32_bf16 v[64:67], v[108:111], v[180:183], v[64:67]
	v_mfma_f32_16x16x32_bf16 v[68:71], v[120:123], v[180:183], v[68:71]
	v_mfma_f32_16x16x32_bf16 v[72:75], v[108:111], v[188:191], v[72:75]
	v_mfma_f32_16x16x32_bf16 v[76:79], v[120:123], v[188:191], v[76:79]
	v_mfma_f32_16x16x32_bf16 v[48:51], v[116:119], v[156:159], v[48:51]
	v_mfma_f32_16x16x32_bf16 v[52:55], v[124:127], v[156:159], v[52:55]
	v_mfma_f32_16x16x32_bf16 v[56:59], v[116:119], v[164:167], v[56:59]
	v_mfma_f32_16x16x32_bf16 v[60:63], v[124:127], v[164:167], v[60:63]
	v_mfma_f32_16x16x32_bf16 v[64:67], v[116:119], v[184:187], v[64:67]
	v_mfma_f32_16x16x32_bf16 v[68:71], v[124:127], v[184:187], v[68:71]
	v_mfma_f32_16x16x32_bf16 v[72:75], v[116:119], v[192:195], v[72:75]
	v_mfma_f32_16x16x32_bf16 v[76:79], v[124:127], v[192:195], v[76:79]
	s_setprio 0
	s_barrier
	s_mov_b32 m0, s49
	v_lshl_add_u64 v[168:169], s[26:27], 0, v[148:149]
	ds_read_b128 v[196:199], v175
	ds_read_b128 v[200:203], v175 offset:1024
	ds_read_b128 v[204:207], v175 offset:2048
	ds_read_b128 v[208:211], v175 offset:3072
	global_load_lds_dwordx4 v[168:169], off
	v_lshl_add_u64 v[230:231], s[26:27], 0, v[144:145]
	s_mov_b32 m0, s50
	s_nop 0
	global_load_lds_dwordx4 v[230:231], off
	s_barrier
	s_waitcnt lgkmcnt(0)
	s_setprio 1
	s_waitcnt lgkmcnt(0)
	v_mfma_f32_16x16x32_bf16 v[96:99], v[196:199], v[152:155], v[96:99]
	v_mfma_f32_16x16x32_bf16 v[16:19], v[204:207], v[152:155], v[16:19]
	v_mfma_f32_16x16x32_bf16 v[20:23], v[196:199], v[160:163], v[20:23]
	v_mfma_f32_16x16x32_bf16 v[24:27], v[204:207], v[160:163], v[24:27]
	v_mfma_f32_16x16x32_bf16 v[28:31], v[196:199], v[180:183], v[28:31]
	v_mfma_f32_16x16x32_bf16 v[32:35], v[204:207], v[180:183], v[32:35]
	v_mfma_f32_16x16x32_bf16 v[36:39], v[196:199], v[188:191], v[36:39]
	v_mfma_f32_16x16x32_bf16 v[40:43], v[204:207], v[188:191], v[40:43]
	v_mfma_f32_16x16x32_bf16 v[152:155], v[200:203], v[156:159], v[96:99]
	v_mfma_f32_16x16x32_bf16 v[16:19], v[208:211], v[156:159], v[16:19]
	v_mfma_f32_16x16x32_bf16 v[20:23], v[200:203], v[164:167], v[20:23]
	v_mfma_f32_16x16x32_bf16 v[24:27], v[208:211], v[164:167], v[24:27]
	v_mfma_f32_16x16x32_bf16 v[28:31], v[200:203], v[184:187], v[28:31]
	v_mfma_f32_16x16x32_bf16 v[32:35], v[208:211], v[184:187], v[32:35]
	v_mfma_f32_16x16x32_bf16 v[36:39], v[200:203], v[192:195], v[36:39]
	v_mfma_f32_16x16x32_bf16 v[40:43], v[208:211], v[192:195], v[40:43]
	s_setprio 0
	s_mov_b32 m0, s38
	v_lshl_add_u64 v[234:235], s[20:21], 0, v[150:151]
	s_barrier
	ds_read_b128 v[96:99], v174 offset:16384
	ds_read_b128 v[156:159], v174 offset:17408
	ds_read_b128 v[160:163], v174 offset:18432
	ds_read_b128 v[164:167], v174 offset:19456
	ds_read_b128 v[180:183], v174 offset:20480
	ds_read_b128 v[184:187], v174 offset:21504
	ds_read_b128 v[188:191], v174 offset:22528
	ds_read_b128 v[192:195], v174 offset:23552
	global_load_lds_dwordx4 v[234:235], off
	v_lshl_add_u64 v[236:237], s[20:21], 0, v[146:147]
	s_mov_b32 m0, s39
	s_nop 0
	global_load_lds_dwordx4 v[236:237], off
	s_barrier
	s_waitcnt lgkmcnt(0)
	s_setprio 1
	s_waitcnt lgkmcnt(0)
	v_mfma_f32_16x16x32_bf16 v[88:91], v[108:111], v[96:99], v[88:91]
	v_mfma_f32_16x16x32_bf16 v[112:115], v[120:123], v[96:99], v[112:115]
	v_mfma_f32_16x16x32_bf16 v[136:139], v[108:111], v[180:183], v[136:139]
	v_mfma_f32_16x16x32_bf16 v[140:143], v[120:123], v[180:183], v[140:143]
	v_mfma_f32_16x16x32_bf16 v[0:3], v[108:111], v[188:191], v[0:3]
	v_mfma_f32_16x16x32_bf16 v[4:7], v[120:123], v[188:191], v[4:7]
	v_mfma_f32_16x16x32_bf16 v[128:131], v[108:111], v[160:163], v[128:131]
	v_mfma_f32_16x16x32_bf16 v[132:135], v[120:123], v[160:163], v[132:135]
	v_mfma_f32_16x16x32_bf16 v[88:91], v[116:119], v[156:159], v[88:91]
	v_mfma_f32_16x16x32_bf16 v[112:115], v[124:127], v[156:159], v[112:115]
	v_mfma_f32_16x16x32_bf16 v[136:139], v[116:119], v[184:187], v[136:139]
	v_mfma_f32_16x16x32_bf16 v[140:143], v[124:127], v[184:187], v[140:143]
	v_mfma_f32_16x16x32_bf16 v[0:3], v[116:119], v[192:195], v[0:3]
	v_mfma_f32_16x16x32_bf16 v[4:7], v[124:127], v[192:195], v[4:7]
	v_mfma_f32_16x16x32_bf16 v[212:215], v[116:119], v[164:167], v[128:131]
	v_mfma_f32_16x16x32_bf16 v[216:219], v[124:127], v[164:167], v[132:135]
	s_setprio 0
	s_barrier
	s_add_u32 s24, s26, 0x10000
	s_addc_u32 s25, s27, 0
	s_mov_b32 m0, s19
	v_lshl_add_u64 v[108:109], s[24:25], 0, v[148:149]
	global_load_lds_dwordx4 v[108:109], off
	v_lshl_add_u64 v[108:109], s[24:25], 0, v[144:145]
	s_mov_b32 m0, s17
	s_nop 0
	global_load_lds_dwordx4 v[108:109], off
	s_waitcnt vmcnt(6)
	s_barrier
	s_setprio 1
	v_mfma_f32_16x16x32_bf16 v[8:11], v[196:199], v[96:99], v[8:11]
	v_mfma_f32_16x16x32_bf16 v[12:15], v[204:207], v[96:99], v[12:15]
	v_mfma_f32_16x16x32_bf16 v[44:47], v[196:199], v[160:163], v[44:47]
	v_mfma_f32_16x16x32_bf16 v[92:95], v[204:207], v[160:163], v[92:95]
	v_mfma_f32_16x16x32_bf16 v[96:99], v[196:199], v[180:183], v[100:103]
	v_mfma_f32_16x16x32_bf16 v[100:103], v[204:207], v[180:183], v[104:107]
	v_mfma_f32_16x16x32_bf16 v[80:83], v[196:199], v[188:191], v[80:83]
	v_mfma_f32_16x16x32_bf16 v[84:87], v[204:207], v[188:191], v[84:87]
	v_mfma_f32_16x16x32_bf16 v[124:127], v[200:203], v[156:159], v[8:11]
	v_mfma_f32_16x16x32_bf16 v[156:159], v[208:211], v[156:159], v[12:15]
	v_mfma_f32_16x16x32_bf16 v[160:163], v[200:203], v[164:167], v[44:47]
	v_mfma_f32_16x16x32_bf16 v[164:167], v[208:211], v[164:167], v[92:95]
	v_mfma_f32_16x16x32_bf16 v[180:183], v[200:203], v[184:187], v[96:99]
	v_mfma_f32_16x16x32_bf16 v[100:103], v[208:211], v[184:187], v[100:103]
	v_mfma_f32_16x16x32_bf16 v[184:187], v[200:203], v[192:195], v[80:83]
	v_mfma_f32_16x16x32_bf16 v[188:191], v[208:211], v[192:195], v[84:87]
	s_setprio 0
	s_barrier
	ds_read_b128 v[8:11], v221
	ds_read_b128 v[12:15], v221 offset:1024
	ds_read_b128 v[44:47], v221 offset:2048
	ds_read_b128 v[192:195], v221 offset:3072
	s_add_u32 s24, s20, 0x40000
	s_addc_u32 s25, s21, 0
	s_mov_b32 m0, s40
	v_lshl_add_u64 v[92:93], s[24:25], 0, v[150:151]
	ds_read_b128 v[80:83], v174 offset:32768
	ds_read_b128 v[84:87], v174 offset:33792
	ds_read_b128 v[104:107], v174 offset:34816
	ds_read_b128 v[196:199], v174 offset:35840
	ds_read_b128 v[108:111], v174 offset:36864
	ds_read_b128 v[200:203], v174 offset:37888
	ds_read_b128 v[204:207], v174 offset:38912
	ds_read_b128 v[208:211], v174 offset:39936
	global_load_lds_dwordx4 v[92:93], off
	v_lshl_add_u64 v[92:93], s[24:25], 0, v[146:147]
	s_mov_b32 m0, s41
	s_nop 0
	global_load_lds_dwordx4 v[92:93], off
	s_waitcnt lgkmcnt(8)
	s_barrier
;     __device__ __forceinline__ void epi(const f32x4 (&acc)[2][2][4][2], const Unit& u, int wr, int wc, int fr, int fq) const {
;     ...
;         const int row0 = u.pm * 256 + wr * 64 + fr, col0 = u.pn * 256 + wc * 32 + 8 * fq;
	s_waitcnt lgkmcnt(0)
	s_setprio 1
	s_waitcnt lgkmcnt(0)
	v_mfma_f32_16x16x32_bf16 v[52:55], v[44:47], v[80:83], v[52:55]
	v_mfma_f32_16x16x32_bf16 v[56:59], v[8:11], v[104:107], v[56:59]
	v_mfma_f32_16x16x32_bf16 v[60:63], v[44:47], v[104:107], v[60:63]
	v_mfma_f32_16x16x32_bf16 v[64:67], v[8:11], v[108:111], v[64:67]
	v_mfma_f32_16x16x32_bf16 v[68:71], v[44:47], v[108:111], v[68:71]
	v_mfma_f32_16x16x32_bf16 v[72:75], v[8:11], v[204:207], v[72:75]
	v_mfma_f32_16x16x32_bf16 v[222:225], v[44:47], v[204:207], v[76:79]
	v_mfma_f32_16x16x32_bf16 v[48:51], v[8:11], v[80:83], v[48:51]
	v_mfma_f32_16x16x32_bf16 v[128:131], v[192:195], v[84:87], v[52:55]
	v_mfma_f32_16x16x32_bf16 v[120:123], v[12:15], v[196:199], v[56:59]
	v_mfma_f32_16x16x32_bf16 v[116:119], v[192:195], v[196:199], v[60:63]
	v_mfma_f32_16x16x32_bf16 v[96:99], v[12:15], v[200:203], v[64:67]
	v_mfma_f32_16x16x32_bf16 v[92:95], v[192:195], v[200:203], v[68:71]
	v_mfma_f32_16x16x32_bf16 v[76:79], v[12:15], v[208:211], v[72:75]
	v_mfma_f32_16x16x32_bf16 v[72:75], v[192:195], v[208:211], v[222:225]
	v_mfma_f32_16x16x32_bf16 v[132:135], v[12:15], v[84:87], v[48:51]
	s_setprio 0
	s_barrier
	s_mov_b32 m0, s53
	v_lshl_add_u64 v[48:49], v[168:169], 0, s[6:7]
	ds_read_b128 v[56:59], v226
	ds_read_b128 v[222:225], v226 offset:1024
	ds_read_b128 v[60:63], v226 offset:2048
	ds_read_b128 v[226:229], v226 offset:3072
	global_load_lds_dwordx4 v[48:49], off
	v_lshl_add_u64 v[48:49], v[230:231], 0, s[6:7]
	s_mov_b32 m0, s51
	s_nop 0
	global_load_lds_dwordx4 v[48:49], off
	s_barrier
	s_waitcnt lgkmcnt(0)
	s_setprio 1
	s_waitcnt lgkmcnt(0)
	v_mfma_f32_16x16x32_bf16 v[48:51], v[56:59], v[80:83], v[152:155]
	v_mfma_f32_16x16x32_bf16 v[16:19], v[60:63], v[80:83], v[16:19]
	v_mfma_f32_16x16x32_bf16 v[20:23], v[56:59], v[104:107], v[20:23]
	v_mfma_f32_16x16x32_bf16 v[24:27], v[60:63], v[104:107], v[24:27]
	v_mfma_f32_16x16x32_bf16 v[28:31], v[56:59], v[108:111], v[28:31]
	v_mfma_f32_16x16x32_bf16 v[32:35], v[60:63], v[108:111], v[32:35]
	v_mfma_f32_16x16x32_bf16 v[36:39], v[56:59], v[204:207], v[36:39]
	v_mfma_f32_16x16x32_bf16 v[40:43], v[60:63], v[204:207], v[40:43]
	v_mfma_f32_16x16x32_bf16 v[204:207], v[222:225], v[84:87], v[48:51]
	v_mfma_f32_16x16x32_bf16 v[230:233], v[226:229], v[84:87], v[16:19]
	v_mfma_f32_16x16x32_bf16 v[108:111], v[222:225], v[196:199], v[20:23]
	v_mfma_f32_16x16x32_bf16 v[104:107], v[226:229], v[196:199], v[24:27]
	v_mfma_f32_16x16x32_bf16 v[84:87], v[222:225], v[200:203], v[28:31]
	v_mfma_f32_16x16x32_bf16 v[80:83], v[226:229], v[200:203], v[32:35]
	v_mfma_f32_16x16x32_bf16 v[68:71], v[222:225], v[208:211], v[36:39]
	v_mfma_f32_16x16x32_bf16 v[64:67], v[226:229], v[208:211], v[40:43]
	s_setprio 0
	s_mov_b32 m0, s43
	v_lshl_add_u64 v[24:25], v[234:235], 0, s[6:7]
	s_barrier
	ds_read_b128 v[16:19], v174 offset:49152
	ds_read_b128 v[20:23], v174 offset:50176
	ds_read_b128 v[32:35], v174 offset:51200
	ds_read_b128 v[152:155], v174 offset:52224
	ds_read_b128 v[36:39], v174 offset:53248
	ds_read_b128 v[196:199], v174 offset:54272
	ds_read_b128 v[200:203], v174 offset:55296
	ds_read_b128 v[208:211], v174 offset:56320
	global_load_lds_dwordx4 v[24:25], off
	v_lshl_add_u64 v[24:25], v[236:237], 0, s[6:7]
	s_mov_b32 m0, s44
	s_nop 0
	global_load_lds_dwordx4 v[24:25], off
	s_barrier
	s_waitcnt lgkmcnt(0)
	s_setprio 1
	s_waitcnt lgkmcnt(0)
	v_mfma_f32_16x16x32_bf16 v[24:27], v[8:11], v[16:19], v[88:91]
	v_mfma_f32_16x16x32_bf16 v[28:31], v[44:47], v[16:19], v[112:115]
	v_mfma_f32_16x16x32_bf16 v[40:43], v[8:11], v[32:35], v[212:215]
	v_mfma_f32_16x16x32_bf16 v[88:91], v[44:47], v[32:35], v[216:219]
	v_mfma_f32_16x16x32_bf16 v[112:115], v[8:11], v[36:39], v[136:139]
	v_mfma_f32_16x16x32_bf16 v[136:139], v[44:47], v[36:39], v[140:143]
	v_mfma_f32_16x16x32_bf16 v[0:3], v[8:11], v[200:203], v[0:3]
	v_mfma_f32_16x16x32_bf16 v[4:7], v[44:47], v[200:203], v[4:7]
	v_mfma_f32_16x16x32_bf16 v[52:55], v[12:15], v[20:23], v[24:27]
	v_mfma_f32_16x16x32_bf16 v[48:51], v[192:195], v[20:23], v[28:31]
	v_mfma_f32_16x16x32_bf16 v[44:47], v[12:15], v[152:155], v[40:43]
	v_mfma_f32_16x16x32_bf16 v[40:43], v[192:195], v[152:155], v[88:91]
	v_mfma_f32_16x16x32_bf16 v[28:31], v[12:15], v[196:199], v[112:115]
	v_mfma_f32_16x16x32_bf16 v[24:27], v[192:195], v[196:199], v[136:139]
	v_mfma_f32_16x16x32_bf16 v[12:15], v[12:15], v[208:211], v[0:3]
	v_mfma_f32_16x16x32_bf16 v[8:11], v[192:195], v[208:211], v[4:7]
	s_setprio 0
	s_barrier
	s_add_u32 s24, s26, 0x10080
	s_addc_u32 s25, s27, 0
	s_mov_b32 m0, s54
	v_lshl_add_u64 v[0:1], s[24:25], 0, v[148:149]
	global_load_lds_dwordx4 v[0:1], off
	v_lshl_add_u64 v[0:1], s[24:25], 0, v[144:145]
	s_mov_b32 m0, s52
	s_nop 0
	global_load_lds_dwordx4 v[0:1], off
	s_waitcnt vmcnt(6)
	s_barrier
	s_setprio 1
	v_mfma_f32_16x16x32_bf16 v[0:3], v[56:59], v[16:19], v[124:127]
	v_mfma_f32_16x16x32_bf16 v[4:7], v[60:63], v[16:19], v[156:159]
	v_mfma_f32_16x16x32_bf16 v[16:19], v[56:59], v[32:35], v[160:163]
	v_mfma_f32_16x16x32_bf16 v[32:35], v[60:63], v[32:35], v[164:167]
	v_mfma_f32_16x16x32_bf16 v[88:91], v[56:59], v[36:39], v[180:183]
	v_mfma_f32_16x16x32_bf16 v[100:103], v[60:63], v[36:39], v[100:103]
	v_mfma_f32_16x16x32_bf16 v[112:115], v[56:59], v[200:203], v[184:187]
	v_mfma_f32_16x16x32_bf16 v[124:127], v[60:63], v[200:203], v[188:191]
	v_mfma_f32_16x16x32_bf16 v[60:63], v[222:225], v[20:23], v[0:3]
	v_mfma_f32_16x16x32_bf16 v[56:59], v[226:229], v[20:23], v[4:7]
	v_mfma_f32_16x16x32_bf16 v[36:39], v[222:225], v[152:155], v[16:19]
	v_mfma_f32_16x16x32_bf16 v[32:35], v[226:229], v[152:155], v[32:35]
	v_mfma_f32_16x16x32_bf16 v[20:23], v[222:225], v[196:199], v[88:91]
	v_mfma_f32_16x16x32_bf16 v[16:19], v[226:229], v[196:199], v[100:103]
	v_mfma_f32_16x16x32_bf16 v[4:7], v[222:225], v[208:211], v[112:115]
	v_mfma_f32_16x16x32_bf16 v[0:3], v[226:229], v[208:211], v[124:127]
	s_setprio 0
	v_lshl_or_b32 v152, s45, 8, v172
	v_lshl_add_u32 v156, s8, 8, v170
	v_ashrrev_i32_e32 v153, 31, v152
	v_lshlrev_b64 v[190:191], 1, v[152:153]
	v_ashrrev_i32_e32 v157, 31, v156
	v_lshl_add_u64 v[154:155], s[0:1], 0, v[190:191]
	v_lshlrev_b64 v[192:193], 11, v[156:157]
	v_lshl_add_u64 v[88:89], v[154:155], 0, v[192:193]
	s_barrier
; __device__ __forceinline__ unsigned pk2(float lo, float hi) { unsigned r; asm volatile("v_cvt_pk_bf16_f32 %0, %1, %2" : "=v"(r) : "v"(lo), "v"(hi)); return r; }
; __device__ __forceinline__ unsigned pk2(float lo, float hi) { return f2bf(lo) | (f2bf(hi) << 16); }
;     __device__ __forceinline__ void epi(const f32x4 (&acc)[2][2][4][2], const Unit& u, int wr, int wc, int fr, int fq) const {
;     ...
;         const int row0 = u.pm * 256 + wr * 64 + fr, col0 = u.pn * 256 + wc * 32 + 8 * fq;
; #pragma unroll
;         for (int ai = 0; ai < 2; ++ai) {
;             u32x4 xo[4][2];
; #pragma unroll
;             for (int m = 0; m < 4; ++m)
; #pragma unroll
;                 for (int bj = 0; bj < 2; ++bj) xo[m][bj] = *(const u32x4*)(xb + (size_t)(row0 + ai * 128 + m * 16) * D + col0 + bj * 128);
; #pragma unroll
;             for (int m = 0; m < 4; ++m) {
;                 const int row = row0 + ai * 128 + m * 16; const size_t off = (size_t)row * D + col0; float ss = 0.f;
; #pragma unroll
;                 for (int bj = 0; bj < 2; ++bj) {
;                     const u32x4 o = xo[m][bj]; const f32x4 a0v = acc[ai][bj][m][0], a1v = acc[ai][bj][m][1];
;                     const float v0 = bf_lo(o.x) + coef * a0v[0], v1 = bf_hi(o.x) + coef * a0v[1], v2 = bf_lo(o.y) + coef * a0v[2], v3 = bf_hi(o.y) + coef * a0v[3];
;                     const float v4 = bf_lo(o.z) + coef * a1v[0], v5 = bf_hi(o.z) + coef * a1v[1], v6 = bf_lo(o.w) + coef * a1v[2], v7 = bf_hi(o.w) + coef * a1v[3];
;                     u32x4 w; w.x = pk2(v0, v1); w.y = pk2(v2, v3); w.z = pk2(v4, v5); w.w = pk2(v6, v7);
;                     *(u32x4*)(xb + off + bj * 128) = w;
;                     ss += ((v0 * v0 + v1 * v1) + (v2 * v2 + v3 * v3)) + ((v4 * v4 + v5 * v5) + (v6 * v6 + v7 * v7));
;                 }
;                 ss += __shfl_xor(ss, 16); ss += __shfl_xor(ss, 32);
;                 if (fq == 0) rowss[(size_t)row * 32 + u.pn * 4 + wc] = ss;
;             }
	v_mov_b32_e32 v214, 0x40000
	v_mov_b32_e32 v215, 0
	v_lshl_add_u64 v[212:213], v[88:89], 0, v[214:215]
	v_mov_b32_e32 v214, 0x8000
	global_load_dwordx4 v[182:185], v[88:89], off
	global_load_dwordx4 v[186:189], v[88:89], off offset:256
	v_or_b32_e32 v166, 16, v156
	v_or_b32_e32 v162, 32, v156
	v_or_b32_e32 v158, 48, v156
	v_ashrrev_i32_e32 v167, 31, v166
	v_ashrrev_i32_e32 v163, 31, v162
	v_ashrrev_i32_e32 v159, 31, v158
	v_lshlrev_b64 v[168:169], 11, v[166:167]
	v_lshlrev_b64 v[164:165], 11, v[162:163]
	v_lshlrev_b64 v[160:161], 11, v[158:159]
	v_lshl_add_u64 v[88:89], v[154:155], 0, v[168:169]
	v_lshl_add_u64 v[90:91], v[154:155], 0, v[164:165]
	v_lshl_add_u64 v[180:181], v[154:155], 0, v[160:161]
	global_load_dwordx4 v[140:143], v[88:89], off
	global_load_dwordx4 v[136:139], v[88:89], off offset:256
	global_load_dwordx4 v[124:127], v[90:91], off
	global_load_dwordx4 v[112:115], v[90:91], off offset:256
	global_load_dwordx4 v[100:103], v[180:181], off
	s_nop 0
	global_load_dwordx4 v[88:91], v[180:181], off offset:256
	global_load_dwordx4 v[216:219], v[212:213], off
	global_load_dwordx4 v[222:225], v[212:213], off offset:256
	v_lshl_add_u64 v[212:213], v[212:213], 0, v[214:215]
	global_load_dwordx4 v[226:229], v[212:213], off
	global_load_dwordx4 v[234:237], v[212:213], off offset:256
	v_lshl_add_u64 v[212:213], v[212:213], 0, v[214:215]
	global_load_dwordx4 v[238:241], v[212:213], off
	global_load_dwordx4 v[242:245], v[212:213], off offset:256
	v_lshl_add_u64 v[212:213], v[212:213], 0, v[214:215]
	global_load_dwordx4 v[246:249], v[212:213], off
	global_load_dwordx4 v[250:253], v[212:213], off offset:256
	v_lshl_add_u64 v[192:193], s[0:1], 0, v[192:193]
	v_lshl_add_u64 v[190:191], v[192:193], 0, v[190:191]
	v_cmp_lt_i32_e32 vcc, v177, v178
	s_waitcnt vmcnt(8)
	v_lshlrev_b32_e32 v181, 16, v182
	v_and_b32_e32 v182, 0xffff0000, v182
	v_lshlrev_b32_e32 v192, 16, v183
	v_and_b32_e32 v183, 0xffff0000, v183
	v_lshlrev_b32_e32 v193, 16, v184
	v_and_b32_e32 v184, 0xffff0000, v184
	v_lshlrev_b32_e32 v194, 16, v185
	v_and_b32_e32 v185, 0xffff0000, v185
	v_lshlrev_b32_e32 v195, 16, v186
	v_and_b32_e32 v186, 0xffff0000, v186
	v_lshlrev_b32_e32 v196, 16, v187
	v_and_b32_e32 v187, 0xffff0000, v187
	v_lshlrev_b32_e32 v197, 16, v188
	v_and_b32_e32 v188, 0xffff0000, v188
	v_lshlrev_b32_e32 v198, 16, v189
	v_and_b32_e32 v189, 0xffff0000, v189
	v_add_f32_e32 v133, v133, v182
	v_add_f32_e32 v135, v135, v183
	v_add_f32_e32 v182, v129, v184
	v_add_f32_e32 v131, v131, v185
	v_add_f32_e32 v185, v205, v186
	v_add_f32_e32 v187, v207, v187
	v_add_f32_e32 v188, v231, v188
	v_add_f32_e32 v189, v233, v189
	v_add_f32_e32 v132, v132, v181
	v_add_f32_e32 v134, v134, v192
	v_add_f32_e32 v181, v128, v193
	v_add_f32_e32 v183, v130, v194
	v_add_f32_e32 v184, v204, v195
	v_add_f32_e32 v186, v206, v196
	v_add_f32_e32 v192, v230, v197
	v_add_f32_e32 v193, v232, v198
	v_cvt_pk_bf16_f32 v128, v132, v133
	v_cvt_pk_bf16_f32 v129, v134, v135
	v_mul_f32_e32 v130, v133, v133
	v_mul_f32_e32 v133, v135, v135
	v_mul_f32_e32 v135, v182, v182
	v_mul_f32_e32 v194, v131, v131
	v_mul_f32_e32 v195, v185, v185
	v_mul_f32_e32 v196, v187, v187
	v_mul_f32_e32 v197, v188, v188
	v_mul_f32_e32 v198, v189, v189
	v_fmac_f32_e32 v130, v132, v132
	v_fmac_f32_e32 v133, v134, v134
	v_fmac_f32_e32 v135, v181, v181
	v_fmac_f32_e32 v194, v183, v183
	v_fmac_f32_e32 v195, v184, v184
	v_fmac_f32_e32 v196, v186, v186
	v_fmac_f32_e32 v197, v192, v192
	v_fmac_f32_e32 v198, v193, v193
	v_add_f32_e32 v130, v130, v133
	v_add_f32_e32 v132, v135, v194
	v_add_f32_e32 v133, v195, v196
	v_add_f32_e32 v134, v197, v198
	v_cndmask_b32_e32 v180, v176, v177, vcc
	v_add_f32_e32 v130, v130, v132
	v_add_f32_e32 v132, v133, v134
	v_lshlrev_b32_e32 v180, 2, v180
	v_add_f32_e32 v133, v130, v132
	ds_bpermute_b32 v134, v180, v133
	v_cmp_lt_i32_e32 vcc, v179, v178
	v_cvt_pk_bf16_f32 v130, v181, v182
	v_cvt_pk_bf16_f32 v131, v183, v131
	global_store_dwordx4 v[190:191], v[128:131], off
	v_cvt_pk_bf16_f32 v132, v184, v185
	s_nop 1
	v_cndmask_b32_e32 v128, v176, v179, vcc
	s_waitcnt lgkmcnt(0)
	v_add_f32_e32 v129, v133, v134
	v_lshlrev_b32_e32 v128, 2, v128
	ds_bpermute_b32 v130, v128, v129
	v_cvt_pk_bf16_f32 v133, v186, v187
	v_cvt_pk_bf16_f32 v134, v192, v188
	v_cvt_pk_bf16_f32 v135, v193, v189
	global_store_dwordx4 v[190:191], v[132:135], off offset:256
	s_and_saveexec_b64 s[24:25], s[4:5]
	s_cbranch_execz .LBB0_1672
	s_waitcnt lgkmcnt(0)
	v_add_f32_e32 v129, v129, v130
	s_lshl_b32 s26, s45, 2
	v_lshlrev_b64 v[130:131], 7, v[156:157]
	s_ashr_i32 s27, s26, 31
	v_lshl_add_u64 v[130:131], s[2:3], 0, v[130:131]
	v_lshl_add_u64 v[130:131], s[26:27], 2, v[130:131]
	s_lshl_b32 s8, s42, 2
	v_lshl_add_u64 v[130:131], v[130:131], 0, s[8:9]
	global_store_dword v[130:131], v129, off

; __device__ __forceinline__ unsigned pk2(float lo, float hi) { unsigned r; asm volatile("v_cvt_pk_bf16_f32 %0, %1, %2" : "=v"(r) : "v"(lo), "v"(hi)); return r; }
; __device__ __forceinline__ unsigned pk2(float lo, float hi) { return f2bf(lo) | (f2bf(hi) << 16); }
;     __device__ __forceinline__ void epi(const f32x4 (&acc)[2][2][4][2], const Unit& u, int wr, int wc, int fr, int fq) const {
;     ...
;         for (int ai = 0; ai < 2; ++ai) {
;             u32x4 xo[4][2];
; #pragma unroll
;             for (int m = 0; m < 4; ++m)
; #pragma unroll
;                 for (int bj = 0; bj < 2; ++bj) xo[m][bj] = *(const u32x4*)(xb + (size_t)(row0 + ai * 128 + m * 16) * D + col0 + bj * 128);
; #pragma unroll
;             for (int m = 0; m < 4; ++m) {
;                 const int row = row0 + ai * 128 + m * 16; const size_t off = (size_t)row * D + col0; float ss = 0.f;
; #pragma unroll
;                 for (int bj = 0; bj < 2; ++bj) {
;                     const u32x4 o = xo[m][bj]; const f32x4 a0v = acc[ai][bj][m][0], a1v = acc[ai][bj][m][1];
;                     const float v0 = bf_lo(o.x) + coef * a0v[0], v1 = bf_hi(o.x) + coef * a0v[1], v2 = bf_lo(o.y) + coef * a0v[2], v3 = bf_hi(o.y) + coef * a0v[3];
;                     const float v4 = bf_lo(o.z) + coef * a1v[0], v5 = bf_hi(o.z) + coef * a1v[1], v6 = bf_lo(o.w) + coef * a1v[2], v7 = bf_hi(o.w) + coef * a1v[3];
;                     u32x4 w; w.x = pk2(v0, v1); w.y = pk2(v2, v3); w.z = pk2(v4, v5); w.w = pk2(v6, v7);
;                     *(u32x4*)(xb + off + bj * 128) = w;
;                     ss += ((v0 * v0 + v1 * v1) + (v2 * v2 + v3 * v3)) + ((v4 * v4 + v5 * v5) + (v6 * v6 + v7 * v7));
;                 }
;                 ss += __shfl_xor(ss, 16); ss += __shfl_xor(ss, 32);
;                 if (fq == 0) rowss[(size_t)row * 32 + u.pn * 4 + wc] = ss;
.LBB0_1678:
	s_or_b64 exec, exec, s[24:25]
	v_add_u32_e32 v100, 0x80, v156
	v_ashrrev_i32_e32 v101, 31, v100
	v_lshlrev_b64 v[110:111], 11, v[100:101]
	s_waitcnt lgkmcnt(0)
	v_lshl_add_u64 v[64:65], v[154:155], 0, v[110:111]
	s_waitcnt vmcnt(8)
	v_mov_b64_e32 v[102:103], v[216:217]
	v_mov_b64_e32 v[104:105], v[218:219]
	v_mov_b64_e32 v[106:107], v[222:223]
	v_mov_b64_e32 v[108:109], v[224:225]
	v_add_u32_e32 v96, 0x90, v156
	v_add_u32_e32 v92, 0xa0, v156
	v_add_u32_e32 v88, 0xb0, v156
	v_ashrrev_i32_e32 v97, 31, v96
	v_ashrrev_i32_e32 v93, 31, v92
	v_ashrrev_i32_e32 v89, 31, v88
	v_lshlrev_b64 v[98:99], 11, v[96:97]
	v_lshlrev_b64 v[94:95], 11, v[92:93]
	v_lshlrev_b64 v[90:91], 11, v[88:89]
	v_lshl_add_u64 v[64:65], v[154:155], 0, v[98:99]
	v_lshl_add_u64 v[66:67], v[154:155], 0, v[94:95]
	v_lshl_add_u64 v[112:113], v[154:155], 0, v[90:91]
	v_mov_b64_e32 v[84:85], v[226:227]
	v_mov_b64_e32 v[86:87], v[228:229]
	v_mov_b64_e32 v[80:81], v[234:235]
	v_mov_b64_e32 v[82:83], v[236:237]
	v_mov_b64_e32 v[76:77], v[238:239]
	v_mov_b64_e32 v[78:79], v[240:241]
	v_mov_b64_e32 v[72:73], v[242:243]
	v_mov_b64_e32 v[74:75], v[244:245]
	v_mov_b64_e32 v[68:69], v[246:247]
	v_mov_b64_e32 v[70:71], v[248:249]
	s_nop 0
	v_mov_b64_e32 v[64:65], v[250:251]
	v_mov_b64_e32 v[66:67], v[252:253]
	v_lshlrev_b32_e32 v112, 16, v102
	v_and_b32_e32 v102, 0xffff0000, v102
	v_lshlrev_b32_e32 v113, 16, v103
	v_and_b32_e32 v103, 0xffff0000, v103
	v_lshlrev_b32_e32 v114, 16, v104
	v_and_b32_e32 v104, 0xffff0000, v104
	v_lshlrev_b32_e32 v115, 16, v105
	v_and_b32_e32 v105, 0xffff0000, v105
	v_lshlrev_b32_e32 v116, 16, v106
	v_and_b32_e32 v106, 0xffff0000, v106
	v_lshlrev_b32_e32 v117, 16, v107
	v_and_b32_e32 v107, 0xffff0000, v107
	v_lshlrev_b32_e32 v118, 16, v108
	v_and_b32_e32 v108, 0xffff0000, v108
	v_lshlrev_b32_e32 v119, 16, v109
	v_and_b32_e32 v109, 0xffff0000, v109
	v_add_f32_e32 v53, v53, v102
	v_add_f32_e32 v55, v55, v103
	v_add_f32_e32 v103, v49, v104
	v_add_f32_e32 v105, v51, v105
	v_add_f32_e32 v61, v61, v106
	v_add_f32_e32 v63, v63, v107
	v_add_f32_e32 v57, v57, v108
	v_add_f32_e32 v59, v59, v109
	v_add_f32_e32 v52, v52, v112
	v_add_f32_e32 v54, v54, v113
	v_add_f32_e32 v102, v48, v114
	v_add_f32_e32 v104, v50, v115
	v_add_f32_e32 v60, v60, v116
	v_add_f32_e32 v62, v62, v117
	v_add_f32_e32 v56, v56, v118
	v_add_f32_e32 v58, v58, v119
	v_cvt_pk_bf16_f32 v48, v52, v53
	v_cvt_pk_bf16_f32 v49, v54, v55
	v_cvt_pk_bf16_f32 v50, v102, v103
	v_cvt_pk_bf16_f32 v51, v104, v105
	v_mul_f32_e32 v53, v53, v53
	v_mul_f32_e32 v55, v55, v55
	v_mul_f32_e32 v103, v103, v103
	v_mul_f32_e32 v105, v105, v105
	v_mul_f32_e32 v106, v61, v61
	v_mul_f32_e32 v107, v63, v63
	v_mul_f32_e32 v108, v57, v57
	v_mul_f32_e32 v109, v59, v59
	v_fmac_f32_e32 v53, v52, v52
	v_fmac_f32_e32 v55, v54, v54
	v_fmac_f32_e32 v103, v102, v102
	v_fmac_f32_e32 v105, v104, v104
	v_fmac_f32_e32 v106, v60, v60
	v_fmac_f32_e32 v107, v62, v62
	v_fmac_f32_e32 v108, v56, v56
	v_fmac_f32_e32 v109, v58, v58
	v_add_f32_e32 v52, v53, v55
	v_add_f32_e32 v53, v103, v105
	v_add_f32_e32 v54, v106, v107
	v_add_f32_e32 v55, v108, v109
	v_add_f32_e32 v52, v52, v53
	v_add_f32_e32 v53, v54, v55
	v_add_f32_e32 v102, v52, v53
	ds_bpermute_b32 v103, v180, v102
	v_lshl_add_u64 v[52:53], s[0:1], 0, v[110:111]
	v_lshl_add_u64 v[54:55], v[152:153], 1, v[52:53]
	global_store_dwordx4 v[54:55], v[48:51], off
	s_waitcnt lgkmcnt(0)
	s_nop 0
	v_add_f32_e32 v48, v102, v103
	ds_bpermute_b32 v49, v128, v48
	v_cvt_pk_bf16_f32 v50, v60, v61
	v_cvt_pk_bf16_f32 v51, v62, v63
	v_cvt_pk_bf16_f32 v52, v56, v57
	v_cvt_pk_bf16_f32 v53, v58, v59
	global_store_dwordx4 v[54:55], v[50:53], off offset:256
	s_and_saveexec_b64 s[24:25], s[4:5]
	s_cbranch_execz .LBB0_1680
	s_waitcnt lgkmcnt(0)
	v_add_f32_e32 v50, v48, v49
	s_lshl_b32 s26, s45, 2
	v_lshlrev_b64 v[48:49], 7, v[100:101]
	s_ashr_i32 s27, s26, 31
	v_lshl_add_u64 v[48:49], s[2:3], 0, v[48:49]
	v_lshl_add_u64 v[48:49], s[26:27], 2, v[48:49]
	s_lshl_b32 s8, s42, 2
	v_lshl_add_u64 v[48:49], v[48:49], 0, s[8:9]
	global_store_dword v[48:49], v50, off
.LBB0_1680:
	s_or_b64 exec, exec, s[24:25]
	v_lshlrev_b32_e32 v48, 16, v84
	v_add_f32_e32 v44, v44, v48
	v_and_b32_e32 v48, 0xffff0000, v84
	v_add_f32_e32 v45, v45, v48
	v_lshlrev_b32_e32 v48, 16, v85
	v_add_f32_e32 v46, v46, v48
	v_and_b32_e32 v48, 0xffff0000, v85
	v_add_f32_e32 v47, v47, v48
	v_lshlrev_b32_e32 v48, 16, v86
	v_add_f32_e32 v48, v40, v48
	v_and_b32_e32 v40, 0xffff0000, v86
	s_waitcnt lgkmcnt(0)
	v_add_f32_e32 v49, v41, v40
	v_lshlrev_b32_e32 v40, 16, v87
	v_add_f32_e32 v50, v42, v40
	v_and_b32_e32 v40, 0xffff0000, v87
	v_add_f32_e32 v51, v43, v40
	v_cvt_pk_bf16_f32 v40, v44, v45
	v_mul_f32_e32 v45, v45, v45
	v_fmac_f32_e32 v45, v44, v44
	v_mul_f32_e32 v44, v47, v47
	v_fmac_f32_e32 v44, v46, v46
	v_cvt_pk_bf16_f32 v41, v46, v47
	v_add_f32_e32 v44, v45, v44
	v_mul_f32_e32 v45, v49, v49
	v_mul_f32_e32 v46, v51, v51
	v_fmac_f32_e32 v45, v48, v48
	v_fmac_f32_e32 v46, v50, v50
	v_add_f32_e32 v45, v45, v46
	v_add_f32_e32 v44, v44, v45
	v_lshlrev_b32_e32 v45, 16, v80
	v_add_f32_e32 v36, v36, v45
	v_and_b32_e32 v45, 0xffff0000, v80
	v_add_f32_e32 v37, v37, v45
	v_lshlrev_b32_e32 v45, 16, v81
	v_add_f32_e32 v45, v38, v45
	v_and_b32_e32 v38, 0xffff0000, v81
	v_add_f32_e32 v46, v39, v38
	v_lshlrev_b32_e32 v38, 16, v82
	v_add_f32_e32 v47, v32, v38
	v_and_b32_e32 v32, 0xffff0000, v82
	v_cvt_pk_bf16_f32 v42, v48, v49
	v_add_f32_e32 v48, v33, v32
	v_lshlrev_b32_e32 v32, 16, v83
	v_add_f32_e32 v49, v34, v32
	v_and_b32_e32 v32, 0xffff0000, v83
	v_cvt_pk_bf16_f32 v43, v50, v51
	v_add_f32_e32 v50, v35, v32
	v_mul_f32_e32 v32, v37, v37
	v_mul_f32_e32 v33, v46, v46
	v_fmac_f32_e32 v32, v36, v36
	v_fmac_f32_e32 v33, v45, v45
	v_add_f32_e32 v32, v32, v33
	v_mul_f32_e32 v33, v48, v48
	v_mul_f32_e32 v34, v50, v50
	v_fmac_f32_e32 v33, v47, v47
	v_fmac_f32_e32 v34, v49, v49
	v_add_f32_e32 v33, v33, v34
	v_add_f32_e32 v32, v32, v33
	v_add_f32_e32 v35, v44, v32
	ds_bpermute_b32 v44, v180, v35
	v_lshl_add_u64 v[32:33], s[0:1], 0, v[98:99]
	v_lshl_add_u64 v[38:39], v[152:153], 1, v[32:33]
	global_store_dwordx4 v[38:39], v[40:43], off
	v_cvt_pk_bf16_f32 v34, v36, v37
	s_waitcnt lgkmcnt(0)
	v_add_f32_e32 v32, v35, v44
	ds_bpermute_b32 v33, v128, v32
	v_cvt_pk_bf16_f32 v35, v45, v46
	v_cvt_pk_bf16_f32 v36, v47, v48
	v_cvt_pk_bf16_f32 v37, v49, v50
	global_store_dwordx4 v[38:39], v[34:37], off offset:256
	s_and_saveexec_b64 s[24:25], s[4:5]
	s_cbranch_execz .LBB0_1682
	s_waitcnt lgkmcnt(0)
	v_add_f32_e32 v34, v32, v33
	s_lshl_b32 s26, s45, 2
	v_lshlrev_b64 v[32:33], 7, v[96:97]
	s_ashr_i32 s27, s26, 31
	v_lshl_add_u64 v[32:33], s[2:3], 0, v[32:33]
	v_lshl_add_u64 v[32:33], s[26:27], 2, v[32:33]
	s_lshl_b32 s8, s42, 2
	v_lshl_add_u64 v[32:33], v[32:33], 0, s[8:9]
	global_store_dword v[32:33], v34, off
; __device__ __forceinline__ unsigned pk2(float lo, float hi) { unsigned r; asm volatile("v_cvt_pk_bf16_f32 %0, %1, %2" : "=v"(r) : "v"(lo), "v"(hi)); return r; }
; __device__ __forceinline__ unsigned pk2(float lo, float hi) { return f2bf(lo) | (f2bf(hi) << 16); }
;     __device__ __forceinline__ void epi(const f32x4 (&acc)[2][2][4][2], const Unit& u, int wr, int wc, int fr, int fq) const {
;     ...
;             for (int m = 0; m < 4; ++m) {
;                 const int row = row0 + ai * 128 + m * 16; const size_t off = (size_t)row * D + col0; float ss = 0.f;
; #pragma unroll
;                 for (int bj = 0; bj < 2; ++bj) {
;                     const u32x4 o = xo[m][bj]; const f32x4 a0v = acc[ai][bj][m][0], a1v = acc[ai][bj][m][1];
;                     const float v0 = bf_lo(o.x) + coef * a0v[0], v1 = bf_hi(o.x) + coef * a0v[1], v2 = bf_lo(o.y) + coef * a0v[2], v3 = bf_hi(o.y) + coef * a0v[3];
;                     const float v4 = bf_lo(o.z) + coef * a1v[0], v5 = bf_hi(o.z) + coef * a1v[1], v6 = bf_lo(o.w) + coef * a1v[2], v7 = bf_hi(o.w) + coef * a1v[3];
;                     u32x4 w; w.x = pk2(v0, v1); w.y = pk2(v2, v3); w.z = pk2(v4, v5); w.w = pk2(v6, v7);
;                     *(u32x4*)(xb + off + bj * 128) = w;
;                     ss += ((v0 * v0 + v1 * v1) + (v2 * v2 + v3 * v3)) + ((v4 * v4 + v5 * v5) + (v6 * v6 + v7 * v7));
;                 }
;                 ss += __shfl_xor(ss, 16); ss += __shfl_xor(ss, 32);
;                 if (fq == 0) rowss[(size_t)row * 32 + u.pn * 4 + wc] = ss;
;             }
.LBB0_1682:
	s_or_b64 exec, exec, s[24:25]
	v_lshlrev_b32_e32 v32, 16, v76
	v_add_f32_e32 v28, v28, v32
	v_and_b32_e32 v32, 0xffff0000, v76
	v_add_f32_e32 v29, v29, v32
	v_lshlrev_b32_e32 v32, 16, v77
	v_add_f32_e32 v30, v30, v32
	v_and_b32_e32 v32, 0xffff0000, v77
	v_add_f32_e32 v31, v31, v32
	v_lshlrev_b32_e32 v32, 16, v78
	v_add_f32_e32 v32, v24, v32
	v_and_b32_e32 v24, 0xffff0000, v78
	s_waitcnt lgkmcnt(0)
	v_add_f32_e32 v33, v25, v24
	v_lshlrev_b32_e32 v24, 16, v79
	v_add_f32_e32 v34, v26, v24
	v_and_b32_e32 v24, 0xffff0000, v79
	v_add_f32_e32 v35, v27, v24
	v_cvt_pk_bf16_f32 v24, v28, v29
	v_mul_f32_e32 v29, v29, v29
	v_fmac_f32_e32 v29, v28, v28
	v_mul_f32_e32 v28, v31, v31
	v_fmac_f32_e32 v28, v30, v30
	v_cvt_pk_bf16_f32 v25, v30, v31
	v_add_f32_e32 v28, v29, v28
	v_mul_f32_e32 v29, v33, v33
	v_mul_f32_e32 v30, v35, v35
	v_fmac_f32_e32 v29, v32, v32
	v_fmac_f32_e32 v30, v34, v34
	v_add_f32_e32 v29, v29, v30
	v_add_f32_e32 v28, v28, v29
	v_lshlrev_b32_e32 v29, 16, v72
	v_add_f32_e32 v20, v20, v29
	v_and_b32_e32 v29, 0xffff0000, v72
	v_add_f32_e32 v21, v21, v29
	v_lshlrev_b32_e32 v29, 16, v73
	v_add_f32_e32 v29, v22, v29
	v_and_b32_e32 v22, 0xffff0000, v73
	v_add_f32_e32 v30, v23, v22
	v_lshlrev_b32_e32 v22, 16, v74
	v_add_f32_e32 v31, v16, v22
	v_and_b32_e32 v16, 0xffff0000, v74
	v_cvt_pk_bf16_f32 v26, v32, v33
	v_add_f32_e32 v32, v17, v16
	v_lshlrev_b32_e32 v16, 16, v75
	v_add_f32_e32 v33, v18, v16
	v_and_b32_e32 v16, 0xffff0000, v75
	v_cvt_pk_bf16_f32 v27, v34, v35
	v_add_f32_e32 v34, v19, v16
	v_mul_f32_e32 v16, v21, v21
	v_mul_f32_e32 v17, v30, v30
	v_fmac_f32_e32 v16, v20, v20
	v_fmac_f32_e32 v17, v29, v29
	v_add_f32_e32 v16, v16, v17
	v_mul_f32_e32 v17, v32, v32
	v_mul_f32_e32 v18, v34, v34
	v_fmac_f32_e32 v17, v31, v31
	v_fmac_f32_e32 v18, v33, v33
	v_add_f32_e32 v17, v17, v18
	v_add_f32_e32 v16, v16, v17
	v_add_f32_e32 v19, v28, v16
	ds_bpermute_b32 v28, v180, v19
	v_lshl_add_u64 v[16:17], s[0:1], 0, v[94:95]
	v_lshl_add_u64 v[22:23], v[152:153], 1, v[16:17]
	global_store_dwordx4 v[22:23], v[24:27], off
	v_cvt_pk_bf16_f32 v18, v20, v21
	s_waitcnt lgkmcnt(0)
	v_add_f32_e32 v16, v19, v28
	ds_bpermute_b32 v17, v128, v16
	v_cvt_pk_bf16_f32 v19, v29, v30
	v_cvt_pk_bf16_f32 v20, v31, v32
	v_cvt_pk_bf16_f32 v21, v33, v34
	global_store_dwordx4 v[22:23], v[18:21], off offset:256
	s_and_saveexec_b64 s[24:25], s[4:5]
	s_cbranch_execz .LBB0_1684
	s_waitcnt lgkmcnt(0)
	v_add_f32_e32 v18, v16, v17
	s_lshl_b32 s26, s45, 2
	v_lshlrev_b64 v[16:17], 7, v[92:93]
	s_ashr_i32 s27, s26, 31
	v_lshl_add_u64 v[16:17], s[2:3], 0, v[16:17]
	v_lshl_add_u64 v[16:17], s[26:27], 2, v[16:17]
	s_lshl_b32 s8, s42, 2
	v_lshl_add_u64 v[16:17], v[16:17], 0, s[8:9]
	global_store_dword v[16:17], v18, off
.LBB0_1684:
	s_or_b64 exec, exec, s[24:25]
	v_lshlrev_b32_e32 v16, 16, v68
	v_add_f32_e32 v12, v12, v16
	v_and_b32_e32 v16, 0xffff0000, v68
	v_add_f32_e32 v13, v13, v16
	v_lshlrev_b32_e32 v16, 16, v69
	v_add_f32_e32 v14, v14, v16
	v_and_b32_e32 v16, 0xffff0000, v69
	v_add_f32_e32 v15, v15, v16
	v_lshlrev_b32_e32 v16, 16, v70
	v_add_f32_e32 v16, v8, v16
	v_and_b32_e32 v8, 0xffff0000, v70
	s_waitcnt lgkmcnt(0)
	v_add_f32_e32 v17, v9, v8
	v_lshlrev_b32_e32 v8, 16, v71
	v_add_f32_e32 v18, v10, v8
	v_and_b32_e32 v8, 0xffff0000, v71
	v_add_f32_e32 v19, v11, v8
	v_cvt_pk_bf16_f32 v8, v12, v13
	v_mul_f32_e32 v13, v13, v13
	v_fmac_f32_e32 v13, v12, v12
	v_mul_f32_e32 v12, v15, v15
	v_fmac_f32_e32 v12, v14, v14
	v_cvt_pk_bf16_f32 v9, v14, v15
	v_add_f32_e32 v12, v13, v12
	v_mul_f32_e32 v13, v17, v17
	v_mul_f32_e32 v14, v19, v19
	v_fmac_f32_e32 v13, v16, v16
	v_fmac_f32_e32 v14, v18, v18
	v_add_f32_e32 v13, v13, v14
	v_add_f32_e32 v12, v12, v13
	v_lshlrev_b32_e32 v13, 16, v64
	v_add_f32_e32 v4, v4, v13
	v_and_b32_e32 v13, 0xffff0000, v64
	v_add_f32_e32 v5, v5, v13
	v_lshlrev_b32_e32 v13, 16, v65
	v_add_f32_e32 v13, v6, v13
	v_and_b32_e32 v6, 0xffff0000, v65
	v_add_f32_e32 v14, v7, v6
	v_lshlrev_b32_e32 v6, 16, v66
	v_add_f32_e32 v15, v0, v6
	v_and_b32_e32 v0, 0xffff0000, v66
	v_cvt_pk_bf16_f32 v10, v16, v17
	v_add_f32_e32 v16, v1, v0
	v_lshlrev_b32_e32 v0, 16, v67
	v_add_f32_e32 v17, v2, v0
	v_and_b32_e32 v0, 0xffff0000, v67
	v_cvt_pk_bf16_f32 v11, v18, v19
	v_add_f32_e32 v18, v3, v0
	v_mul_f32_e32 v0, v5, v5
	v_mul_f32_e32 v1, v14, v14
	v_fmac_f32_e32 v0, v4, v4
	v_fmac_f32_e32 v1, v13, v13
	v_add_f32_e32 v0, v0, v1
	v_mul_f32_e32 v1, v16, v16
	v_mul_f32_e32 v2, v18, v18
	v_fmac_f32_e32 v1, v15, v15
	v_fmac_f32_e32 v2, v17, v17
	v_add_f32_e32 v1, v1, v2
	v_add_f32_e32 v0, v0, v1
	v_add_f32_e32 v3, v12, v0
	ds_bpermute_b32 v12, v180, v3
	v_lshl_add_u64 v[0:1], s[0:1], 0, v[90:91]
	v_lshl_add_u64 v[6:7], v[152:153], 1, v[0:1]
	global_store_dwordx4 v[6:7], v[8:11], off
	v_cvt_pk_bf16_f32 v2, v4, v5
	s_waitcnt lgkmcnt(0)
	v_add_f32_e32 v0, v3, v12
	ds_bpermute_b32 v1, v128, v0
	v_cvt_pk_bf16_f32 v3, v13, v14
	v_cvt_pk_bf16_f32 v4, v15, v16
	v_cvt_pk_bf16_f32 v5, v17, v18
	global_store_dwordx4 v[6:7], v[2:5], off offset:256
	s_and_saveexec_b64 s[24:25], s[4:5]
	s_cbranch_execz .LBB0_1665
	s_waitcnt lgkmcnt(0)
	v_add_f32_e32 v2, v0, v1
	s_lshl_b32 s26, s45, 2
	v_lshlrev_b64 v[0:1], 7, v[88:89]
	s_ashr_i32 s27, s26, 31
	v_lshl_add_u64 v[0:1], s[2:3], 0, v[0:1]
	v_lshl_add_u64 v[0:1], s[26:27], 2, v[0:1]
	s_lshl_b32 s8, s42, 2
	v_lshl_add_u64 v[0:1], v[0:1], 0, s[8:9]
	global_store_dword v[0:1], v2, off
	s_branch .LBB0_1665

.LBB0_1906:
	ds_read_b128 v[134:137], v185
	ds_read_b128 v[138:141], v185 offset:1024
	ds_read_b128 v[142:145], v185 offset:2048
	ds_read_b128 v[146:149], v185 offset:3072
	s_add_i32 s26, s24, 0xfff50080
	s_cmp_eq_u32 s58, 40
	s_cselect_b32 s59, s19, s21
	s_cselect_b32 s60, s18, s20
	s_cselect_b32 s27, s7, s23
	s_cselect_b32 s61, s6, s22
	s_mov_b32 m0, s45
	v_lshl_add_u64 v[150:151], v[128:129], 0, s[24:25]
	ds_read_b128 v[164:167], v186
	ds_read_b128 v[168:171], v186 offset:1024
	ds_read_b128 v[172:175], v186 offset:2048
	ds_read_b128 v[176:179], v186 offset:3072
	ds_read_b128 v[190:193], v186 offset:4096
	ds_read_b128 v[194:197], v186 offset:5120
	ds_read_b128 v[198:201], v186 offset:6144
	ds_read_b128 v[202:205], v186 offset:7168
	global_load_lds_dwordx4 v[150:151], off
	v_lshl_add_u64 v[150:151], v[130:131], 0, s[24:25]
	s_mov_b32 m0, s46
	s_nop 0
	global_load_lds_dwordx4 v[150:151], off
	s_waitcnt lgkmcnt(8)
	s_barrier
	s_waitcnt lgkmcnt(0)
	s_setprio 1
	s_waitcnt lgkmcnt(0)
	v_mfma_f32_16x16x32_bf16 v[116:119], v[134:137], v[164:167], v[116:119]
	v_mfma_f32_16x16x32_bf16 v[112:115], v[142:145], v[164:167], v[112:115]
	v_mfma_f32_16x16x32_bf16 v[108:111], v[134:137], v[172:175], v[108:111]
	v_mfma_f32_16x16x32_bf16 v[104:107], v[142:145], v[172:175], v[104:107]
	v_mfma_f32_16x16x32_bf16 v[92:95], v[134:137], v[190:193], v[92:95]
	v_mfma_f32_16x16x32_bf16 v[88:91], v[142:145], v[190:193], v[88:91]
	v_mfma_f32_16x16x32_bf16 v[76:79], v[134:137], v[198:201], v[76:79]
	v_mfma_f32_16x16x32_bf16 v[72:75], v[142:145], v[198:201], v[72:75]
	v_mfma_f32_16x16x32_bf16 v[116:119], v[138:141], v[168:171], v[116:119]
	v_mfma_f32_16x16x32_bf16 v[112:115], v[146:149], v[168:171], v[112:115]
	v_mfma_f32_16x16x32_bf16 v[108:111], v[138:141], v[176:179], v[108:111]
	v_mfma_f32_16x16x32_bf16 v[104:107], v[146:149], v[176:179], v[104:107]
	v_mfma_f32_16x16x32_bf16 v[92:95], v[138:141], v[194:197], v[92:95]
	v_mfma_f32_16x16x32_bf16 v[88:91], v[146:149], v[194:197], v[88:91]
	v_mfma_f32_16x16x32_bf16 v[76:79], v[138:141], v[202:205], v[76:79]
	v_mfma_f32_16x16x32_bf16 v[72:75], v[146:149], v[202:205], v[72:75]
	s_setprio 0
	s_barrier
	s_cselect_b32 s62, 0, s26
	s_add_u32 s26, s61, s62
	s_addc_u32 s27, s27, 0
	s_mov_b32 m0, s47
	v_lshl_add_u64 v[150:151], s[26:27], 0, v[154:155]
	ds_read_b128 v[206:209], v187
	ds_read_b128 v[210:213], v187 offset:1024
	ds_read_b128 v[214:217], v187 offset:2048
	ds_read_b128 v[222:225], v187 offset:3072
	global_load_lds_dwordx4 v[150:151], off
	v_lshl_add_u64 v[180:181], s[26:27], 0, v[158:159]
	s_mov_b32 m0, s48
	s_nop 0
	global_load_lds_dwordx4 v[180:181], off
	s_barrier
	s_waitcnt lgkmcnt(0)
	s_setprio 1
	s_waitcnt lgkmcnt(0)
	v_mfma_f32_16x16x32_bf16 v[124:127], v[206:209], v[164:167], v[124:127]
	v_mfma_f32_16x16x32_bf16 v[120:123], v[214:217], v[164:167], v[120:123]
	v_mfma_f32_16x16x32_bf16 v[100:103], v[206:209], v[172:175], v[100:103]
	v_mfma_f32_16x16x32_bf16 v[96:99], v[214:217], v[172:175], v[96:99]
	v_mfma_f32_16x16x32_bf16 v[84:87], v[206:209], v[190:193], v[84:87]
	v_mfma_f32_16x16x32_bf16 v[80:83], v[214:217], v[190:193], v[80:83]
	v_mfma_f32_16x16x32_bf16 v[68:71], v[206:209], v[198:201], v[68:71]
	v_mfma_f32_16x16x32_bf16 v[64:67], v[214:217], v[198:201], v[64:67]
	v_mfma_f32_16x16x32_bf16 v[124:127], v[210:213], v[168:171], v[124:127]
	v_mfma_f32_16x16x32_bf16 v[120:123], v[222:225], v[168:171], v[120:123]
	v_mfma_f32_16x16x32_bf16 v[100:103], v[210:213], v[176:179], v[100:103]
	v_mfma_f32_16x16x32_bf16 v[96:99], v[222:225], v[176:179], v[96:99]
	v_mfma_f32_16x16x32_bf16 v[84:87], v[210:213], v[194:197], v[84:87]
	v_mfma_f32_16x16x32_bf16 v[80:83], v[222:225], v[194:197], v[80:83]
	v_mfma_f32_16x16x32_bf16 v[68:71], v[210:213], v[202:205], v[68:71]
	v_mfma_f32_16x16x32_bf16 v[64:67], v[222:225], v[202:205], v[64:67]
	s_setprio 0
	s_add_u32 s60, s60, s62
	s_addc_u32 s61, s59, 0
	s_mov_b32 m0, s37
	v_lshl_add_u64 v[218:219], s[60:61], 0, v[152:153]
	s_barrier
	ds_read_b128 v[164:167], v186 offset:16384
	ds_read_b128 v[168:171], v186 offset:17408
	ds_read_b128 v[172:175], v186 offset:18432
	ds_read_b128 v[176:179], v186 offset:19456
	ds_read_b128 v[190:193], v186 offset:20480
	ds_read_b128 v[194:197], v186 offset:21504
	ds_read_b128 v[198:201], v186 offset:22528
	ds_read_b128 v[202:205], v186 offset:23552
	global_load_lds_dwordx4 v[218:219], off
	v_lshl_add_u64 v[226:227], s[60:61], 0, v[156:157]
	s_mov_b32 m0, s38
	s_nop 0
	global_load_lds_dwordx4 v[226:227], off
	s_barrier
	s_waitcnt lgkmcnt(0)
	s_setprio 1
	s_waitcnt lgkmcnt(0)
	v_mfma_f32_16x16x32_bf16 v[52:55], v[134:137], v[164:167], v[52:55]
	v_mfma_f32_16x16x32_bf16 v[48:51], v[142:145], v[164:167], v[48:51]
	v_mfma_f32_16x16x32_bf16 v[44:47], v[134:137], v[172:175], v[44:47]
	v_mfma_f32_16x16x32_bf16 v[36:39], v[142:145], v[172:175], v[36:39]
	v_mfma_f32_16x16x32_bf16 v[28:31], v[134:137], v[190:193], v[28:31]
	v_mfma_f32_16x16x32_bf16 v[20:23], v[142:145], v[190:193], v[20:23]
	v_mfma_f32_16x16x32_bf16 v[12:15], v[134:137], v[198:201], v[12:15]
	v_mfma_f32_16x16x32_bf16 v[4:7], v[142:145], v[198:201], v[4:7]
	v_mfma_f32_16x16x32_bf16 v[52:55], v[138:141], v[168:171], v[52:55]
	v_mfma_f32_16x16x32_bf16 v[48:51], v[146:149], v[168:171], v[48:51]
	v_mfma_f32_16x16x32_bf16 v[44:47], v[138:141], v[176:179], v[44:47]
	v_mfma_f32_16x16x32_bf16 v[36:39], v[146:149], v[176:179], v[36:39]
	v_mfma_f32_16x16x32_bf16 v[28:31], v[138:141], v[194:197], v[28:31]
	v_mfma_f32_16x16x32_bf16 v[20:23], v[146:149], v[194:197], v[20:23]
	v_mfma_f32_16x16x32_bf16 v[12:15], v[138:141], v[202:205], v[12:15]
	v_mfma_f32_16x16x32_bf16 v[4:7], v[146:149], v[202:205], v[4:7]
	s_setprio 0
	s_barrier
	s_add_u32 s62, s26, 0xb0000
	s_addc_u32 s63, s27, 0
	s_mov_b32 m0, s52
	v_lshl_add_u64 v[134:135], s[62:63], 0, v[154:155]
	global_load_lds_dwordx4 v[134:135], off
	v_lshl_add_u64 v[134:135], s[62:63], 0, v[158:159]
	s_mov_b32 m0, s53
	s_nop 0
	global_load_lds_dwordx4 v[134:135], off
	s_waitcnt vmcnt(6)
	s_barrier
	s_setprio 1
	v_mfma_f32_16x16x32_bf16 v[60:63], v[206:209], v[164:167], v[60:63]
	v_mfma_f32_16x16x32_bf16 v[56:59], v[214:217], v[164:167], v[56:59]
	v_mfma_f32_16x16x32_bf16 v[40:43], v[206:209], v[172:175], v[40:43]
	v_mfma_f32_16x16x32_bf16 v[32:35], v[214:217], v[172:175], v[32:35]
	v_mfma_f32_16x16x32_bf16 v[24:27], v[206:209], v[190:193], v[24:27]
	v_mfma_f32_16x16x32_bf16 v[16:19], v[214:217], v[190:193], v[16:19]
	v_mfma_f32_16x16x32_bf16 v[8:11], v[206:209], v[198:201], v[8:11]
	v_mfma_f32_16x16x32_bf16 v[0:3], v[214:217], v[198:201], v[0:3]
	v_mfma_f32_16x16x32_bf16 v[60:63], v[210:213], v[168:171], v[60:63]
	v_mfma_f32_16x16x32_bf16 v[56:59], v[222:225], v[168:171], v[56:59]
	v_mfma_f32_16x16x32_bf16 v[40:43], v[210:213], v[176:179], v[40:43]
	v_mfma_f32_16x16x32_bf16 v[32:35], v[222:225], v[176:179], v[32:35]
	v_mfma_f32_16x16x32_bf16 v[24:27], v[210:213], v[194:197], v[24:27]
	v_mfma_f32_16x16x32_bf16 v[16:19], v[222:225], v[194:197], v[16:19]
	v_mfma_f32_16x16x32_bf16 v[8:11], v[210:213], v[202:205], v[8:11]
	v_mfma_f32_16x16x32_bf16 v[0:3], v[222:225], v[202:205], v[0:3]
	s_setprio 0
	s_barrier
	ds_read_b128 v[134:137], v132
	ds_read_b128 v[138:141], v132 offset:1024
	ds_read_b128 v[142:145], v132 offset:2048
	ds_read_b128 v[146:149], v132 offset:3072
	s_add_u32 s60, s60, 0xb0000
	s_addc_u32 s61, s61, 0
	s_mov_b32 m0, s39
	v_lshl_add_u64 v[206:207], s[60:61], 0, v[152:153]
	ds_read_b128 v[164:167], v186 offset:32768
	ds_read_b128 v[168:171], v186 offset:33792
	ds_read_b128 v[172:175], v186 offset:34816
	ds_read_b128 v[176:179], v186 offset:35840
	ds_read_b128 v[190:193], v186 offset:36864
	ds_read_b128 v[194:197], v186 offset:37888
	ds_read_b128 v[198:201], v186 offset:38912
	ds_read_b128 v[202:205], v186 offset:39936
	global_load_lds_dwordx4 v[206:207], off
	v_lshl_add_u64 v[206:207], s[60:61], 0, v[156:157]
	s_mov_b32 m0, s40
	s_nop 0
	global_load_lds_dwordx4 v[206:207], off
	s_waitcnt lgkmcnt(8)
	s_barrier
	s_waitcnt lgkmcnt(0)
	s_setprio 1
	s_waitcnt lgkmcnt(0)
	v_mfma_f32_16x16x32_bf16 v[116:119], v[134:137], v[164:167], v[116:119]
	v_mfma_f32_16x16x32_bf16 v[112:115], v[142:145], v[164:167], v[112:115]
	v_mfma_f32_16x16x32_bf16 v[108:111], v[134:137], v[172:175], v[108:111]
	v_mfma_f32_16x16x32_bf16 v[104:107], v[142:145], v[172:175], v[104:107]
	v_mfma_f32_16x16x32_bf16 v[92:95], v[134:137], v[190:193], v[92:95]
	v_mfma_f32_16x16x32_bf16 v[88:91], v[142:145], v[190:193], v[88:91]
	v_mfma_f32_16x16x32_bf16 v[76:79], v[134:137], v[198:201], v[76:79]
	v_mfma_f32_16x16x32_bf16 v[72:75], v[142:145], v[198:201], v[72:75]
	v_mfma_f32_16x16x32_bf16 v[116:119], v[138:141], v[168:171], v[116:119]
	v_mfma_f32_16x16x32_bf16 v[112:115], v[146:149], v[168:171], v[112:115]
	v_mfma_f32_16x16x32_bf16 v[108:111], v[138:141], v[176:179], v[108:111]
	v_mfma_f32_16x16x32_bf16 v[104:107], v[146:149], v[176:179], v[104:107]
	v_mfma_f32_16x16x32_bf16 v[92:95], v[138:141], v[194:197], v[92:95]
	v_mfma_f32_16x16x32_bf16 v[88:91], v[146:149], v[194:197], v[88:91]
	v_mfma_f32_16x16x32_bf16 v[76:79], v[138:141], v[202:205], v[76:79]
	v_mfma_f32_16x16x32_bf16 v[72:75], v[146:149], v[202:205], v[72:75]
	s_setprio 0
	s_barrier
	s_mov_b32 m0, s54
	v_lshl_add_u64 v[150:151], v[150:151], 0, s[10:11]
	ds_read_b128 v[206:209], v133
	ds_read_b128 v[210:213], v133 offset:1024
	ds_read_b128 v[214:217], v133 offset:2048
	ds_read_b128 v[222:225], v133 offset:3072
	global_load_lds_dwordx4 v[150:151], off
	v_lshl_add_u64 v[150:151], v[180:181], 0, s[10:11]
	s_mov_b32 m0, s55
	s_nop 0
	global_load_lds_dwordx4 v[150:151], off
	s_barrier
	s_waitcnt lgkmcnt(0)
	s_setprio 1
	s_waitcnt lgkmcnt(0)
	v_mfma_f32_16x16x32_bf16 v[124:127], v[206:209], v[164:167], v[124:127]
	v_mfma_f32_16x16x32_bf16 v[120:123], v[214:217], v[164:167], v[120:123]
	v_mfma_f32_16x16x32_bf16 v[100:103], v[206:209], v[172:175], v[100:103]
	v_mfma_f32_16x16x32_bf16 v[96:99], v[214:217], v[172:175], v[96:99]
	v_mfma_f32_16x16x32_bf16 v[84:87], v[206:209], v[190:193], v[84:87]
	v_mfma_f32_16x16x32_bf16 v[80:83], v[214:217], v[190:193], v[80:83]
	v_mfma_f32_16x16x32_bf16 v[68:71], v[206:209], v[198:201], v[68:71]
	v_mfma_f32_16x16x32_bf16 v[64:67], v[214:217], v[198:201], v[64:67]
	v_mfma_f32_16x16x32_bf16 v[124:127], v[210:213], v[168:171], v[124:127]
	v_mfma_f32_16x16x32_bf16 v[120:123], v[222:225], v[168:171], v[120:123]
	v_mfma_f32_16x16x32_bf16 v[100:103], v[210:213], v[176:179], v[100:103]
	v_mfma_f32_16x16x32_bf16 v[96:99], v[222:225], v[176:179], v[96:99]
	v_mfma_f32_16x16x32_bf16 v[84:87], v[210:213], v[194:197], v[84:87]
	v_mfma_f32_16x16x32_bf16 v[80:83], v[222:225], v[194:197], v[80:83]
	v_mfma_f32_16x16x32_bf16 v[68:71], v[210:213], v[202:205], v[68:71]
	v_mfma_f32_16x16x32_bf16 v[64:67], v[222:225], v[202:205], v[64:67]
	s_setprio 0
	s_mov_b32 m0, s42
	v_lshl_add_u64 v[150:151], v[218:219], 0, s[10:11]
	s_barrier
	ds_read_b128 v[164:167], v186 offset:49152
	ds_read_b128 v[168:171], v186 offset:50176
	ds_read_b128 v[172:175], v186 offset:51200
	ds_read_b128 v[176:179], v186 offset:52224
	ds_read_b128 v[190:193], v186 offset:53248
	ds_read_b128 v[194:197], v186 offset:54272
	ds_read_b128 v[198:201], v186 offset:55296
	ds_read_b128 v[202:205], v186 offset:56320
	global_load_lds_dwordx4 v[150:151], off
	v_lshl_add_u64 v[150:151], v[226:227], 0, s[10:11]
	s_mov_b32 m0, s43
	s_nop 0
	global_load_lds_dwordx4 v[150:151], off
	s_barrier
;     ...
;         G_PAIR(0, 1);
; #pragma unroll 1
;         for (int t = 2; t < nt; t += 2) G_PAIR(t, 0);
	s_waitcnt lgkmcnt(0)
	s_setprio 1
	s_waitcnt lgkmcnt(0)
	v_mfma_f32_16x16x32_bf16 v[52:55], v[134:137], v[164:167], v[52:55]
	v_mfma_f32_16x16x32_bf16 v[48:51], v[142:145], v[164:167], v[48:51]
	v_mfma_f32_16x16x32_bf16 v[44:47], v[134:137], v[172:175], v[44:47]
	v_mfma_f32_16x16x32_bf16 v[36:39], v[142:145], v[172:175], v[36:39]
	v_mfma_f32_16x16x32_bf16 v[28:31], v[134:137], v[190:193], v[28:31]
	v_mfma_f32_16x16x32_bf16 v[20:23], v[142:145], v[190:193], v[20:23]
	v_mfma_f32_16x16x32_bf16 v[12:15], v[134:137], v[198:201], v[12:15]
	v_mfma_f32_16x16x32_bf16 v[4:7], v[142:145], v[198:201], v[4:7]
	v_mfma_f32_16x16x32_bf16 v[52:55], v[138:141], v[168:171], v[52:55]
	v_mfma_f32_16x16x32_bf16 v[48:51], v[146:149], v[168:171], v[48:51]
	v_mfma_f32_16x16x32_bf16 v[44:47], v[138:141], v[176:179], v[44:47]
	v_mfma_f32_16x16x32_bf16 v[36:39], v[146:149], v[176:179], v[36:39]
	v_mfma_f32_16x16x32_bf16 v[28:31], v[138:141], v[194:197], v[28:31]
	v_mfma_f32_16x16x32_bf16 v[20:23], v[146:149], v[194:197], v[20:23]
	v_mfma_f32_16x16x32_bf16 v[12:15], v[138:141], v[202:205], v[12:15]
	v_mfma_f32_16x16x32_bf16 v[4:7], v[146:149], v[202:205], v[4:7]
	s_setprio 0
	s_barrier
	s_add_u32 s26, s26, 0xb0080
	s_addc_u32 s27, s27, 0
	s_mov_b32 m0, s56
	v_lshl_add_u64 v[134:135], s[26:27], 0, v[154:155]
	global_load_lds_dwordx4 v[134:135], off
	v_lshl_add_u64 v[134:135], s[26:27], 0, v[158:159]
	s_mov_b32 m0, s57
	s_nop 0
	global_load_lds_dwordx4 v[134:135], off
	s_waitcnt vmcnt(6)
	s_barrier
	s_setprio 1
	v_mfma_f32_16x16x32_bf16 v[60:63], v[206:209], v[164:167], v[60:63]
	v_mfma_f32_16x16x32_bf16 v[56:59], v[214:217], v[164:167], v[56:59]
	v_mfma_f32_16x16x32_bf16 v[40:43], v[206:209], v[172:175], v[40:43]
	v_mfma_f32_16x16x32_bf16 v[32:35], v[214:217], v[172:175], v[32:35]
	v_mfma_f32_16x16x32_bf16 v[24:27], v[206:209], v[190:193], v[24:27]
	v_mfma_f32_16x16x32_bf16 v[16:19], v[214:217], v[190:193], v[16:19]
	v_mfma_f32_16x16x32_bf16 v[8:11], v[206:209], v[198:201], v[8:11]
	v_mfma_f32_16x16x32_bf16 v[0:3], v[214:217], v[198:201], v[0:3]
	v_mfma_f32_16x16x32_bf16 v[60:63], v[210:213], v[168:171], v[60:63]
	v_mfma_f32_16x16x32_bf16 v[56:59], v[222:225], v[168:171], v[56:59]
	v_mfma_f32_16x16x32_bf16 v[40:43], v[210:213], v[176:179], v[40:43]
	v_mfma_f32_16x16x32_bf16 v[32:35], v[222:225], v[176:179], v[32:35]
	v_mfma_f32_16x16x32_bf16 v[24:27], v[210:213], v[194:197], v[24:27]
	v_mfma_f32_16x16x32_bf16 v[16:19], v[222:225], v[194:197], v[16:19]
	v_mfma_f32_16x16x32_bf16 v[8:11], v[210:213], v[202:205], v[8:11]
	v_mfma_f32_16x16x32_bf16 v[0:3], v[222:225], v[202:205], v[0:3]
	s_setprio 0
	s_add_i32 s58, s58, 2
	s_add_u32 s24, s24, 0x100
	s_addc_u32 s25, s25, 0
	s_cmp_gt_u32 s58, 41
	s_barrier
	s_cbranch_scc0 .LBB0_1906
; __device__ __forceinline__ unsigned pk2(float lo, float hi) { unsigned r; asm volatile("v_cvt_pk_bf16_f32 %0, %1, %2" : "=v"(r) : "v"(lo), "v"(hi)); return r; }
; __device__ __forceinline__ unsigned pk2(float lo, float hi) { return f2bf(lo) | (f2bf(hi) << 16); }
;     __device__ __forceinline__ void epi(const f32x4 (&acc)[2][2][4][2], const Unit& u, int wr, int wc, int fr, int fq) const {
;     ...
;         for (int ai = 0; ai < 2; ++ai) {
;             u32x4 xo[4][2];
; #pragma unroll
;             for (int m = 0; m < 4; ++m)
; #pragma unroll
;                 for (int bj = 0; bj < 2; ++bj) xo[m][bj] = *(const u32x4*)(xb + (size_t)(row0 + ai * 128 + m * 16) * D + col0 + bj * 128);
; #pragma unroll
;             for (int m = 0; m < 4; ++m) {
;                 const int row = row0 + ai * 128 + m * 16; const size_t off = (size_t)row * D + col0; float ss = 0.f;
; #pragma unroll
;                 for (int bj = 0; bj < 2; ++bj) {
;                     const u32x4 o = xo[m][bj]; const f32x4 a0v = acc[ai][bj][m][0], a1v = acc[ai][bj][m][1];
;                     const float v0 = bf_lo(o.x) + coef * a0v[0], v1 = bf_hi(o.x) + coef * a0v[1], v2 = bf_lo(o.y) + coef * a0v[2], v3 = bf_hi(o.y) + coef * a0v[3];
;                     const float v4 = bf_lo(o.z) + coef * a1v[0], v5 = bf_hi(o.z) + coef * a1v[1], v6 = bf_lo(o.w) + coef * a1v[2], v7 = bf_hi(o.w) + coef * a1v[3];
;                     u32x4 w; w.x = pk2(v0, v1); w.y = pk2(v2, v3); w.z = pk2(v4, v5); w.w = pk2(v6, v7);
;                     *(u32x4*)(xb + off + bj * 128) = w;
;                     ss += ((v0 * v0 + v1 * v1) + (v2 * v2 + v3 * v3)) + ((v4 * v4 + v5 * v5) + (v6 * v6 + v7 * v7));
;                 }
;                 ss += __shfl_xor(ss, 16); ss += __shfl_xor(ss, 32);
;                 if (fq == 0) rowss[(size_t)row * 32 + u.pn * 4 + wc] = ss;
	v_lshl_or_b32 v164, s30, 8, v184
	v_lshl_add_u32 v168, s2, 8, v182
	v_ashrrev_i32_e32 v165, 31, v164
	v_lshlrev_b64 v[198:199], 1, v[164:165]
	v_ashrrev_i32_e32 v169, 31, v168
	v_lshl_add_u64 v[166:167], s[0:1], 0, v[198:199]
	v_lshlrev_b64 v[200:201], 11, v[168:169]
	v_lshl_add_u64 v[128:129], v[166:167], 0, v[200:201]
	v_mov_b32_e32 v218, 0x40000
	v_mov_b32_e32 v219, 0
	v_lshl_add_u64 v[216:217], v[128:129], 0, v[218:219]
	v_mov_b32_e32 v218, 0x8000
	global_load_dwordx4 v[190:193], v[128:129], off
	global_load_dwordx4 v[194:197], v[128:129], off offset:256
	v_or_b32_e32 v178, 16, v168
	v_or_b32_e32 v174, 32, v168
	v_or_b32_e32 v170, 48, v168
	v_ashrrev_i32_e32 v179, 31, v178
	v_ashrrev_i32_e32 v175, 31, v174
	v_ashrrev_i32_e32 v171, 31, v170
	v_lshlrev_b64 v[180:181], 11, v[178:179]
	v_lshlrev_b64 v[176:177], 11, v[174:175]
	v_lshlrev_b64 v[172:173], 11, v[170:171]
	v_lshl_add_u64 v[128:129], v[166:167], 0, v[180:181]
	v_lshl_add_u64 v[130:131], v[166:167], 0, v[176:177]
	v_lshl_add_u64 v[202:203], v[166:167], 0, v[172:173]
	global_load_dwordx4 v[148:151], v[128:129], off
	global_load_dwordx4 v[144:147], v[128:129], off offset:256
	global_load_dwordx4 v[140:143], v[130:131], off
	global_load_dwordx4 v[136:139], v[130:131], off offset:256
	global_load_dwordx4 v[132:135], v[202:203], off
	s_nop 0
	global_load_dwordx4 v[128:131], v[202:203], off offset:256
	global_load_dwordx4 v[222:225], v[216:217], off
	global_load_dwordx4 v[226:229], v[216:217], off offset:256
	v_lshl_add_u64 v[216:217], v[216:217], 0, v[218:219]
	global_load_dwordx4 v[230:233], v[216:217], off
	global_load_dwordx4 v[234:237], v[216:217], off offset:256
	v_lshl_add_u64 v[216:217], v[216:217], 0, v[218:219]
	global_load_dwordx4 v[238:241], v[216:217], off
	global_load_dwordx4 v[242:245], v[216:217], off offset:256
	v_lshl_add_u64 v[216:217], v[216:217], 0, v[218:219]
	global_load_dwordx4 v[246:249], v[216:217], off
	global_load_dwordx4 v[250:253], v[216:217], off offset:256
	v_and_b32_e32 v202, 64, v188
	v_xor_b32_e32 v189, 16, v188
	v_add_u32_e32 v202, 64, v202
	v_cmp_lt_i32_e32 vcc, v189, v202
	s_waitcnt vmcnt(8)
	v_lshlrev_b32_e32 v203, 16, v190
	v_and_b32_e32 v190, 0xffff0000, v190
	v_lshlrev_b32_e32 v204, 16, v191
	v_and_b32_e32 v191, 0xffff0000, v191
	v_lshlrev_b32_e32 v205, 16, v192
	v_and_b32_e32 v192, 0xffff0000, v192
	v_lshlrev_b32_e32 v206, 16, v193
	v_and_b32_e32 v193, 0xffff0000, v193
	v_lshlrev_b32_e32 v207, 16, v194
	v_and_b32_e32 v194, 0xffff0000, v194
	v_lshlrev_b32_e32 v208, 16, v195
	v_and_b32_e32 v195, 0xffff0000, v195
	v_lshlrev_b32_e32 v209, 16, v196
	v_and_b32_e32 v196, 0xffff0000, v196
	v_lshlrev_b32_e32 v210, 16, v197
	v_and_b32_e32 v197, 0xffff0000, v197
	v_fmac_f32_e32 v190, 0.5, v117
	v_fmac_f32_e32 v191, 0.5, v119
	v_fmac_f32_e32 v192, 0.5, v113
	v_fmac_f32_e32 v193, 0.5, v115
	v_fmac_f32_e32 v194, 0.5, v125
	v_fmac_f32_e32 v195, 0.5, v127
	v_fmac_f32_e32 v196, 0.5, v121
	v_fmac_f32_e32 v197, 0.5, v123
	v_fmac_f32_e32 v203, 0.5, v116
	v_fmac_f32_e32 v204, 0.5, v118
	v_fmac_f32_e32 v205, 0.5, v112
	v_fmac_f32_e32 v206, 0.5, v114
	v_fmac_f32_e32 v207, 0.5, v124
	v_fmac_f32_e32 v208, 0.5, v126
	v_fmac_f32_e32 v209, 0.5, v120
	v_fmac_f32_e32 v210, 0.5, v122
	v_mul_f32_e32 v112, v190, v190
	v_mul_f32_e32 v113, v191, v191
	v_mul_f32_e32 v118, v192, v192
	v_mul_f32_e32 v119, v193, v193
	v_mul_f32_e32 v120, v194, v194
	v_mul_f32_e32 v121, v195, v195
	v_mul_f32_e32 v122, v196, v196
	v_mul_f32_e32 v123, v197, v197
	v_fmac_f32_e32 v112, v203, v203
	v_fmac_f32_e32 v113, v204, v204
	v_fmac_f32_e32 v118, v205, v205
	v_fmac_f32_e32 v119, v206, v206
	v_fmac_f32_e32 v120, v207, v207
	v_fmac_f32_e32 v121, v208, v208
	v_fmac_f32_e32 v122, v209, v209
	v_fmac_f32_e32 v123, v210, v210
	v_add_f32_e32 v112, v112, v113
	v_add_f32_e32 v113, v118, v119
	v_add_f32_e32 v118, v120, v121
	v_add_f32_e32 v119, v122, v123
	v_cndmask_b32_e32 v189, v188, v189, vcc
	v_add_f32_e32 v112, v112, v113
	v_add_f32_e32 v113, v118, v119
	v_add_f32_e32 v113, v112, v113
	v_lshlrev_b32_e32 v112, 2, v189
	ds_bpermute_b32 v122, v112, v113
	v_lshl_add_u64 v[118:119], s[0:1], 0, v[200:201]
	v_cvt_pk_bf16_f32 v114, v203, v190
	v_lshl_add_u64 v[120:121], v[118:119], 0, v[198:199]
	v_cvt_pk_bf16_f32 v115, v204, v191
	v_cvt_pk_bf16_f32 v116, v205, v192
	v_cvt_pk_bf16_f32 v117, v206, v193
	global_store_dwordx4 v[120:121], v[114:117], off
	s_waitcnt lgkmcnt(0)
	s_nop 0
	v_add_f32_e32 v114, v113, v122
	v_xor_b32_e32 v113, 32, v188
	v_cmp_lt_i32_e32 vcc, v113, v202
	v_cvt_pk_bf16_f32 v116, v207, v194
	v_cvt_pk_bf16_f32 v117, v208, v195
	v_cvt_pk_bf16_f32 v118, v209, v196
	v_cvt_pk_bf16_f32 v119, v210, v197
	global_store_dwordx4 v[120:121], v[116:119], off offset:256
	s_nop 0
	v_cndmask_b32_e32 v113, v188, v113, vcc
	v_lshlrev_b32_e32 v113, 2, v113
	ds_bpermute_b32 v115, v113, v114
	s_and_saveexec_b64 s[20:21], s[4:5]
	s_cbranch_execz .LBB0_1909
	s_waitcnt lgkmcnt(0)
	v_add_f32_e32 v116, v114, v115
	s_lshl_b32 s22, s30, 2
	v_lshlrev_b64 v[114:115], 7, v[168:169]
	s_ashr_i32 s23, s22, 31
	v_lshl_add_u64 v[114:115], s[8:9], 0, v[114:115]
	v_lshl_add_u64 v[114:115], s[22:23], 2, v[114:115]
	s_lshl_b32 s2, s41, 2
	v_lshl_add_u64 v[114:115], v[114:115], 0, s[2:3]
	global_store_dword v[114:115], v116, off

; __device__ __forceinline__ unsigned pk2(float lo, float hi) { unsigned r; asm volatile("v_cvt_pk_bf16_f32 %0, %1, %2" : "=v"(r) : "v"(lo), "v"(hi)); return r; }
; __device__ __forceinline__ unsigned pk2(float lo, float hi) { return f2bf(lo) | (f2bf(hi) << 16); }
;     __device__ __forceinline__ void epi(const f32x4 (&acc)[2][2][4][2], const Unit& u, int wr, int wc, int fr, int fq) const {
;     ...
;             for (int m = 0; m < 4; ++m)
; #pragma unroll
;                 for (int bj = 0; bj < 2; ++bj) xo[m][bj] = *(const u32x4*)(xb + (size_t)(row0 + ai * 128 + m * 16) * D + col0 + bj * 128);
; #pragma unroll
;             for (int m = 0; m < 4; ++m) {
;                 const int row = row0 + ai * 128 + m * 16; const size_t off = (size_t)row * D + col0; float ss = 0.f;
; #pragma unroll
;                 for (int bj = 0; bj < 2; ++bj) {
;                     const u32x4 o = xo[m][bj]; const f32x4 a0v = acc[ai][bj][m][0], a1v = acc[ai][bj][m][1];
;                     const float v0 = bf_lo(o.x) + coef * a0v[0], v1 = bf_hi(o.x) + coef * a0v[1], v2 = bf_lo(o.y) + coef * a0v[2], v3 = bf_hi(o.y) + coef * a0v[3];
;                     const float v4 = bf_lo(o.z) + coef * a1v[0], v5 = bf_hi(o.z) + coef * a1v[1], v6 = bf_lo(o.w) + coef * a1v[2], v7 = bf_hi(o.w) + coef * a1v[3];
;                     u32x4 w; w.x = pk2(v0, v1); w.y = pk2(v2, v3); w.z = pk2(v4, v5); w.w = pk2(v6, v7);
;                     *(u32x4*)(xb + off + bj * 128) = w;
;                     ss += ((v0 * v0 + v1 * v1) + (v2 * v2 + v3 * v3)) + ((v4 * v4 + v5 * v5) + (v6 * v6 + v7 * v7));
;                 }
;                 ss += __shfl_xor(ss, 16); ss += __shfl_xor(ss, 32);
;                 if (fq == 0) rowss[(size_t)row * 32 + u.pn * 4 + wc] = ss;
;             }
.LBB0_1915:
	s_or_b64 exec, exec, s[20:21]
	v_add_u32_e32 v100, 0x80, v168
	v_ashrrev_i32_e32 v101, 31, v100
	v_lshlrev_b64 v[110:111], 11, v[100:101]
	s_waitcnt lgkmcnt(0)
	v_lshl_add_u64 v[64:65], v[166:167], 0, v[110:111]
	s_waitcnt vmcnt(8)
	v_mov_b64_e32 v[102:103], v[222:223]
	v_mov_b64_e32 v[104:105], v[224:225]
	v_mov_b64_e32 v[106:107], v[226:227]
	v_mov_b64_e32 v[108:109], v[228:229]
	v_add_u32_e32 v96, 0x90, v168
	v_add_u32_e32 v92, 0xa0, v168
	v_add_u32_e32 v88, 0xb0, v168
	v_ashrrev_i32_e32 v97, 31, v96
	v_ashrrev_i32_e32 v93, 31, v92
	v_ashrrev_i32_e32 v89, 31, v88
	v_lshlrev_b64 v[98:99], 11, v[96:97]
	v_lshlrev_b64 v[94:95], 11, v[92:93]
	v_lshlrev_b64 v[90:91], 11, v[88:89]
	v_lshl_add_u64 v[64:65], v[166:167], 0, v[98:99]
	v_lshl_add_u64 v[66:67], v[166:167], 0, v[94:95]
	v_lshl_add_u64 v[114:115], v[166:167], 0, v[90:91]
	v_mov_b64_e32 v[84:85], v[230:231]
	v_mov_b64_e32 v[86:87], v[232:233]
	v_mov_b64_e32 v[80:81], v[234:235]
	v_mov_b64_e32 v[82:83], v[236:237]
	v_mov_b64_e32 v[76:77], v[238:239]
	v_mov_b64_e32 v[78:79], v[240:241]
	v_mov_b64_e32 v[72:73], v[242:243]
	v_mov_b64_e32 v[74:75], v[244:245]
	v_mov_b64_e32 v[68:69], v[246:247]
	v_mov_b64_e32 v[70:71], v[248:249]
	s_nop 0
	v_mov_b64_e32 v[64:65], v[250:251]
	v_mov_b64_e32 v[66:67], v[252:253]
	v_lshlrev_b32_e32 v114, 16, v102
	v_and_b32_e32 v102, 0xffff0000, v102
	v_lshlrev_b32_e32 v115, 16, v103
	v_and_b32_e32 v103, 0xffff0000, v103
	v_lshlrev_b32_e32 v116, 16, v104
	v_and_b32_e32 v104, 0xffff0000, v104
	v_lshlrev_b32_e32 v117, 16, v105
	v_and_b32_e32 v105, 0xffff0000, v105
	v_lshlrev_b32_e32 v118, 16, v106
	v_and_b32_e32 v106, 0xffff0000, v106
	v_lshlrev_b32_e32 v119, 16, v107
	v_and_b32_e32 v107, 0xffff0000, v107
	v_lshlrev_b32_e32 v120, 16, v108
	v_and_b32_e32 v108, 0xffff0000, v108
	v_lshlrev_b32_e32 v121, 16, v109
	v_and_b32_e32 v109, 0xffff0000, v109
	v_fmac_f32_e32 v102, 0.5, v53
	v_fmac_f32_e32 v103, 0.5, v55
	v_fmac_f32_e32 v104, 0.5, v49
	v_fmac_f32_e32 v105, 0.5, v51
	v_fmac_f32_e32 v106, 0.5, v61
	v_fmac_f32_e32 v107, 0.5, v63
	v_fmac_f32_e32 v108, 0.5, v57
	v_fmac_f32_e32 v109, 0.5, v59
	v_fmac_f32_e32 v114, 0.5, v52
	v_fmac_f32_e32 v115, 0.5, v54
	v_fmac_f32_e32 v116, 0.5, v48
	v_fmac_f32_e32 v117, 0.5, v50
	v_fmac_f32_e32 v118, 0.5, v60
	v_fmac_f32_e32 v119, 0.5, v62
	v_fmac_f32_e32 v120, 0.5, v56
	v_fmac_f32_e32 v121, 0.5, v58
	v_mul_f32_e32 v52, v102, v102
	v_mul_f32_e32 v53, v103, v103
	v_mul_f32_e32 v54, v104, v104
	v_mul_f32_e32 v55, v105, v105
	v_mul_f32_e32 v56, v106, v106
	v_mul_f32_e32 v57, v107, v107
	v_mul_f32_e32 v58, v108, v108
	v_mul_f32_e32 v59, v109, v109
	v_fmac_f32_e32 v52, v114, v114
	v_fmac_f32_e32 v53, v115, v115
	v_fmac_f32_e32 v54, v116, v116
	v_fmac_f32_e32 v55, v117, v117
	v_fmac_f32_e32 v56, v118, v118
	v_fmac_f32_e32 v57, v119, v119
	v_fmac_f32_e32 v58, v120, v120
	v_fmac_f32_e32 v59, v121, v121
	v_add_f32_e32 v52, v52, v53
	v_add_f32_e32 v53, v54, v55
	v_add_f32_e32 v54, v56, v57
	v_add_f32_e32 v55, v58, v59
	v_add_f32_e32 v52, v52, v53
	v_add_f32_e32 v53, v54, v55
	v_add_f32_e32 v56, v52, v53
	ds_bpermute_b32 v57, v112, v56
	v_lshl_add_u64 v[52:53], s[0:1], 0, v[110:111]
	v_cvt_pk_bf16_f32 v48, v114, v102
	v_lshl_add_u64 v[54:55], v[164:165], 1, v[52:53]
	v_cvt_pk_bf16_f32 v49, v115, v103
	v_cvt_pk_bf16_f32 v50, v116, v104
	v_cvt_pk_bf16_f32 v51, v117, v105
	global_store_dwordx4 v[54:55], v[48:51], off
	s_waitcnt lgkmcnt(0)
	s_nop 0
	v_add_f32_e32 v48, v56, v57
	ds_bpermute_b32 v49, v113, v48
	v_cvt_pk_bf16_f32 v50, v118, v106
	v_cvt_pk_bf16_f32 v51, v119, v107
	v_cvt_pk_bf16_f32 v52, v120, v108
	v_cvt_pk_bf16_f32 v53, v121, v109
	global_store_dwordx4 v[54:55], v[50:53], off offset:256
	s_and_saveexec_b64 s[20:21], s[4:5]
	s_cbranch_execz .LBB0_1917
	s_waitcnt lgkmcnt(0)
	v_add_f32_e32 v50, v48, v49
	s_lshl_b32 s22, s30, 2
	v_lshlrev_b64 v[48:49], 7, v[100:101]
	s_ashr_i32 s23, s22, 31
	v_lshl_add_u64 v[48:49], s[8:9], 0, v[48:49]
	v_lshl_add_u64 v[48:49], s[22:23], 2, v[48:49]
	s_lshl_b32 s2, s41, 2
	v_lshl_add_u64 v[48:49], v[48:49], 0, s[2:3]
	global_store_dword v[48:49], v50, off
.LBB0_1917:
	s_or_b64 exec, exec, s[20:21]
	v_lshlrev_b32_e32 v48, 16, v84
	v_fmac_f32_e32 v48, 0.5, v44
	v_and_b32_e32 v44, 0xffff0000, v84
	v_fmac_f32_e32 v44, 0.5, v45
	v_lshlrev_b32_e32 v45, 16, v85
	v_fmac_f32_e32 v45, 0.5, v46
	v_and_b32_e32 v46, 0xffff0000, v85
	v_fmac_f32_e32 v46, 0.5, v47
	v_lshlrev_b32_e32 v47, 16, v86
	s_waitcnt lgkmcnt(0)
	v_and_b32_e32 v49, 0xffff0000, v86
	v_fmac_f32_e32 v47, 0.5, v36
	v_fmac_f32_e32 v49, 0.5, v37
	v_and_b32_e32 v51, 0xffff0000, v87
	v_cvt_pk_bf16_f32 v36, v48, v44
	v_cvt_pk_bf16_f32 v37, v45, v46
	v_mul_f32_e32 v44, v44, v44
	v_mul_f32_e32 v46, v46, v46
	v_lshlrev_b32_e32 v50, 16, v87
	v_fmac_f32_e32 v51, 0.5, v39
	v_fmac_f32_e32 v44, v48, v48
	v_fmac_f32_e32 v46, v45, v45
	v_fmac_f32_e32 v50, 0.5, v38
	v_add_f32_e32 v44, v44, v46
	v_mul_f32_e32 v45, v49, v49
	v_mul_f32_e32 v46, v51, v51
	v_cvt_pk_bf16_f32 v38, v47, v49
	v_fmac_f32_e32 v45, v47, v47
	v_fmac_f32_e32 v46, v50, v50
	v_lshlrev_b32_e32 v47, 16, v81
	v_add_f32_e32 v45, v45, v46
	v_and_b32_e32 v46, 0xffff0000, v80
	v_fmac_f32_e32 v47, 0.5, v42
	v_and_b32_e32 v42, 0xffff0000, v81
	v_add_f32_e32 v44, v44, v45
	v_lshlrev_b32_e32 v45, 16, v80
	v_fmac_f32_e32 v46, 0.5, v41
	v_fmac_f32_e32 v42, 0.5, v43
	v_lshlrev_b32_e32 v43, 16, v82
	v_and_b32_e32 v48, 0xffff0000, v82
	v_cvt_pk_bf16_f32 v39, v50, v51
	v_fmac_f32_e32 v45, 0.5, v40
	v_fmac_f32_e32 v43, 0.5, v32
	v_fmac_f32_e32 v48, 0.5, v33
	v_and_b32_e32 v50, 0xffff0000, v83
	v_mul_f32_e32 v32, v46, v46
	v_mul_f32_e32 v33, v42, v42
	v_lshlrev_b32_e32 v49, 16, v83
	v_fmac_f32_e32 v50, 0.5, v35
	v_fmac_f32_e32 v32, v45, v45
	v_fmac_f32_e32 v33, v47, v47
	v_fmac_f32_e32 v49, 0.5, v34
	v_add_f32_e32 v32, v32, v33
	v_mul_f32_e32 v33, v48, v48
	v_mul_f32_e32 v34, v50, v50
	v_fmac_f32_e32 v33, v43, v43
	v_fmac_f32_e32 v34, v49, v49
	v_add_f32_e32 v33, v33, v34
	v_add_f32_e32 v32, v32, v33
	v_add_f32_e32 v35, v44, v32
	ds_bpermute_b32 v44, v112, v35
	v_lshl_add_u64 v[32:33], s[0:1], 0, v[98:99]
	v_lshl_add_u64 v[40:41], v[164:165], 1, v[32:33]
	global_store_dwordx4 v[40:41], v[36:39], off
	v_cvt_pk_bf16_f32 v34, v45, v46
	s_waitcnt lgkmcnt(0)
	v_add_f32_e32 v32, v35, v44
	ds_bpermute_b32 v33, v113, v32
	v_cvt_pk_bf16_f32 v35, v47, v42
	v_cvt_pk_bf16_f32 v36, v43, v48
	v_cvt_pk_bf16_f32 v37, v49, v50
	global_store_dwordx4 v[40:41], v[34:37], off offset:256
	s_and_saveexec_b64 s[20:21], s[4:5]
	s_cbranch_execz .LBB0_1919
	s_waitcnt lgkmcnt(0)
	v_add_f32_e32 v34, v32, v33
	s_lshl_b32 s22, s30, 2
	v_lshlrev_b64 v[32:33], 7, v[96:97]
	s_ashr_i32 s23, s22, 31
	v_lshl_add_u64 v[32:33], s[8:9], 0, v[32:33]
	v_lshl_add_u64 v[32:33], s[22:23], 2, v[32:33]
	s_lshl_b32 s2, s41, 2
	v_lshl_add_u64 v[32:33], v[32:33], 0, s[2:3]
	global_store_dword v[32:33], v34, off
; __device__ __forceinline__ unsigned pk2(float lo, float hi) { unsigned r; asm volatile("v_cvt_pk_bf16_f32 %0, %1, %2" : "=v"(r) : "v"(lo), "v"(hi)); return r; }
; __device__ __forceinline__ unsigned pk2(float lo, float hi) { return f2bf(lo) | (f2bf(hi) << 16); }
;     __device__ __forceinline__ void epi(const f32x4 (&acc)[2][2][4][2], const Unit& u, int wr, int wc, int fr, int fq) const {
;     ...
;             for (int m = 0; m < 4; ++m) {
;                 const int row = row0 + ai * 128 + m * 16; const size_t off = (size_t)row * D + col0; float ss = 0.f;
; #pragma unroll
;                 for (int bj = 0; bj < 2; ++bj) {
;                     const u32x4 o = xo[m][bj]; const f32x4 a0v = acc[ai][bj][m][0], a1v = acc[ai][bj][m][1];
;                     const float v0 = bf_lo(o.x) + coef * a0v[0], v1 = bf_hi(o.x) + coef * a0v[1], v2 = bf_lo(o.y) + coef * a0v[2], v3 = bf_hi(o.y) + coef * a0v[3];
;                     const float v4 = bf_lo(o.z) + coef * a1v[0], v5 = bf_hi(o.z) + coef * a1v[1], v6 = bf_lo(o.w) + coef * a1v[2], v7 = bf_hi(o.w) + coef * a1v[3];
;                     u32x4 w; w.x = pk2(v0, v1); w.y = pk2(v2, v3); w.z = pk2(v4, v5); w.w = pk2(v6, v7);
;                     *(u32x4*)(xb + off + bj * 128) = w;
;                     ss += ((v0 * v0 + v1 * v1) + (v2 * v2 + v3 * v3)) + ((v4 * v4 + v5 * v5) + (v6 * v6 + v7 * v7));
;                 }
;                 ss += __shfl_xor(ss, 16); ss += __shfl_xor(ss, 32);
;                 if (fq == 0) rowss[(size_t)row * 32 + u.pn * 4 + wc] = ss;
;             }
.LBB0_1919:
	s_or_b64 exec, exec, s[20:21]
	v_lshlrev_b32_e32 v32, 16, v76
	v_fmac_f32_e32 v32, 0.5, v28
	v_and_b32_e32 v28, 0xffff0000, v76
	v_fmac_f32_e32 v28, 0.5, v29
	v_lshlrev_b32_e32 v29, 16, v77
	v_fmac_f32_e32 v29, 0.5, v30
	v_and_b32_e32 v30, 0xffff0000, v77
	v_fmac_f32_e32 v30, 0.5, v31
	v_lshlrev_b32_e32 v31, 16, v78
	s_waitcnt lgkmcnt(0)
	v_and_b32_e32 v33, 0xffff0000, v78
	v_fmac_f32_e32 v31, 0.5, v20
	v_fmac_f32_e32 v33, 0.5, v21
	v_and_b32_e32 v35, 0xffff0000, v79
	v_cvt_pk_bf16_f32 v20, v32, v28
	v_cvt_pk_bf16_f32 v21, v29, v30
	v_mul_f32_e32 v28, v28, v28
	v_mul_f32_e32 v30, v30, v30
	v_lshlrev_b32_e32 v34, 16, v79
	v_fmac_f32_e32 v35, 0.5, v23
	v_fmac_f32_e32 v28, v32, v32
	v_fmac_f32_e32 v30, v29, v29
	v_fmac_f32_e32 v34, 0.5, v22
	v_add_f32_e32 v28, v28, v30
	v_mul_f32_e32 v29, v33, v33
	v_mul_f32_e32 v30, v35, v35
	v_cvt_pk_bf16_f32 v22, v31, v33
	v_fmac_f32_e32 v29, v31, v31
	v_fmac_f32_e32 v30, v34, v34
	v_lshlrev_b32_e32 v31, 16, v73
	v_add_f32_e32 v29, v29, v30
	v_and_b32_e32 v30, 0xffff0000, v72
	v_fmac_f32_e32 v31, 0.5, v26
	v_and_b32_e32 v26, 0xffff0000, v73
	v_add_f32_e32 v28, v28, v29
	v_lshlrev_b32_e32 v29, 16, v72
	v_fmac_f32_e32 v30, 0.5, v25
	v_fmac_f32_e32 v26, 0.5, v27
	v_lshlrev_b32_e32 v27, 16, v74
	v_and_b32_e32 v32, 0xffff0000, v74
	v_cvt_pk_bf16_f32 v23, v34, v35
	v_fmac_f32_e32 v29, 0.5, v24
	v_fmac_f32_e32 v27, 0.5, v16
	v_fmac_f32_e32 v32, 0.5, v17
	v_and_b32_e32 v34, 0xffff0000, v75
	v_mul_f32_e32 v16, v30, v30
	v_mul_f32_e32 v17, v26, v26
	v_lshlrev_b32_e32 v33, 16, v75
	v_fmac_f32_e32 v34, 0.5, v19
	v_fmac_f32_e32 v16, v29, v29
	v_fmac_f32_e32 v17, v31, v31
	v_fmac_f32_e32 v33, 0.5, v18
	v_add_f32_e32 v16, v16, v17
	v_mul_f32_e32 v17, v32, v32
	v_mul_f32_e32 v18, v34, v34
	v_fmac_f32_e32 v17, v27, v27
	v_fmac_f32_e32 v18, v33, v33
	v_add_f32_e32 v17, v17, v18
	v_add_f32_e32 v16, v16, v17
	v_add_f32_e32 v19, v28, v16
	ds_bpermute_b32 v28, v112, v19
	v_lshl_add_u64 v[16:17], s[0:1], 0, v[94:95]
	v_lshl_add_u64 v[24:25], v[164:165], 1, v[16:17]
	global_store_dwordx4 v[24:25], v[20:23], off
	v_cvt_pk_bf16_f32 v18, v29, v30
	s_waitcnt lgkmcnt(0)
	v_add_f32_e32 v16, v19, v28
	ds_bpermute_b32 v17, v113, v16
	v_cvt_pk_bf16_f32 v19, v31, v26
	v_cvt_pk_bf16_f32 v20, v27, v32
	v_cvt_pk_bf16_f32 v21, v33, v34
	global_store_dwordx4 v[24:25], v[18:21], off offset:256
	s_and_saveexec_b64 s[20:21], s[4:5]
	s_cbranch_execz .LBB0_1921
	s_waitcnt lgkmcnt(0)
	v_add_f32_e32 v18, v16, v17
	s_lshl_b32 s22, s30, 2
	v_lshlrev_b64 v[16:17], 7, v[92:93]
	s_ashr_i32 s23, s22, 31
	v_lshl_add_u64 v[16:17], s[8:9], 0, v[16:17]
	v_lshl_add_u64 v[16:17], s[22:23], 2, v[16:17]
	s_lshl_b32 s2, s41, 2
	v_lshl_add_u64 v[16:17], v[16:17], 0, s[2:3]
	global_store_dword v[16:17], v18, off
.LBB0_1921:
	s_or_b64 exec, exec, s[20:21]
	v_lshlrev_b32_e32 v16, 16, v68
	v_fmac_f32_e32 v16, 0.5, v12
	v_and_b32_e32 v12, 0xffff0000, v68
	v_fmac_f32_e32 v12, 0.5, v13
	v_lshlrev_b32_e32 v13, 16, v69
	v_fmac_f32_e32 v13, 0.5, v14
	v_and_b32_e32 v14, 0xffff0000, v69
	v_fmac_f32_e32 v14, 0.5, v15
	v_lshlrev_b32_e32 v15, 16, v70
	s_waitcnt lgkmcnt(0)
	v_and_b32_e32 v17, 0xffff0000, v70
	v_fmac_f32_e32 v15, 0.5, v4
	v_fmac_f32_e32 v17, 0.5, v5
	v_and_b32_e32 v19, 0xffff0000, v71
	v_cvt_pk_bf16_f32 v4, v16, v12
	v_cvt_pk_bf16_f32 v5, v13, v14
	v_mul_f32_e32 v12, v12, v12
	v_mul_f32_e32 v14, v14, v14
	v_lshlrev_b32_e32 v18, 16, v71
	v_fmac_f32_e32 v19, 0.5, v7
	v_fmac_f32_e32 v12, v16, v16
	v_fmac_f32_e32 v14, v13, v13
	v_fmac_f32_e32 v18, 0.5, v6
	v_add_f32_e32 v12, v12, v14
	v_mul_f32_e32 v13, v17, v17
	v_mul_f32_e32 v14, v19, v19
	v_cvt_pk_bf16_f32 v6, v15, v17
	v_fmac_f32_e32 v13, v15, v15
	v_fmac_f32_e32 v14, v18, v18
	v_lshlrev_b32_e32 v15, 16, v65
	v_add_f32_e32 v13, v13, v14
	v_and_b32_e32 v14, 0xffff0000, v64
	v_fmac_f32_e32 v15, 0.5, v10
	v_and_b32_e32 v10, 0xffff0000, v65
	v_add_f32_e32 v12, v12, v13
	v_lshlrev_b32_e32 v13, 16, v64
	v_fmac_f32_e32 v14, 0.5, v9
	v_fmac_f32_e32 v10, 0.5, v11
	v_lshlrev_b32_e32 v11, 16, v66
	v_and_b32_e32 v16, 0xffff0000, v66
	v_cvt_pk_bf16_f32 v7, v18, v19
	v_fmac_f32_e32 v13, 0.5, v8
	v_fmac_f32_e32 v11, 0.5, v0
	v_fmac_f32_e32 v16, 0.5, v1
	v_and_b32_e32 v18, 0xffff0000, v67
	v_mul_f32_e32 v0, v14, v14
	v_mul_f32_e32 v1, v10, v10
	v_lshlrev_b32_e32 v17, 16, v67
	v_fmac_f32_e32 v18, 0.5, v3
	v_fmac_f32_e32 v0, v13, v13
	v_fmac_f32_e32 v1, v15, v15
	v_fmac_f32_e32 v17, 0.5, v2
	v_add_f32_e32 v0, v0, v1
	v_mul_f32_e32 v1, v16, v16
	v_mul_f32_e32 v2, v18, v18
	v_fmac_f32_e32 v1, v11, v11
	v_fmac_f32_e32 v2, v17, v17
	v_add_f32_e32 v1, v1, v2
	v_add_f32_e32 v0, v0, v1
	v_add_f32_e32 v3, v12, v0
	ds_bpermute_b32 v12, v112, v3
	v_lshl_add_u64 v[0:1], s[0:1], 0, v[90:91]
	v_lshl_add_u64 v[8:9], v[164:165], 1, v[0:1]
	global_store_dwordx4 v[8:9], v[4:7], off
	v_cvt_pk_bf16_f32 v2, v13, v14
	s_waitcnt lgkmcnt(0)
	v_add_f32_e32 v0, v3, v12
	ds_bpermute_b32 v1, v113, v0
	v_cvt_pk_bf16_f32 v3, v15, v10
	v_cvt_pk_bf16_f32 v4, v11, v16
	v_cvt_pk_bf16_f32 v5, v17, v18
	global_store_dwordx4 v[8:9], v[2:5], off offset:256
	s_and_saveexec_b64 s[20:21], s[4:5]
	s_cbranch_execz .LBB0_1898
	s_waitcnt lgkmcnt(0)
	v_add_f32_e32 v2, v0, v1
	s_lshl_b32 s22, s30, 2
	v_lshlrev_b64 v[0:1], 7, v[88:89]
	s_ashr_i32 s23, s22, 31
	v_lshl_add_u64 v[0:1], s[8:9], 0, v[0:1]
	v_lshl_add_u64 v[0:1], s[22:23], 2, v[0:1]
	s_lshl_b32 s2, s41, 2
	v_lshl_add_u64 v[0:1], v[0:1], 0, s[2:3]
	global_store_dword v[0:1], v2, off
	s_branch .LBB0_1898
